# all big GEMM K-loops: waves 4-7 staggered half a K-step
# baseline (speedup 1.0000x reference)
.LBB0_533:
	s_ashr_i32 s4, s11, 31
	s_lshr_b32 s4, s4, 26
	s_add_i32 s4, s11, s4
	s_and_b32 s6, s4, 0xffffc0
	s_sub_i32 s6, s11, s6
	s_lshl_b32 s7, s6, 8
	v_add_u32_e32 v2, s7, v204
	v_mad_i64_i32 v[168:169], s[20:21], v2, s52, v[162:163]
	v_add_co_u32_e32 v56, vcc, 0x58000, v168
	s_lshl_b32 s4, s4, 2
	s_nop 0
	v_addc_co_u32_e32 v57, vcc, 0, v169, vcc
	v_add_co_u32_e32 v58, vcc, 0xb0000, v168
	s_and_b32 s6, s4, 0xffffff00
	s_nop 0
	v_addc_co_u32_e32 v59, vcc, 0, v169, vcc
	v_add_u32_e32 v2, s6, v204
	v_add_co_u32_e32 v60, vcc, 0x108000, v168
	v_mad_i64_i32 v[170:171], s[20:21], v2, s52, v[164:165]
	s_nop 0
	v_addc_co_u32_e32 v61, vcc, 0, v169, vcc
	v_add_co_u32_e32 v62, vcc, s92, v170
	global_load_dwordx4 v[24:27], v[56:57], off
	global_load_dwordx4 v[28:31], v[58:59], off
	v_addc_co_u32_e32 v63, vcc, 0, v171, vcc
	v_add_co_u32_e32 v64, vcc, s53, v170
	global_load_dwordx4 v[32:35], v[168:169], off
	global_load_dwordx4 v[36:39], v[170:171], off
	v_addc_co_u32_e32 v65, vcc, 0, v171, vcc
	v_add_co_u32_e32 v66, vcc, s8, v170
	global_load_dwordx4 v[40:43], v[60:61], off
	global_load_dwordx4 v[44:47], v[62:63], off
	v_addc_co_u32_e32 v67, vcc, 0, v171, vcc
	global_load_dwordx4 v[48:51], v[64:65], off
	global_load_dwordx4 v[52:55], v[66:67], off
	s_waitcnt lgkmcnt(0)
	s_barrier
	global_load_dwordx4 v[110:113], v[168:169], off offset:128
	global_load_dwordx4 v[102:105], v[56:57], off offset:128
	global_load_dwordx4 v[106:109], v[58:59], off offset:128
	global_load_dwordx4 v[122:125], v[60:61], off offset:128
	global_load_dwordx4 v[118:121], v[170:171], off offset:128
	global_load_dwordx4 v[114:117], v[62:63], off offset:128
	global_load_dwordx4 v[130:133], v[64:65], off offset:128
	global_load_dwordx4 v[126:129], v[66:67], off offset:128
	v_readfirstlane_b32 s100, v172
	s_nop 0
	s_lshr_b32 m0, s100, 8
	v_readfirstlane_b32 vcc_lo, v168
	v_readfirstlane_b32 vcc_hi, v169
	v_readfirstlane_b32 s100, v170
	v_readfirstlane_b32 s101, v171
	s_nop 1
	v_subrev_u32_e32 v168, vcc_lo, v168
	v_subrev_u32_e32 v170, s100, v170
	v_mov_b32_e32 v2, 0
	s_mov_b32 s4, 0
	v_mov_b32_e32 v3, v2
	v_mov_b32_e32 v4, v2
	v_mov_b32_e32 v5, v2
	v_mov_b32_e32 v6, v2
	v_mov_b32_e32 v7, v2
	v_mov_b32_e32 v8, v2
	v_mov_b32_e32 v9, v2
	v_mov_b32_e32 v10, v2
	v_mov_b32_e32 v11, v2
	v_mov_b32_e32 v12, v2
	v_mov_b32_e32 v13, v2
	v_mov_b32_e32 v14, v2
	v_mov_b32_e32 v15, v2
	v_mov_b32_e32 v16, v2
	v_mov_b32_e32 v17, v2
	v_mov_b32_e32 v18, v2
	v_mov_b32_e32 v19, v2
	v_mov_b32_e32 v20, v2
	v_mov_b32_e32 v21, v2
	v_mov_b32_e32 v22, v2
	v_mov_b32_e32 v23, v2
	v_mov_b32_e32 v56, v2
	v_mov_b32_e32 v57, v2
	v_mov_b32_e32 v58, v2
	v_mov_b32_e32 v59, v2
	v_mov_b32_e32 v60, v2
	v_mov_b32_e32 v61, v2
	v_mov_b32_e32 v62, v2
	v_mov_b32_e32 v63, v2
	v_mov_b32_e32 v64, v2
	v_mov_b32_e32 v65, v2
	v_mov_b32_e32 v66, v2
	v_mov_b32_e32 v67, v2
	v_mov_b32_e32 v68, v2
	v_mov_b32_e32 v69, v2
	v_mov_b32_e32 v70, v2
	v_mov_b32_e32 v71, v2
	v_mov_b32_e32 v72, v2
	v_mov_b32_e32 v73, v2
	v_mov_b32_e32 v74, v2
	v_mov_b32_e32 v75, v2
	v_mov_b32_e32 v76, v2
	v_mov_b32_e32 v77, v2
	v_mov_b32_e32 v78, v2
	v_mov_b32_e32 v79, v2
	v_mov_b32_e32 v80, v2
	v_mov_b32_e32 v81, v2
	v_mov_b32_e32 v82, v2
	v_mov_b32_e32 v83, v2
	v_mov_b32_e32 v84, v2
	v_mov_b32_e32 v85, v2
	s_waitcnt vmcnt(13)
	ds_write_b128 v166, v[32:35]
	s_waitcnt vmcnt(12)
	ds_write_b128 v166, v[36:39] offset:32768
	ds_write_b128 v166, v[24:27] offset:8192
	ds_write_b128 v166, v[28:31] offset:16384
	s_waitcnt vmcnt(11)
	ds_write_b128 v166, v[40:43] offset:24576
	s_waitcnt vmcnt(10)
	ds_write_b128 v166, v[44:47] offset:40960
	s_waitcnt vmcnt(9)
	ds_write_b128 v166, v[48:51] offset:49152
	s_waitcnt vmcnt(8)
	ds_write_b128 v166, v[52:55] offset:57344
	v_mov_b32_e32 v24, v2
	v_mov_b32_e32 v25, v2
	v_mov_b32_e32 v26, v2
	v_mov_b32_e32 v27, v2
	v_mov_b32_e32 v28, v2
	v_mov_b32_e32 v29, v2
	v_mov_b32_e32 v30, v2
	v_mov_b32_e32 v31, v2
	v_mov_b32_e32 v32, v2
	v_mov_b32_e32 v33, v2
	v_mov_b32_e32 v34, v2
	v_mov_b32_e32 v35, v2
	v_mov_b32_e32 v36, v2
	v_mov_b32_e32 v37, v2
	v_mov_b32_e32 v38, v2
	v_mov_b32_e32 v39, v2
	v_mov_b32_e32 v40, v2
	v_mov_b32_e32 v41, v2
	v_mov_b32_e32 v42, v2
	v_mov_b32_e32 v43, v2
	v_mov_b32_e32 v44, v2
	v_mov_b32_e32 v45, v2
	v_mov_b32_e32 v46, v2
	v_mov_b32_e32 v47, v2
	v_mov_b32_e32 v48, v2
	v_mov_b32_e32 v49, v2
	v_mov_b32_e32 v50, v2
	v_mov_b32_e32 v51, v2
	v_mov_b32_e32 v52, v2
	v_mov_b32_e32 v53, v2
	v_mov_b32_e32 v54, v2
	v_mov_b32_e32 v55, v2
	v_mov_b32_e32 v86, v2
	v_mov_b32_e32 v87, v2
	v_mov_b32_e32 v88, v2
	v_mov_b32_e32 v89, v2
	v_mov_b32_e32 v90, v2
	v_mov_b32_e32 v91, v2
	v_mov_b32_e32 v92, v2
	v_mov_b32_e32 v93, v2
	v_mov_b32_e32 v94, v2
	v_mov_b32_e32 v95, v2
	v_mov_b32_e32 v96, v2
	v_mov_b32_e32 v97, v2
	v_mov_b32_e32 v98, v2
	v_mov_b32_e32 v99, v2
	v_mov_b32_e32 v100, v2
	v_mov_b32_e32 v101, v2
	v_mov_b32_e32 v134, v2
	v_mov_b32_e32 v135, v2
	v_mov_b32_e32 v136, v2
	v_mov_b32_e32 v137, v2
	v_mov_b32_e32 v138, v2
	v_mov_b32_e32 v139, v2
	v_mov_b32_e32 v140, v2
	v_mov_b32_e32 v141, v2
	v_mov_b32_e32 v142, v2
	v_mov_b32_e32 v143, v2
	v_mov_b32_e32 v144, v2
	v_mov_b32_e32 v145, v2
	v_mov_b32_e32 v146, v2
	v_mov_b32_e32 v147, v2
	v_mov_b32_e32 v148, v2
	v_mov_b32_e32 v149, v2
	v_mov_b32_e32 v150, v2
	v_mov_b32_e32 v151, v2
	v_mov_b32_e32 v152, v2
	v_mov_b32_e32 v153, v2
	v_mov_b32_e32 v154, v2
	v_mov_b32_e32 v155, v2
	v_mov_b32_e32 v156, v2
	v_mov_b32_e32 v157, v2
	v_mov_b32_e32 v158, v2
	v_mov_b32_e32 v159, v2
	v_mov_b32_e32 v160, v2
	v_mov_b32_e32 v161, v2
	s_waitcnt lgkmcnt(0)
	s_barrier
	s_cmp_lg_u32 m0, 0
	s_cbranch_scc1 .Lg1_534
.LBB0_534:
	s_bitcmp1_b32 s4, 0
	s_cselect_b32 s21, 0x12000, 0
	v_or_b32_e32 v218, s21, v207
	v_add_u32_e32 v214, v218, v0
	v_add_u32_e32 v246, v218, v167
	ds_read_b128 v[184:187], v214
	ds_read_b128 v[218:221], v246 offset:32768
	ds_read_b128 v[198:201], v214 offset:2048
	ds_read_b128 v[210:213], v214 offset:4096
	ds_read_b128 v[214:217], v214 offset:6144
	ds_read_b128 v[222:225], v246 offset:34816
	ds_read_b128 v[226:229], v246 offset:36864
	ds_read_b128 v[230:233], v246 offset:38912
	ds_read_b128 v[234:237], v246 offset:40960
	ds_read_b128 v[238:241], v246 offset:43008
	ds_read_b128 v[242:245], v246 offset:45056
	ds_read_b128 v[246:249], v246 offset:47104
	s_add_i32 s20, s4, 1
	s_bitcmp1_b32 s20, 0
	s_cselect_b32 s23, 0x12000, 0
	v_add_u32_e32 v171, s23, v166
	v_xor_b32_e32 v169, 64, v207
	v_add3_u32 v169, s21, v167, v169
	s_waitcnt lgkmcnt(10)
	v_mfma_f32_16x16x32_bf16 v[158:161], v[218:221], v[184:187], v[158:161]
	s_waitcnt lgkmcnt(9)
	v_mfma_f32_16x16x32_bf16 v[94:97], v[218:221], v[198:201], v[94:97]
	s_waitcnt lgkmcnt(8)
	v_mfma_f32_16x16x32_bf16 v[62:65], v[218:221], v[210:213], v[62:65]
	s_waitcnt lgkmcnt(7)
	v_mfma_f32_16x16x32_bf16 v[30:33], v[218:221], v[214:217], v[30:33]
	ds_read_b128 v[218:221], v169 offset:32768
	s_waitcnt lgkmcnt(7)
	v_mfma_f32_16x16x32_bf16 v[154:157], v[222:225], v[184:187], v[154:157]
	v_mfma_f32_16x16x32_bf16 v[90:93], v[222:225], v[198:201], v[90:93]
	v_mfma_f32_16x16x32_bf16 v[58:61], v[222:225], v[210:213], v[58:61]
	v_mfma_f32_16x16x32_bf16 v[26:29], v[222:225], v[214:217], v[26:29]
	ds_read_b128 v[222:225], v169 offset:34816
	s_waitcnt lgkmcnt(7)
	v_mfma_f32_16x16x32_bf16 v[150:153], v[226:229], v[184:187], v[150:153]
	v_mfma_f32_16x16x32_bf16 v[86:89], v[226:229], v[198:201], v[86:89]
	v_mfma_f32_16x16x32_bf16 v[54:57], v[226:229], v[210:213], v[54:57]
	v_mfma_f32_16x16x32_bf16 v[22:25], v[226:229], v[214:217], v[22:25]
	ds_read_b128 v[226:229], v169 offset:36864
	s_waitcnt lgkmcnt(7)
	v_mfma_f32_16x16x32_bf16 v[146:149], v[230:233], v[184:187], v[146:149]
	v_mfma_f32_16x16x32_bf16 v[82:85], v[230:233], v[198:201], v[82:85]
	v_mfma_f32_16x16x32_bf16 v[50:53], v[230:233], v[210:213], v[50:53]
	v_mfma_f32_16x16x32_bf16 v[18:21], v[230:233], v[214:217], v[18:21]
	ds_read_b128 v[230:233], v169 offset:38912
	s_waitcnt lgkmcnt(7)
	v_mfma_f32_16x16x32_bf16 v[142:145], v[234:237], v[184:187], v[142:145]
	v_mfma_f32_16x16x32_bf16 v[78:81], v[234:237], v[198:201], v[78:81]
	v_mfma_f32_16x16x32_bf16 v[46:49], v[234:237], v[210:213], v[46:49]
	v_mfma_f32_16x16x32_bf16 v[14:17], v[234:237], v[214:217], v[14:17]
	ds_read_b128 v[234:237], v169 offset:40960
	s_waitcnt lgkmcnt(7)
	v_mfma_f32_16x16x32_bf16 v[138:141], v[238:241], v[184:187], v[138:141]
	v_mfma_f32_16x16x32_bf16 v[74:77], v[238:241], v[198:201], v[74:77]
	v_mfma_f32_16x16x32_bf16 v[42:45], v[238:241], v[210:213], v[42:45]
	v_mfma_f32_16x16x32_bf16 v[10:13], v[238:241], v[214:217], v[10:13]
	ds_read_b128 v[238:241], v169 offset:43008
	s_waitcnt lgkmcnt(7)
	v_mfma_f32_16x16x32_bf16 v[134:137], v[242:245], v[184:187], v[134:137]
	v_mfma_f32_16x16x32_bf16 v[70:73], v[242:245], v[198:201], v[70:73]
	v_mfma_f32_16x16x32_bf16 v[38:41], v[242:245], v[210:213], v[38:41]
	v_mfma_f32_16x16x32_bf16 v[6:9], v[242:245], v[214:217], v[6:9]
	ds_read_b128 v[242:245], v169 offset:45056
	s_waitcnt lgkmcnt(7)
	v_mfma_f32_16x16x32_bf16 v[98:101], v[246:249], v[184:187], v[98:101]
	v_mfma_f32_16x16x32_bf16 v[66:69], v[246:249], v[198:201], v[66:69]
	v_xor_b32_e32 v169, 64, v207
	v_add3_u32 v169, s21, v0, v169
	ds_read_b128 v[184:187], v169
	ds_read_b128 v[198:201], v169 offset:2048
	v_mfma_f32_16x16x32_bf16 v[34:37], v[246:249], v[210:213], v[34:37]
	ds_read_b128 v[210:213], v169 offset:4096
	v_mfma_f32_16x16x32_bf16 v[2:5], v[246:249], v[214:217], v[2:5]
	ds_read_b128 v[214:217], v169 offset:6144
	v_xor_b32_e32 v169, 64, v207
	v_add3_u32 v169, s21, v167, v169
	ds_read_b128 v[246:249], v169 offset:47104
	s_waitcnt lgkmcnt(4)
	v_mfma_f32_16x16x32_bf16 v[158:161], v[218:221], v[184:187], v[158:161]
	s_waitcnt lgkmcnt(3)
	v_mfma_f32_16x16x32_bf16 v[94:97], v[218:221], v[198:201], v[94:97]
	s_waitcnt lgkmcnt(2)
	v_mfma_f32_16x16x32_bf16 v[62:65], v[218:221], v[210:213], v[62:65]
	s_waitcnt lgkmcnt(1)
	v_mfma_f32_16x16x32_bf16 v[30:33], v[218:221], v[214:217], v[30:33]
	s_waitcnt vmcnt(7)
	ds_write_b128 v171, v[110:113]
	v_mfma_f32_16x16x32_bf16 v[154:157], v[222:225], v[184:187], v[154:157]
	v_mfma_f32_16x16x32_bf16 v[90:93], v[222:225], v[198:201], v[90:93]
	global_load_dwordx4 v[110:113], v168, vcc offset:256
	v_mfma_f32_16x16x32_bf16 v[58:61], v[222:225], v[210:213], v[58:61]
	v_mfma_f32_16x16x32_bf16 v[26:29], v[222:225], v[214:217], v[26:29]
	s_waitcnt vmcnt(7)
	ds_write_b128 v171, v[102:105] offset:8192
	v_mfma_f32_16x16x32_bf16 v[150:153], v[226:229], v[184:187], v[150:153]
	v_mfma_f32_16x16x32_bf16 v[86:89], v[226:229], v[198:201], v[86:89]
	v_add_u32_e32 v102, 0x58000, v168
	global_load_dwordx4 v[102:105], v102, vcc offset:256
	v_mfma_f32_16x16x32_bf16 v[54:57], v[226:229], v[210:213], v[54:57]
	v_mfma_f32_16x16x32_bf16 v[22:25], v[226:229], v[214:217], v[22:25]
	s_waitcnt vmcnt(7)
	ds_write_b128 v171, v[106:109] offset:16384
	v_mfma_f32_16x16x32_bf16 v[146:149], v[230:233], v[184:187], v[146:149]
	v_mfma_f32_16x16x32_bf16 v[82:85], v[230:233], v[198:201], v[82:85]
	v_add_u32_e32 v106, 0xb0000, v168
	global_load_dwordx4 v[106:109], v106, vcc offset:256
	v_mfma_f32_16x16x32_bf16 v[50:53], v[230:233], v[210:213], v[50:53]
	v_mfma_f32_16x16x32_bf16 v[18:21], v[230:233], v[214:217], v[18:21]
	s_waitcnt vmcnt(7)
	ds_write_b128 v171, v[122:125] offset:24576
	v_mfma_f32_16x16x32_bf16 v[142:145], v[234:237], v[184:187], v[142:145]
	v_mfma_f32_16x16x32_bf16 v[78:81], v[234:237], v[198:201], v[78:81]
	v_add_u32_e32 v122, 0x108000, v168
	global_load_dwordx4 v[122:125], v122, vcc offset:256
	v_mfma_f32_16x16x32_bf16 v[46:49], v[234:237], v[210:213], v[46:49]
	v_mfma_f32_16x16x32_bf16 v[14:17], v[234:237], v[214:217], v[14:17]
	s_waitcnt vmcnt(7)
	ds_write_b128 v171, v[118:121] offset:32768
	v_mfma_f32_16x16x32_bf16 v[138:141], v[238:241], v[184:187], v[138:141]
	v_mfma_f32_16x16x32_bf16 v[74:77], v[238:241], v[198:201], v[74:77]
	global_load_dwordx4 v[118:121], v170, s[100:101] offset:256
	v_mfma_f32_16x16x32_bf16 v[42:45], v[238:241], v[210:213], v[42:45]
	v_mfma_f32_16x16x32_bf16 v[10:13], v[238:241], v[214:217], v[10:13]
	s_waitcnt vmcnt(7)
	ds_write_b128 v171, v[114:117] offset:40960
	v_mfma_f32_16x16x32_bf16 v[134:137], v[242:245], v[184:187], v[134:137]
	v_mfma_f32_16x16x32_bf16 v[70:73], v[242:245], v[198:201], v[70:73]
	v_add_u32_e32 v114, 0x58000, v170
	global_load_dwordx4 v[114:117], v114, s[100:101] offset:256
	v_mfma_f32_16x16x32_bf16 v[38:41], v[242:245], v[210:213], v[38:41]
	v_mfma_f32_16x16x32_bf16 v[6:9], v[242:245], v[214:217], v[6:9]
	s_waitcnt vmcnt(7)
	ds_write_b128 v171, v[130:133] offset:49152
	s_waitcnt lgkmcnt(7)
	v_mfma_f32_16x16x32_bf16 v[98:101], v[246:249], v[184:187], v[98:101]
	v_mfma_f32_16x16x32_bf16 v[66:69], v[246:249], v[198:201], v[66:69]
	v_add_u32_e32 v130, 0xb0000, v170
	global_load_dwordx4 v[130:133], v130, s[100:101] offset:256
	v_mfma_f32_16x16x32_bf16 v[34:37], v[246:249], v[210:213], v[34:37]
	v_mfma_f32_16x16x32_bf16 v[2:5], v[246:249], v[214:217], v[2:5]
	s_waitcnt vmcnt(7)
	ds_write_b128 v171, v[126:129] offset:57344
	v_add_u32_e32 v126, 0x108000, v170
	global_load_dwordx4 v[126:129], v126, s[100:101] offset:256
	v_add_u32_e32 v168, 0x80, v168
	v_add_u32_e32 v170, 0x80, v170
	s_waitcnt lgkmcnt(0)
	s_barrier
	s_cmp_eq_u32 s20, 44
	s_mov_b32 s4, s20
	s_cbranch_scc0 .LBB0_534
	s_branch .Lkdone_534
.Lg1_534:
	v_add_u32_e32 v171, 0x12000, v166
	s_waitcnt vmcnt(7)
	ds_write_b128 v171, v[110:113]
	global_load_dwordx4 v[110:113], v168, vcc offset:256
	s_waitcnt vmcnt(7)
	ds_write_b128 v171, v[102:105] offset:8192
	v_add_u32_e32 v102, 0x58000, v168
	global_load_dwordx4 v[102:105], v102, vcc offset:256
	s_waitcnt vmcnt(7)
	ds_write_b128 v171, v[106:109] offset:16384
	v_add_u32_e32 v106, 0xb0000, v168
	global_load_dwordx4 v[106:109], v106, vcc offset:256
	s_waitcnt vmcnt(7)
	ds_write_b128 v171, v[122:125] offset:24576
	v_add_u32_e32 v122, 0x108000, v168
	global_load_dwordx4 v[122:125], v122, vcc offset:256
	s_waitcnt vmcnt(7)
	ds_write_b128 v171, v[118:121] offset:32768
	global_load_dwordx4 v[118:121], v170, s[100:101] offset:256
	s_waitcnt vmcnt(7)
	ds_write_b128 v171, v[114:117] offset:40960
	v_add_u32_e32 v114, 0x58000, v170
	global_load_dwordx4 v[114:117], v114, s[100:101] offset:256
	s_waitcnt vmcnt(7)
	ds_write_b128 v171, v[130:133] offset:49152
	v_add_u32_e32 v130, 0xb0000, v170
	global_load_dwordx4 v[130:133], v130, s[100:101] offset:256
	s_waitcnt vmcnt(7)
	ds_write_b128 v171, v[126:129] offset:57344
	v_add_u32_e32 v126, 0x108000, v170
	global_load_dwordx4 v[126:129], v126, s[100:101] offset:256
	v_add_u32_e32 v168, 0x80, v168
	v_add_u32_e32 v170, 0x80, v170
.Lg1loop_534:
	s_bitcmp1_b32 s4, 0
	s_cselect_b32 s21, 0x12000, 0
	v_or_b32_e32 v218, s21, v207
	v_add_u32_e32 v214, v218, v0
	v_add_u32_e32 v246, v218, v167
	ds_read_b128 v[184:187], v214
	ds_read_b128 v[218:221], v246 offset:32768
	ds_read_b128 v[198:201], v214 offset:2048
	ds_read_b128 v[210:213], v214 offset:4096
	ds_read_b128 v[214:217], v214 offset:6144
	ds_read_b128 v[222:225], v246 offset:34816
	ds_read_b128 v[226:229], v246 offset:36864
	ds_read_b128 v[230:233], v246 offset:38912
	ds_read_b128 v[234:237], v246 offset:40960
	ds_read_b128 v[238:241], v246 offset:43008
	ds_read_b128 v[242:245], v246 offset:45056
	ds_read_b128 v[246:249], v246 offset:47104
	s_add_i32 s20, s4, 1
	s_bitcmp1_b32 s20, 0
	s_cselect_b32 s23, 0x12000, 0
	v_add_u32_e32 v171, s21, v166
	v_xor_b32_e32 v169, 64, v207
	v_add3_u32 v169, s21, v167, v169
	s_waitcnt lgkmcnt(10)
	v_mfma_f32_16x16x32_bf16 v[158:161], v[218:221], v[184:187], v[158:161]
	s_waitcnt lgkmcnt(9)
	v_mfma_f32_16x16x32_bf16 v[94:97], v[218:221], v[198:201], v[94:97]
	s_waitcnt lgkmcnt(8)
	v_mfma_f32_16x16x32_bf16 v[62:65], v[218:221], v[210:213], v[62:65]
	s_waitcnt lgkmcnt(7)
	v_mfma_f32_16x16x32_bf16 v[30:33], v[218:221], v[214:217], v[30:33]
	ds_read_b128 v[218:221], v169 offset:32768
	s_waitcnt lgkmcnt(7)
	v_mfma_f32_16x16x32_bf16 v[154:157], v[222:225], v[184:187], v[154:157]
	v_mfma_f32_16x16x32_bf16 v[90:93], v[222:225], v[198:201], v[90:93]
	v_mfma_f32_16x16x32_bf16 v[58:61], v[222:225], v[210:213], v[58:61]
	v_mfma_f32_16x16x32_bf16 v[26:29], v[222:225], v[214:217], v[26:29]
	ds_read_b128 v[222:225], v169 offset:34816
	s_waitcnt lgkmcnt(7)
	v_mfma_f32_16x16x32_bf16 v[150:153], v[226:229], v[184:187], v[150:153]
	v_mfma_f32_16x16x32_bf16 v[86:89], v[226:229], v[198:201], v[86:89]
	v_mfma_f32_16x16x32_bf16 v[54:57], v[226:229], v[210:213], v[54:57]
	v_mfma_f32_16x16x32_bf16 v[22:25], v[226:229], v[214:217], v[22:25]
	ds_read_b128 v[226:229], v169 offset:36864
	s_waitcnt lgkmcnt(7)
	v_mfma_f32_16x16x32_bf16 v[146:149], v[230:233], v[184:187], v[146:149]
	v_mfma_f32_16x16x32_bf16 v[82:85], v[230:233], v[198:201], v[82:85]
	v_mfma_f32_16x16x32_bf16 v[50:53], v[230:233], v[210:213], v[50:53]
	v_mfma_f32_16x16x32_bf16 v[18:21], v[230:233], v[214:217], v[18:21]
	ds_read_b128 v[230:233], v169 offset:38912
	s_waitcnt lgkmcnt(7)
	v_mfma_f32_16x16x32_bf16 v[142:145], v[234:237], v[184:187], v[142:145]
	v_mfma_f32_16x16x32_bf16 v[78:81], v[234:237], v[198:201], v[78:81]
	v_mfma_f32_16x16x32_bf16 v[46:49], v[234:237], v[210:213], v[46:49]
	v_mfma_f32_16x16x32_bf16 v[14:17], v[234:237], v[214:217], v[14:17]
	ds_read_b128 v[234:237], v169 offset:40960
	s_waitcnt lgkmcnt(7)
	v_mfma_f32_16x16x32_bf16 v[138:141], v[238:241], v[184:187], v[138:141]
	v_mfma_f32_16x16x32_bf16 v[74:77], v[238:241], v[198:201], v[74:77]
	v_mfma_f32_16x16x32_bf16 v[42:45], v[238:241], v[210:213], v[42:45]
	v_mfma_f32_16x16x32_bf16 v[10:13], v[238:241], v[214:217], v[10:13]
	ds_read_b128 v[238:241], v169 offset:43008
	s_waitcnt lgkmcnt(7)
	v_mfma_f32_16x16x32_bf16 v[134:137], v[242:245], v[184:187], v[134:137]
	v_mfma_f32_16x16x32_bf16 v[70:73], v[242:245], v[198:201], v[70:73]
	v_mfma_f32_16x16x32_bf16 v[38:41], v[242:245], v[210:213], v[38:41]
	v_mfma_f32_16x16x32_bf16 v[6:9], v[242:245], v[214:217], v[6:9]
	ds_read_b128 v[242:245], v169 offset:45056
	s_waitcnt lgkmcnt(7)
	v_mfma_f32_16x16x32_bf16 v[98:101], v[246:249], v[184:187], v[98:101]
	v_mfma_f32_16x16x32_bf16 v[66:69], v[246:249], v[198:201], v[66:69]
	v_xor_b32_e32 v169, 64, v207
	v_add3_u32 v169, s21, v0, v169
	ds_read_b128 v[184:187], v169
	ds_read_b128 v[198:201], v169 offset:2048
	v_mfma_f32_16x16x32_bf16 v[34:37], v[246:249], v[210:213], v[34:37]
	ds_read_b128 v[210:213], v169 offset:4096
	v_mfma_f32_16x16x32_bf16 v[2:5], v[246:249], v[214:217], v[2:5]
	ds_read_b128 v[214:217], v169 offset:6144
	v_xor_b32_e32 v169, 64, v207
	v_add3_u32 v169, s21, v167, v169
	ds_read_b128 v[246:249], v169 offset:47104
	s_waitcnt lgkmcnt(0)
	s_barrier
	s_waitcnt lgkmcnt(4)
	v_mfma_f32_16x16x32_bf16 v[158:161], v[218:221], v[184:187], v[158:161]
	s_waitcnt lgkmcnt(3)
	v_mfma_f32_16x16x32_bf16 v[94:97], v[218:221], v[198:201], v[94:97]
	s_waitcnt lgkmcnt(2)
	v_mfma_f32_16x16x32_bf16 v[62:65], v[218:221], v[210:213], v[62:65]
	s_waitcnt lgkmcnt(1)
	v_mfma_f32_16x16x32_bf16 v[30:33], v[218:221], v[214:217], v[30:33]
	s_waitcnt vmcnt(7)
	ds_write_b128 v171, v[110:113]
	v_mfma_f32_16x16x32_bf16 v[154:157], v[222:225], v[184:187], v[154:157]
	v_mfma_f32_16x16x32_bf16 v[90:93], v[222:225], v[198:201], v[90:93]
	global_load_dwordx4 v[110:113], v168, vcc offset:256
	v_mfma_f32_16x16x32_bf16 v[58:61], v[222:225], v[210:213], v[58:61]
	v_mfma_f32_16x16x32_bf16 v[26:29], v[222:225], v[214:217], v[26:29]
	s_waitcnt vmcnt(7)
	ds_write_b128 v171, v[102:105] offset:8192
	v_mfma_f32_16x16x32_bf16 v[150:153], v[226:229], v[184:187], v[150:153]
	v_mfma_f32_16x16x32_bf16 v[86:89], v[226:229], v[198:201], v[86:89]
	v_add_u32_e32 v102, 0x58000, v168
	global_load_dwordx4 v[102:105], v102, vcc offset:256
	v_mfma_f32_16x16x32_bf16 v[54:57], v[226:229], v[210:213], v[54:57]
	v_mfma_f32_16x16x32_bf16 v[22:25], v[226:229], v[214:217], v[22:25]
	s_waitcnt vmcnt(7)
	ds_write_b128 v171, v[106:109] offset:16384
	v_mfma_f32_16x16x32_bf16 v[146:149], v[230:233], v[184:187], v[146:149]
	v_mfma_f32_16x16x32_bf16 v[82:85], v[230:233], v[198:201], v[82:85]
	v_add_u32_e32 v106, 0xb0000, v168
	global_load_dwordx4 v[106:109], v106, vcc offset:256
	v_mfma_f32_16x16x32_bf16 v[50:53], v[230:233], v[210:213], v[50:53]
	v_mfma_f32_16x16x32_bf16 v[18:21], v[230:233], v[214:217], v[18:21]
	s_waitcnt vmcnt(7)
	ds_write_b128 v171, v[122:125] offset:24576
	v_mfma_f32_16x16x32_bf16 v[142:145], v[234:237], v[184:187], v[142:145]
	v_mfma_f32_16x16x32_bf16 v[78:81], v[234:237], v[198:201], v[78:81]
	v_add_u32_e32 v122, 0x108000, v168
	global_load_dwordx4 v[122:125], v122, vcc offset:256
	v_mfma_f32_16x16x32_bf16 v[46:49], v[234:237], v[210:213], v[46:49]
	v_mfma_f32_16x16x32_bf16 v[14:17], v[234:237], v[214:217], v[14:17]
	s_waitcnt vmcnt(7)
	ds_write_b128 v171, v[118:121] offset:32768
	v_mfma_f32_16x16x32_bf16 v[138:141], v[238:241], v[184:187], v[138:141]
	v_mfma_f32_16x16x32_bf16 v[74:77], v[238:241], v[198:201], v[74:77]
	global_load_dwordx4 v[118:121], v170, s[100:101] offset:256
	v_mfma_f32_16x16x32_bf16 v[42:45], v[238:241], v[210:213], v[42:45]
	v_mfma_f32_16x16x32_bf16 v[10:13], v[238:241], v[214:217], v[10:13]
	s_waitcnt vmcnt(7)
	ds_write_b128 v171, v[114:117] offset:40960
	v_mfma_f32_16x16x32_bf16 v[134:137], v[242:245], v[184:187], v[134:137]
	v_mfma_f32_16x16x32_bf16 v[70:73], v[242:245], v[198:201], v[70:73]
	v_add_u32_e32 v114, 0x58000, v170
	global_load_dwordx4 v[114:117], v114, s[100:101] offset:256
	v_mfma_f32_16x16x32_bf16 v[38:41], v[242:245], v[210:213], v[38:41]
	v_mfma_f32_16x16x32_bf16 v[6:9], v[242:245], v[214:217], v[6:9]
	s_waitcnt vmcnt(7)
	ds_write_b128 v171, v[130:133] offset:49152
	s_waitcnt lgkmcnt(7)
	v_mfma_f32_16x16x32_bf16 v[98:101], v[246:249], v[184:187], v[98:101]
	v_mfma_f32_16x16x32_bf16 v[66:69], v[246:249], v[198:201], v[66:69]
	v_add_u32_e32 v130, 0xb0000, v170
	global_load_dwordx4 v[130:133], v130, s[100:101] offset:256
	v_mfma_f32_16x16x32_bf16 v[34:37], v[246:249], v[210:213], v[34:37]
	v_mfma_f32_16x16x32_bf16 v[2:5], v[246:249], v[214:217], v[2:5]
	s_waitcnt vmcnt(7)
	ds_write_b128 v171, v[126:129] offset:57344
	v_add_u32_e32 v126, 0x108000, v170
	global_load_dwordx4 v[126:129], v126, s[100:101] offset:256
	v_add_u32_e32 v168, 0x80, v168
	v_add_u32_e32 v170, 0x80, v170
	s_cmp_eq_u32 s20, 44
	s_mov_b32 s4, s20
	s_cbranch_scc0 .Lg1loop_534
	s_waitcnt lgkmcnt(0)
.Lkdone_534:
	s_waitcnt vmcnt(4)
	v_add_u32_e32 v102, s7, v206
	v_or_b32_e32 v104, v102, v205
	v_cmp_lt_i32_e32 vcc, s97, v104
	s_waitcnt vmcnt(3)
	v_ashrrev_i32_e32 v106, 31, v104
	v_add_u32_e32 v107, 0xffffc000, v104
	v_ashrrev_i32_e32 v105, 11, v102
	v_cndmask_b32_e64 v111, v106, 0, vcc
	v_cndmask_b32_e32 v110, v104, v107, vcc
	v_mov_b32_e32 v106, s45
	v_mov_b32_e32 v107, s47
	v_mov_b32_e32 v108, s44
	v_mov_b32_e32 v109, s46
	v_or_b32_e32 v102, s6, v208
	s_waitcnt vmcnt(2)
	v_cndmask_b32_e64 v114, v105, 8, vcc
	v_cndmask_b32_e32 v113, v106, v107, vcc
	v_cndmask_b32_e32 v112, v108, v109, vcc
	v_lshlrev_b64 v[122:123], 12, v[110:111]
	v_ashrrev_i32_e32 v103, 31, v102
	v_lshl_add_u64 v[110:111], v[112:113], 0, v[122:123]
	v_mul_hi_i32_i24_e32 v113, 0x9000, v114
	v_mul_i32_i24_e32 v112, 0x9000, v114
	v_lshl_add_u64 v[112:113], s[12:13], 0, v[112:113]
	v_lshlrev_b64 v[102:103], 2, v[102:103]
	s_waitcnt vmcnt(0)
	v_lshl_add_u64 v[124:125], v[112:113], 0, v[102:103]
	global_load_dwordx4 v[114:117], v[124:125], off
	s_waitcnt vmcnt(1)
	v_lshl_add_u64 v[126:127], v[110:111], 0, v[102:103]
	global_load_dwordx4 v[118:121], v[126:127], off
	v_mov_b32_e32 v110, s49
	v_mov_b32_e32 v111, s17
	v_mov_b32_e32 v112, s48
	v_mov_b32_e32 v113, s16
	v_cndmask_b32_e32 v129, v110, v111, vcc
	v_cndmask_b32_e32 v128, v112, v113, vcc
	v_lshl_add_u64 v[122:123], v[128:129], 0, v[122:123]
	v_lshl_add_u64 v[122:123], v[122:123], 0, v[102:103]
	s_waitcnt vmcnt(1)
	v_pk_mul_f32 v[114:115], v[114:115], 0.5 op_sel_hi:[1,0]
	v_pk_mul_f32 v[116:117], v[116:117], 0.5 op_sel_hi:[1,0]
	s_waitcnt vmcnt(0)
	v_pk_fma_f32 v[114:115], v[158:159], v[114:115], v[118:119]
	v_pk_fma_f32 v[116:117], v[160:161], v[116:117], v[120:121]
	global_store_dwordx4 v[122:123], v[114:117], off
	global_load_dwordx4 v[114:117], v[124:125], off offset:64
	s_nop 0
	global_load_dwordx4 v[118:121], v[126:127], off offset:64
	s_waitcnt vmcnt(1)
	v_pk_mul_f32 v[114:115], v[114:115], 0.5 op_sel_hi:[1,0]
	v_pk_mul_f32 v[116:117], v[116:117], 0.5 op_sel_hi:[1,0]
	s_waitcnt vmcnt(0)
	v_pk_fma_f32 v[114:115], v[154:155], v[114:115], v[118:119]
	v_pk_fma_f32 v[116:117], v[156:157], v[116:117], v[120:121]
	global_store_dwordx4 v[122:123], v[114:117], off offset:64
	global_load_dwordx4 v[114:117], v[124:125], off offset:128
	s_nop 0
	global_load_dwordx4 v[118:121], v[126:127], off offset:128
	s_waitcnt vmcnt(1)
	v_pk_mul_f32 v[114:115], v[114:115], 0.5 op_sel_hi:[1,0]
	v_pk_mul_f32 v[116:117], v[116:117], 0.5 op_sel_hi:[1,0]
	s_waitcnt vmcnt(0)
	v_pk_fma_f32 v[114:115], v[150:151], v[114:115], v[118:119]
	v_pk_fma_f32 v[116:117], v[152:153], v[116:117], v[120:121]
	global_store_dwordx4 v[122:123], v[114:117], off offset:128
	global_load_dwordx4 v[114:117], v[124:125], off offset:192
	s_nop 0
	global_load_dwordx4 v[118:121], v[126:127], off offset:192
	s_waitcnt vmcnt(1)
	v_pk_mul_f32 v[114:115], v[114:115], 0.5 op_sel_hi:[1,0]
	v_pk_mul_f32 v[116:117], v[116:117], 0.5 op_sel_hi:[1,0]
	s_waitcnt vmcnt(0)
	v_pk_fma_f32 v[114:115], v[146:147], v[114:115], v[118:119]
	v_pk_fma_f32 v[116:117], v[148:149], v[116:117], v[120:121]
	global_store_dwordx4 v[122:123], v[114:117], off offset:192
	global_load_dwordx4 v[114:117], v[124:125], off offset:256
	s_nop 0
	global_load_dwordx4 v[118:121], v[126:127], off offset:256
	s_waitcnt vmcnt(1)
	v_pk_mul_f32 v[114:115], v[114:115], 0.5 op_sel_hi:[1,0]
	v_pk_mul_f32 v[116:117], v[116:117], 0.5 op_sel_hi:[1,0]
	s_waitcnt vmcnt(0)
	v_pk_fma_f32 v[114:115], v[142:143], v[114:115], v[118:119]
	v_pk_fma_f32 v[116:117], v[144:145], v[116:117], v[120:121]
	global_store_dwordx4 v[122:123], v[114:117], off offset:256
	global_load_dwordx4 v[114:117], v[124:125], off offset:320
	s_nop 0
	global_load_dwordx4 v[118:121], v[126:127], off offset:320
	s_waitcnt vmcnt(1)
	v_pk_mul_f32 v[114:115], v[114:115], 0.5 op_sel_hi:[1,0]
	v_pk_mul_f32 v[116:117], v[116:117], 0.5 op_sel_hi:[1,0]
	s_waitcnt vmcnt(0)
	v_pk_fma_f32 v[114:115], v[138:139], v[114:115], v[118:119]
	v_pk_fma_f32 v[116:117], v[140:141], v[116:117], v[120:121]
	global_store_dwordx4 v[122:123], v[114:117], off offset:320
	global_load_dwordx4 v[114:117], v[124:125], off offset:384
	s_nop 0
	global_load_dwordx4 v[118:121], v[126:127], off offset:384
	s_waitcnt vmcnt(1)
	v_pk_mul_f32 v[114:115], v[114:115], 0.5 op_sel_hi:[1,0]
	v_pk_mul_f32 v[116:117], v[116:117], 0.5 op_sel_hi:[1,0]
	s_waitcnt vmcnt(0)
	v_pk_fma_f32 v[114:115], v[134:135], v[114:115], v[118:119]
	v_pk_fma_f32 v[116:117], v[136:137], v[116:117], v[120:121]
	global_store_dwordx4 v[122:123], v[114:117], off offset:384
	global_load_dwordx4 v[114:117], v[124:125], off offset:448
	s_nop 0
	global_load_dwordx4 v[118:121], v[126:127], off offset:448
	s_waitcnt vmcnt(1)
	v_pk_mul_f32 v[114:115], v[114:115], 0.5 op_sel_hi:[1,0]
	v_pk_mul_f32 v[116:117], v[116:117], 0.5 op_sel_hi:[1,0]
	s_waitcnt vmcnt(0)
	v_pk_fma_f32 v[98:99], v[98:99], v[114:115], v[118:119]
	v_pk_fma_f32 v[100:101], v[100:101], v[116:117], v[120:121]
	global_store_dwordx4 v[122:123], v[98:101], off offset:448
	s_nop 1
	v_or_b32_e32 v98, 16, v104
	v_cmp_lt_i32_e32 vcc, s97, v98
	v_add_u32_e32 v100, 0xffffc010, v104
	v_ashrrev_i32_e32 v99, 31, v98
	v_cndmask_b32_e64 v116, v105, 8, vcc
	v_cndmask_b32_e64 v99, v99, 0, vcc
	v_cndmask_b32_e32 v98, v98, v100, vcc
	v_lshlrev_b64 v[118:119], 12, v[98:99]
	v_mul_hi_i32_i24_e32 v99, 0x9000, v116
	v_mul_i32_i24_e32 v98, 0x9000, v116
	v_cndmask_b32_e32 v101, v106, v107, vcc
	v_cndmask_b32_e32 v100, v108, v109, vcc
	v_lshl_add_u64 v[98:99], s[12:13], 0, v[98:99]
	v_lshl_add_u64 v[114:115], v[100:101], 0, v[118:119]
	v_lshl_add_u64 v[120:121], v[98:99], 0, v[102:103]
	global_load_dwordx4 v[98:101], v[120:121], off
	v_lshl_add_u64 v[122:123], v[114:115], 0, v[102:103]
	global_load_dwordx4 v[114:117], v[122:123], off
	v_cndmask_b32_e32 v125, v110, v111, vcc
	v_cndmask_b32_e32 v124, v112, v113, vcc
	v_lshl_add_u64 v[118:119], v[124:125], 0, v[118:119]
	v_lshl_add_u64 v[118:119], v[118:119], 0, v[102:103]
	s_waitcnt vmcnt(1)
	v_pk_mul_f32 v[98:99], v[98:99], 0.5 op_sel_hi:[1,0]
	v_pk_mul_f32 v[100:101], v[100:101], 0.5 op_sel_hi:[1,0]
	s_waitcnt vmcnt(0)
	v_pk_fma_f32 v[94:95], v[94:95], v[98:99], v[114:115]
	v_pk_fma_f32 v[96:97], v[96:97], v[100:101], v[116:117]
	global_store_dwordx4 v[118:119], v[94:97], off
	global_load_dwordx4 v[94:97], v[120:121], off offset:64
	s_nop 0
	global_load_dwordx4 v[98:101], v[122:123], off offset:64
	s_waitcnt vmcnt(1)
	v_pk_mul_f32 v[94:95], v[94:95], 0.5 op_sel_hi:[1,0]
	v_pk_mul_f32 v[96:97], v[96:97], 0.5 op_sel_hi:[1,0]
	s_waitcnt vmcnt(0)
	v_pk_fma_f32 v[90:91], v[90:91], v[94:95], v[98:99]
	v_pk_fma_f32 v[92:93], v[92:93], v[96:97], v[100:101]
	global_store_dwordx4 v[118:119], v[90:93], off offset:64
	global_load_dwordx4 v[90:93], v[120:121], off offset:128
	s_nop 0
	global_load_dwordx4 v[94:97], v[122:123], off offset:128
	s_waitcnt vmcnt(1)
	v_pk_mul_f32 v[90:91], v[90:91], 0.5 op_sel_hi:[1,0]
	v_pk_mul_f32 v[92:93], v[92:93], 0.5 op_sel_hi:[1,0]
	s_waitcnt vmcnt(0)
	v_pk_fma_f32 v[86:87], v[86:87], v[90:91], v[94:95]
	v_pk_fma_f32 v[88:89], v[88:89], v[92:93], v[96:97]
	global_store_dwordx4 v[118:119], v[86:89], off offset:128
	global_load_dwordx4 v[86:89], v[120:121], off offset:192
	s_nop 0
	global_load_dwordx4 v[90:93], v[122:123], off offset:192
	s_waitcnt vmcnt(1)
	v_pk_mul_f32 v[86:87], v[86:87], 0.5 op_sel_hi:[1,0]
	v_pk_mul_f32 v[88:89], v[88:89], 0.5 op_sel_hi:[1,0]
	s_waitcnt vmcnt(0)
	v_pk_fma_f32 v[82:83], v[82:83], v[86:87], v[90:91]
	v_pk_fma_f32 v[84:85], v[84:85], v[88:89], v[92:93]
	global_store_dwordx4 v[118:119], v[82:85], off offset:192
	global_load_dwordx4 v[82:85], v[120:121], off offset:256
	s_nop 0
	global_load_dwordx4 v[86:89], v[122:123], off offset:256
	s_waitcnt vmcnt(1)
	v_pk_mul_f32 v[82:83], v[82:83], 0.5 op_sel_hi:[1,0]
	v_pk_mul_f32 v[84:85], v[84:85], 0.5 op_sel_hi:[1,0]
	s_waitcnt vmcnt(0)
	v_pk_fma_f32 v[78:79], v[78:79], v[82:83], v[86:87]
	v_pk_fma_f32 v[80:81], v[80:81], v[84:85], v[88:89]
	global_store_dwordx4 v[118:119], v[78:81], off offset:256
	global_load_dwordx4 v[78:81], v[120:121], off offset:320
	s_nop 0
	global_load_dwordx4 v[82:85], v[122:123], off offset:320
	s_waitcnt vmcnt(1)
	v_pk_mul_f32 v[78:79], v[78:79], 0.5 op_sel_hi:[1,0]
	v_pk_mul_f32 v[80:81], v[80:81], 0.5 op_sel_hi:[1,0]
	s_waitcnt vmcnt(0)
	v_pk_fma_f32 v[74:75], v[74:75], v[78:79], v[82:83]
	v_pk_fma_f32 v[76:77], v[76:77], v[80:81], v[84:85]
	global_store_dwordx4 v[118:119], v[74:77], off offset:320
	global_load_dwordx4 v[74:77], v[120:121], off offset:384
	s_nop 0
	global_load_dwordx4 v[78:81], v[122:123], off offset:384
	s_waitcnt vmcnt(1)
	v_pk_mul_f32 v[74:75], v[74:75], 0.5 op_sel_hi:[1,0]
	v_pk_mul_f32 v[76:77], v[76:77], 0.5 op_sel_hi:[1,0]
	s_waitcnt vmcnt(0)
	v_pk_fma_f32 v[70:71], v[70:71], v[74:75], v[78:79]
	v_pk_fma_f32 v[72:73], v[72:73], v[76:77], v[80:81]
	global_store_dwordx4 v[118:119], v[70:73], off offset:384
	global_load_dwordx4 v[70:73], v[120:121], off offset:448
	s_nop 0
	global_load_dwordx4 v[74:77], v[122:123], off offset:448
	s_waitcnt vmcnt(1)
	v_pk_mul_f32 v[70:71], v[70:71], 0.5 op_sel_hi:[1,0]
	v_pk_mul_f32 v[72:73], v[72:73], 0.5 op_sel_hi:[1,0]
	s_waitcnt vmcnt(0)
	v_pk_fma_f32 v[66:67], v[66:67], v[70:71], v[74:75]
	v_pk_fma_f32 v[68:69], v[68:69], v[72:73], v[76:77]
	global_store_dwordx4 v[118:119], v[66:69], off offset:448
	s_nop 1
	v_or_b32_e32 v66, 32, v104
	v_cmp_lt_i32_e32 vcc, s97, v66
	v_add_u32_e32 v68, 0xffffc020, v104
	v_ashrrev_i32_e32 v67, 31, v66
	v_cndmask_b32_e64 v72, v105, 8, vcc
	v_cndmask_b32_e64 v67, v67, 0, vcc
	v_cndmask_b32_e32 v66, v66, v68, vcc
	v_lshlrev_b64 v[74:75], 12, v[66:67]
	v_mul_hi_i32_i24_e32 v67, 0x9000, v72
	v_mul_i32_i24_e32 v66, 0x9000, v72
	v_cndmask_b32_e32 v69, v106, v107, vcc
	v_cndmask_b32_e32 v68, v108, v109, vcc
	v_lshl_add_u64 v[66:67], s[12:13], 0, v[66:67]
	v_lshl_add_u64 v[70:71], v[68:69], 0, v[74:75]
	v_lshl_add_u64 v[76:77], v[66:67], 0, v[102:103]
	global_load_dwordx4 v[66:69], v[76:77], off
	v_lshl_add_u64 v[78:79], v[70:71], 0, v[102:103]
	global_load_dwordx4 v[70:73], v[78:79], off
	v_cndmask_b32_e32 v81, v110, v111, vcc
	v_cndmask_b32_e32 v80, v112, v113, vcc
	v_lshl_add_u64 v[74:75], v[80:81], 0, v[74:75]
	v_lshl_add_u64 v[74:75], v[74:75], 0, v[102:103]
	s_waitcnt vmcnt(1)
	v_pk_mul_f32 v[66:67], v[66:67], 0.5 op_sel_hi:[1,0]
	v_pk_mul_f32 v[68:69], v[68:69], 0.5 op_sel_hi:[1,0]
	s_waitcnt vmcnt(0)
	v_pk_fma_f32 v[62:63], v[62:63], v[66:67], v[70:71]
	v_pk_fma_f32 v[64:65], v[64:65], v[68:69], v[72:73]
	global_store_dwordx4 v[74:75], v[62:65], off
	global_load_dwordx4 v[62:65], v[76:77], off offset:64
	s_nop 0
	global_load_dwordx4 v[66:69], v[78:79], off offset:64
	s_waitcnt vmcnt(1)
	v_pk_mul_f32 v[62:63], v[62:63], 0.5 op_sel_hi:[1,0]
	v_pk_mul_f32 v[64:65], v[64:65], 0.5 op_sel_hi:[1,0]
	s_waitcnt vmcnt(0)
	v_pk_fma_f32 v[58:59], v[58:59], v[62:63], v[66:67]
	v_pk_fma_f32 v[60:61], v[60:61], v[64:65], v[68:69]
	global_store_dwordx4 v[74:75], v[58:61], off offset:64
	global_load_dwordx4 v[58:61], v[76:77], off offset:128
	s_nop 0
	global_load_dwordx4 v[62:65], v[78:79], off offset:128
	s_waitcnt vmcnt(1)
	v_pk_mul_f32 v[58:59], v[58:59], 0.5 op_sel_hi:[1,0]
	v_pk_mul_f32 v[60:61], v[60:61], 0.5 op_sel_hi:[1,0]
	s_waitcnt vmcnt(0)
	v_pk_fma_f32 v[54:55], v[54:55], v[58:59], v[62:63]
	v_pk_fma_f32 v[56:57], v[56:57], v[60:61], v[64:65]
	global_store_dwordx4 v[74:75], v[54:57], off offset:128
	global_load_dwordx4 v[54:57], v[76:77], off offset:192
	s_nop 0
	global_load_dwordx4 v[58:61], v[78:79], off offset:192
	s_waitcnt vmcnt(1)
	v_pk_mul_f32 v[54:55], v[54:55], 0.5 op_sel_hi:[1,0]
	v_pk_mul_f32 v[56:57], v[56:57], 0.5 op_sel_hi:[1,0]
	s_waitcnt vmcnt(0)
	v_pk_fma_f32 v[50:51], v[50:51], v[54:55], v[58:59]
	v_pk_fma_f32 v[52:53], v[52:53], v[56:57], v[60:61]
	global_store_dwordx4 v[74:75], v[50:53], off offset:192
	global_load_dwordx4 v[50:53], v[76:77], off offset:256
	s_nop 0
	global_load_dwordx4 v[54:57], v[78:79], off offset:256
	s_waitcnt vmcnt(1)
	v_pk_mul_f32 v[50:51], v[50:51], 0.5 op_sel_hi:[1,0]
	v_pk_mul_f32 v[52:53], v[52:53], 0.5 op_sel_hi:[1,0]
	s_waitcnt vmcnt(0)
	v_pk_fma_f32 v[46:47], v[46:47], v[50:51], v[54:55]
	v_pk_fma_f32 v[48:49], v[48:49], v[52:53], v[56:57]
	global_store_dwordx4 v[74:75], v[46:49], off offset:256
	global_load_dwordx4 v[46:49], v[76:77], off offset:320
	s_nop 0
	global_load_dwordx4 v[50:53], v[78:79], off offset:320
	s_waitcnt vmcnt(1)
	v_pk_mul_f32 v[46:47], v[46:47], 0.5 op_sel_hi:[1,0]
	v_pk_mul_f32 v[48:49], v[48:49], 0.5 op_sel_hi:[1,0]
	s_waitcnt vmcnt(0)
	v_pk_fma_f32 v[42:43], v[42:43], v[46:47], v[50:51]
	v_pk_fma_f32 v[44:45], v[44:45], v[48:49], v[52:53]
	global_store_dwordx4 v[74:75], v[42:45], off offset:320
	global_load_dwordx4 v[42:45], v[76:77], off offset:384
	s_nop 0
	global_load_dwordx4 v[46:49], v[78:79], off offset:384
	s_waitcnt vmcnt(1)
	v_pk_mul_f32 v[42:43], v[42:43], 0.5 op_sel_hi:[1,0]
	v_pk_mul_f32 v[44:45], v[44:45], 0.5 op_sel_hi:[1,0]
	s_waitcnt vmcnt(0)
	v_pk_fma_f32 v[38:39], v[38:39], v[42:43], v[46:47]
	v_pk_fma_f32 v[40:41], v[40:41], v[44:45], v[48:49]
	global_store_dwordx4 v[74:75], v[38:41], off offset:384
	global_load_dwordx4 v[38:41], v[76:77], off offset:448
	s_nop 0
	global_load_dwordx4 v[42:45], v[78:79], off offset:448
	s_waitcnt vmcnt(1)
	v_pk_mul_f32 v[38:39], v[38:39], 0.5 op_sel_hi:[1,0]
	v_pk_mul_f32 v[40:41], v[40:41], 0.5 op_sel_hi:[1,0]
	s_waitcnt vmcnt(0)
	v_pk_fma_f32 v[34:35], v[34:35], v[38:39], v[42:43]
	v_pk_fma_f32 v[36:37], v[36:37], v[40:41], v[44:45]
	global_store_dwordx4 v[74:75], v[34:37], off offset:448
	s_nop 1
	v_or_b32_e32 v34, 48, v104
	v_cmp_lt_i32_e32 vcc, s97, v34
	v_add_u32_e32 v36, 0xffffc030, v104
	v_ashrrev_i32_e32 v35, 31, v34
	v_cndmask_b32_e64 v35, v35, 0, vcc
	v_cndmask_b32_e32 v34, v34, v36, vcc
	v_cndmask_b32_e64 v40, v105, 8, vcc
	v_cndmask_b32_e32 v37, v106, v107, vcc
	v_cndmask_b32_e32 v36, v108, v109, vcc
	v_lshlrev_b64 v[34:35], 12, v[34:35]
	v_cndmask_b32_e32 v39, v110, v111, vcc
	v_cndmask_b32_e32 v38, v112, v113, vcc
	v_lshl_add_u64 v[36:37], v[36:37], 0, v[34:35]
	v_lshl_add_u64 v[34:35], v[38:39], 0, v[34:35]
	v_mul_hi_i32_i24_e32 v39, 0x9000, v40
	v_mul_i32_i24_e32 v38, 0x9000, v40
	v_lshl_add_u64 v[38:39], s[12:13], 0, v[38:39]
	v_lshl_add_u64 v[42:43], v[38:39], 0, v[102:103]
	v_lshl_add_u64 v[44:45], v[36:37], 0, v[102:103]
	v_lshl_add_u64 v[46:47], v[34:35], 0, v[102:103]
	global_load_dwordx4 v[34:37], v[42:43], off
	global_load_dwordx4 v[38:41], v[44:45], off
	s_waitcnt vmcnt(1)
	v_pk_mul_f32 v[34:35], v[34:35], 0.5 op_sel_hi:[1,0]
	s_waitcnt vmcnt(0)
	v_pk_fma_f32 v[30:31], v[30:31], v[34:35], v[38:39]
	v_pk_mul_f32 v[34:35], v[36:37], 0.5 op_sel_hi:[1,0]
	s_nop 0
	v_pk_fma_f32 v[32:33], v[32:33], v[34:35], v[40:41]
	global_store_dwordx4 v[46:47], v[30:33], off
	global_load_dwordx4 v[30:33], v[42:43], off offset:64
	s_nop 0
	global_load_dwordx4 v[34:37], v[44:45], off offset:64
	s_waitcnt vmcnt(1)
	v_pk_mul_f32 v[30:31], v[30:31], 0.5 op_sel_hi:[1,0]
	s_waitcnt vmcnt(0)
	v_pk_fma_f32 v[26:27], v[26:27], v[30:31], v[34:35]
	v_pk_mul_f32 v[30:31], v[32:33], 0.5 op_sel_hi:[1,0]
	s_nop 0
	v_pk_fma_f32 v[28:29], v[28:29], v[30:31], v[36:37]
	global_store_dwordx4 v[46:47], v[26:29], off offset:64
	global_load_dwordx4 v[26:29], v[42:43], off offset:128
	s_nop 0
	global_load_dwordx4 v[30:33], v[44:45], off offset:128
	s_waitcnt vmcnt(1)
	v_pk_mul_f32 v[26:27], v[26:27], 0.5 op_sel_hi:[1,0]
	s_waitcnt vmcnt(0)
	v_pk_fma_f32 v[22:23], v[22:23], v[26:27], v[30:31]
	v_pk_mul_f32 v[26:27], v[28:29], 0.5 op_sel_hi:[1,0]
	s_nop 0
	v_pk_fma_f32 v[24:25], v[24:25], v[26:27], v[32:33]
	global_store_dwordx4 v[46:47], v[22:25], off offset:128
	global_load_dwordx4 v[22:25], v[42:43], off offset:192
	s_nop 0
	global_load_dwordx4 v[26:29], v[44:45], off offset:192
	s_waitcnt vmcnt(1)
	v_pk_mul_f32 v[22:23], v[22:23], 0.5 op_sel_hi:[1,0]
	s_waitcnt vmcnt(0)
	v_pk_fma_f32 v[18:19], v[18:19], v[22:23], v[26:27]
	v_pk_mul_f32 v[22:23], v[24:25], 0.5 op_sel_hi:[1,0]
	s_nop 0
	v_pk_fma_f32 v[20:21], v[20:21], v[22:23], v[28:29]
	global_store_dwordx4 v[46:47], v[18:21], off offset:192
	global_load_dwordx4 v[18:21], v[42:43], off offset:256
	s_nop 0
	global_load_dwordx4 v[22:25], v[44:45], off offset:256
	s_waitcnt vmcnt(1)
	v_pk_mul_f32 v[18:19], v[18:19], 0.5 op_sel_hi:[1,0]
	s_waitcnt vmcnt(0)
	v_pk_fma_f32 v[14:15], v[14:15], v[18:19], v[22:23]
	v_pk_mul_f32 v[18:19], v[20:21], 0.5 op_sel_hi:[1,0]
	s_nop 0
	v_pk_fma_f32 v[16:17], v[16:17], v[18:19], v[24:25]
	global_store_dwordx4 v[46:47], v[14:17], off offset:256
	global_load_dwordx4 v[14:17], v[42:43], off offset:320
	s_nop 0
	global_load_dwordx4 v[18:21], v[44:45], off offset:320
	s_waitcnt vmcnt(1)
	v_pk_mul_f32 v[14:15], v[14:15], 0.5 op_sel_hi:[1,0]
	s_waitcnt vmcnt(0)
	v_pk_fma_f32 v[10:11], v[10:11], v[14:15], v[18:19]
	v_pk_mul_f32 v[14:15], v[16:17], 0.5 op_sel_hi:[1,0]
	s_nop 0
	v_pk_fma_f32 v[12:13], v[12:13], v[14:15], v[20:21]
	global_store_dwordx4 v[46:47], v[10:13], off offset:320
	global_load_dwordx4 v[10:13], v[42:43], off offset:384
	s_nop 0
	global_load_dwordx4 v[14:17], v[44:45], off offset:384
	s_waitcnt vmcnt(1)
	v_pk_mul_f32 v[10:11], v[10:11], 0.5 op_sel_hi:[1,0]
	s_waitcnt vmcnt(0)
	v_pk_fma_f32 v[6:7], v[6:7], v[10:11], v[14:15]
	v_pk_mul_f32 v[10:11], v[12:13], 0.5 op_sel_hi:[1,0]
	s_nop 0
	v_pk_fma_f32 v[8:9], v[8:9], v[10:11], v[16:17]
	global_store_dwordx4 v[46:47], v[6:9], off offset:384
	global_load_dwordx4 v[6:9], v[42:43], off offset:448
	s_nop 0
	global_load_dwordx4 v[10:13], v[44:45], off offset:448
	s_waitcnt vmcnt(1)
	v_pk_mul_f32 v[6:7], v[6:7], 0.5 op_sel_hi:[1,0]
	s_waitcnt vmcnt(0)
	v_pk_fma_f32 v[2:3], v[2:3], v[6:7], v[10:11]
	v_pk_mul_f32 v[6:7], v[8:9], 0.5 op_sel_hi:[1,0]
	s_nop 0
	v_pk_fma_f32 v[4:5], v[4:5], v[6:7], v[12:13]
	global_store_dwordx4 v[46:47], v[2:5], off offset:448
	s_add_i32 s11, s11, s10
	s_cmpk_gt_i32 s11, 0xff
	s_cbranch_scc0 .LBB0_533

.LBB0_664:
	s_mul_hi_i32 s4, s11, 0x38e38e39
	s_lshr_b32 s6, s4, 31
	s_ashr_i32 s4, s4, 4
	s_add_i32 s4, s4, s6
	s_mul_i32 s6, s4, 0x48
	s_sub_i32 s6, s11, s6
	s_lshl_b32 s6, s6, 8
	v_add_u32_e32 v2, s6, v204
	v_ashrrev_i32_e32 v3, 31, v2
	v_lshlrev_b64 v[2:3], 11, v[2:3]
	v_lshl_add_u64 v[168:169], v[162:163], 0, v[2:3]
	v_add_co_u32_e32 v56, vcc, s34, v168
	s_lshl_b32 s7, s4, 8
	s_nop 0
	v_addc_co_u32_e32 v57, vcc, 0, v169, vcc
	v_add_u32_e32 v2, s7, v204
	v_add_co_u32_e32 v58, vcc, s35, v168
	v_ashrrev_i32_e32 v3, 31, v2
	s_nop 0
	v_addc_co_u32_e32 v59, vcc, 0, v169, vcc
	v_lshlrev_b64 v[2:3], 11, v[2:3]
	v_add_co_u32_e32 v60, vcc, s36, v168
	v_lshl_add_u64 v[170:171], v[164:165], 0, v[2:3]
	s_nop 0
	v_addc_co_u32_e32 v61, vcc, 0, v169, vcc
	v_add_co_u32_e32 v62, vcc, s35, v170
	global_load_dwordx4 v[24:27], v[56:57], off
	global_load_dwordx4 v[28:31], v[58:59], off
	v_addc_co_u32_e32 v63, vcc, 0, v171, vcc
	v_add_co_u32_e32 v64, vcc, s36, v170
	global_load_dwordx4 v[32:35], v[168:169], off
	global_load_dwordx4 v[36:39], v[170:171], off
	v_addc_co_u32_e32 v65, vcc, 0, v171, vcc
	v_add_co_u32_e32 v66, vcc, s34, v170
	global_load_dwordx4 v[40:43], v[62:63], off
	global_load_dwordx4 v[44:47], v[64:65], off
	v_addc_co_u32_e32 v67, vcc, 0, v171, vcc
	global_load_dwordx4 v[48:51], v[60:61], off
	global_load_dwordx4 v[52:55], v[66:67], off
	s_barrier
	global_load_dwordx4 v[94:97], v[168:169], off offset:128
	global_load_dwordx4 v[86:89], v[56:57], off offset:128
	global_load_dwordx4 v[90:93], v[58:59], off offset:128
	global_load_dwordx4 v[106:109], v[60:61], off offset:128
	global_load_dwordx4 v[102:105], v[170:171], off offset:128
	global_load_dwordx4 v[98:101], v[66:67], off offset:128
	global_load_dwordx4 v[118:121], v[62:63], off offset:128
	global_load_dwordx4 v[110:113], v[64:65], off offset:128
	v_readfirstlane_b32 s100, v172
	s_nop 0
	s_lshr_b32 m0, s100, 8
	v_readfirstlane_b32 vcc_lo, v168
	v_readfirstlane_b32 vcc_hi, v169
	v_readfirstlane_b32 s100, v170
	v_readfirstlane_b32 s101, v171
	s_nop 1
	v_subrev_u32_e32 v168, vcc_lo, v168
	v_subrev_u32_e32 v170, s100, v170
	v_mov_b32_e32 v2, 0
	s_mov_b32 s4, 0
	v_mov_b32_e32 v3, v2
	v_mov_b32_e32 v4, v2
	v_mov_b32_e32 v5, v2
	v_mov_b32_e32 v6, v2
	v_mov_b32_e32 v7, v2
	v_mov_b32_e32 v8, v2
	v_mov_b32_e32 v9, v2
	v_mov_b32_e32 v10, v2
	v_mov_b32_e32 v11, v2
	v_mov_b32_e32 v12, v2
	v_mov_b32_e32 v13, v2
	v_mov_b32_e32 v14, v2
	v_mov_b32_e32 v15, v2
	v_mov_b32_e32 v16, v2
	v_mov_b32_e32 v17, v2
	v_mov_b32_e32 v18, v2
	v_mov_b32_e32 v19, v2
	v_mov_b32_e32 v20, v2
	v_mov_b32_e32 v21, v2
	v_mov_b32_e32 v22, v2
	v_mov_b32_e32 v23, v2
	v_mov_b32_e32 v56, v2
	v_mov_b32_e32 v57, v2
	v_mov_b32_e32 v58, v2
	v_mov_b32_e32 v59, v2
	v_mov_b32_e32 v60, v2
	v_mov_b32_e32 v61, v2
	v_mov_b32_e32 v66, v2
	v_mov_b32_e32 v67, v2
	v_mov_b32_e32 v68, v2
	v_mov_b32_e32 v69, v2
	v_mov_b32_e32 v62, v2
	v_mov_b32_e32 v63, v2
	v_mov_b32_e32 v64, v2
	v_mov_b32_e32 v65, v2
	v_mov_b32_e32 v70, v2
	v_mov_b32_e32 v71, v2
	v_mov_b32_e32 v72, v2
	v_mov_b32_e32 v73, v2
	v_mov_b32_e32 v74, v2
	v_mov_b32_e32 v75, v2
	v_mov_b32_e32 v76, v2
	v_mov_b32_e32 v77, v2
	v_mov_b32_e32 v78, v2
	v_mov_b32_e32 v79, v2
	v_mov_b32_e32 v80, v2
	v_mov_b32_e32 v81, v2
	v_mov_b32_e32 v82, v2
	v_mov_b32_e32 v83, v2
	v_mov_b32_e32 v84, v2
	v_mov_b32_e32 v85, v2
	s_waitcnt vmcnt(11)
	ds_write_b128 v166, v[40:43] offset:49152
	s_waitcnt vmcnt(10)
	ds_write_b128 v166, v[44:47] offset:57344
	ds_write_b128 v166, v[32:35]
	ds_write_b128 v166, v[36:39] offset:32768
	ds_write_b128 v166, v[24:27] offset:8192
	ds_write_b128 v166, v[28:31] offset:16384
	s_waitcnt vmcnt(9)
	ds_write_b128 v166, v[48:51] offset:24576
	s_waitcnt vmcnt(8)
	ds_write_b128 v166, v[52:55] offset:40960
	v_mov_b32_e32 v24, v2
	v_mov_b32_e32 v25, v2
	v_mov_b32_e32 v26, v2
	v_mov_b32_e32 v27, v2
	v_mov_b32_e32 v28, v2
	v_mov_b32_e32 v29, v2
	v_mov_b32_e32 v34, v2
	v_mov_b32_e32 v35, v2
	v_mov_b32_e32 v36, v2
	v_mov_b32_e32 v37, v2
	v_mov_b32_e32 v30, v2
	v_mov_b32_e32 v31, v2
	v_mov_b32_e32 v32, v2
	v_mov_b32_e32 v33, v2
	v_mov_b32_e32 v38, v2
	v_mov_b32_e32 v39, v2
	v_mov_b32_e32 v40, v2
	v_mov_b32_e32 v41, v2
	v_mov_b32_e32 v42, v2
	v_mov_b32_e32 v43, v2
	v_mov_b32_e32 v44, v2
	v_mov_b32_e32 v45, v2
	v_mov_b32_e32 v46, v2
	v_mov_b32_e32 v47, v2
	v_mov_b32_e32 v48, v2
	v_mov_b32_e32 v49, v2
	v_mov_b32_e32 v50, v2
	v_mov_b32_e32 v51, v2
	v_mov_b32_e32 v52, v2
	v_mov_b32_e32 v53, v2
	v_mov_b32_e32 v54, v2
	v_mov_b32_e32 v55, v2
	v_mov_b32_e32 v114, v2
	v_mov_b32_e32 v115, v2
	v_mov_b32_e32 v116, v2
	v_mov_b32_e32 v117, v2
	v_mov_b32_e32 v122, v2
	v_mov_b32_e32 v123, v2
	v_mov_b32_e32 v124, v2
	v_mov_b32_e32 v125, v2
	v_mov_b32_e32 v130, v2
	v_mov_b32_e32 v131, v2
	v_mov_b32_e32 v132, v2
	v_mov_b32_e32 v133, v2
	v_mov_b32_e32 v126, v2
	v_mov_b32_e32 v127, v2
	v_mov_b32_e32 v128, v2
	v_mov_b32_e32 v129, v2
	v_mov_b32_e32 v134, v2
	v_mov_b32_e32 v135, v2
	v_mov_b32_e32 v136, v2
	v_mov_b32_e32 v137, v2
	v_mov_b32_e32 v138, v2
	v_mov_b32_e32 v139, v2
	v_mov_b32_e32 v140, v2
	v_mov_b32_e32 v141, v2
	v_mov_b32_e32 v142, v2
	v_mov_b32_e32 v143, v2
	v_mov_b32_e32 v144, v2
	v_mov_b32_e32 v145, v2
	v_mov_b32_e32 v146, v2
	v_mov_b32_e32 v147, v2
	v_mov_b32_e32 v148, v2
	v_mov_b32_e32 v149, v2
	v_mov_b32_e32 v150, v2
	v_mov_b32_e32 v151, v2
	v_mov_b32_e32 v152, v2
	v_mov_b32_e32 v153, v2
	v_mov_b32_e32 v154, v2
	v_mov_b32_e32 v155, v2
	v_mov_b32_e32 v156, v2
	v_mov_b32_e32 v157, v2
	v_mov_b32_e32 v158, v2
	v_mov_b32_e32 v159, v2
	v_mov_b32_e32 v160, v2
	v_mov_b32_e32 v161, v2
	s_waitcnt lgkmcnt(0)
	s_barrier
	s_cmp_lg_u32 m0, 0
	s_cbranch_scc1 .Lg1_665
.LBB0_665:
	s_bitcmp1_b32 s4, 0
	s_cselect_b32 s15, 0x12000, 0
	v_or_b32_e32 v208, s15, v206
	v_add_u32_e32 v214, v208, v0
	v_add_u32_e32 v208, v208, v167
	ds_read_b128 v[184:187], v214
	ds_read_b128 v[218:221], v208 offset:32768
	ds_read_b128 v[198:201], v214 offset:2048
	ds_read_b128 v[210:213], v214 offset:4096
	ds_read_b128 v[214:217], v214 offset:6144
	ds_read_b128 v[222:225], v208 offset:34816
	ds_read_b128 v[226:229], v208 offset:36864
	ds_read_b128 v[230:233], v208 offset:38912
	ds_read_b128 v[234:237], v208 offset:40960
	ds_read_b128 v[238:241], v208 offset:43008
	ds_read_b128 v[242:245], v208 offset:45056
	ds_read_b128 v[246:249], v208 offset:47104
	s_add_i32 s14, s4, 1
	s_bitcmp1_b32 s14, 0
	s_cselect_b32 s16, 0x12000, 0
	v_add_u32_e32 v208, s16, v166
	v_add_u32_e32 v171, s16, v166
	v_xor_b32_e32 v169, 64, v206
	v_add3_u32 v169, s15, v167, v169
	s_waitcnt lgkmcnt(10)
	v_mfma_f32_16x16x32_bf16 v[158:161], v[218:221], v[184:187], v[158:161]
	s_waitcnt lgkmcnt(9)
	v_mfma_f32_16x16x32_bf16 v[130:133], v[218:221], v[198:201], v[130:133]
	s_waitcnt lgkmcnt(8)
	v_mfma_f32_16x16x32_bf16 v[66:69], v[218:221], v[210:213], v[66:69]
	s_waitcnt lgkmcnt(7)
	v_mfma_f32_16x16x32_bf16 v[34:37], v[218:221], v[214:217], v[34:37]
	ds_read_b128 v[218:221], v169 offset:32768
	s_waitcnt lgkmcnt(7)
	v_mfma_f32_16x16x32_bf16 v[154:157], v[222:225], v[184:187], v[154:157]
	v_mfma_f32_16x16x32_bf16 v[122:125], v[222:225], v[198:201], v[122:125]
	v_mfma_f32_16x16x32_bf16 v[58:61], v[222:225], v[210:213], v[58:61]
	v_mfma_f32_16x16x32_bf16 v[26:29], v[222:225], v[214:217], v[26:29]
	ds_read_b128 v[222:225], v169 offset:34816
	s_waitcnt lgkmcnt(7)
	v_mfma_f32_16x16x32_bf16 v[150:153], v[226:229], v[184:187], v[150:153]
	v_mfma_f32_16x16x32_bf16 v[114:117], v[226:229], v[198:201], v[114:117]
	v_mfma_f32_16x16x32_bf16 v[54:57], v[226:229], v[210:213], v[54:57]
	v_mfma_f32_16x16x32_bf16 v[22:25], v[226:229], v[214:217], v[22:25]
	ds_read_b128 v[226:229], v169 offset:36864
	s_waitcnt lgkmcnt(7)
	v_mfma_f32_16x16x32_bf16 v[146:149], v[230:233], v[184:187], v[146:149]
	v_mfma_f32_16x16x32_bf16 v[82:85], v[230:233], v[198:201], v[82:85]
	v_mfma_f32_16x16x32_bf16 v[50:53], v[230:233], v[210:213], v[50:53]
	v_mfma_f32_16x16x32_bf16 v[18:21], v[230:233], v[214:217], v[18:21]
	ds_read_b128 v[230:233], v169 offset:38912
	s_waitcnt lgkmcnt(7)
	v_mfma_f32_16x16x32_bf16 v[142:145], v[234:237], v[184:187], v[142:145]
	v_mfma_f32_16x16x32_bf16 v[78:81], v[234:237], v[198:201], v[78:81]
	v_mfma_f32_16x16x32_bf16 v[46:49], v[234:237], v[210:213], v[46:49]
	v_mfma_f32_16x16x32_bf16 v[14:17], v[234:237], v[214:217], v[14:17]
	ds_read_b128 v[234:237], v169 offset:40960
	s_waitcnt lgkmcnt(7)
	v_mfma_f32_16x16x32_bf16 v[138:141], v[238:241], v[184:187], v[138:141]
	v_mfma_f32_16x16x32_bf16 v[74:77], v[238:241], v[198:201], v[74:77]
	v_mfma_f32_16x16x32_bf16 v[42:45], v[238:241], v[210:213], v[42:45]
	v_mfma_f32_16x16x32_bf16 v[10:13], v[238:241], v[214:217], v[10:13]
	ds_read_b128 v[238:241], v169 offset:43008
	s_waitcnt lgkmcnt(7)
	v_mfma_f32_16x16x32_bf16 v[134:137], v[242:245], v[184:187], v[134:137]
	v_mfma_f32_16x16x32_bf16 v[70:73], v[242:245], v[198:201], v[70:73]
	v_mfma_f32_16x16x32_bf16 v[38:41], v[242:245], v[210:213], v[38:41]
	v_mfma_f32_16x16x32_bf16 v[6:9], v[242:245], v[214:217], v[6:9]
	ds_read_b128 v[242:245], v169 offset:45056
	s_waitcnt lgkmcnt(7)
	v_mfma_f32_16x16x32_bf16 v[126:129], v[246:249], v[184:187], v[126:129]
	v_mfma_f32_16x16x32_bf16 v[62:65], v[246:249], v[198:201], v[62:65]
	v_xor_b32_e32 v169, 64, v206
	v_add3_u32 v169, s15, v0, v169
	ds_read_b128 v[184:187], v169
	ds_read_b128 v[198:201], v169 offset:2048
	v_mfma_f32_16x16x32_bf16 v[30:33], v[246:249], v[210:213], v[30:33]
	ds_read_b128 v[210:213], v169 offset:4096
	v_mfma_f32_16x16x32_bf16 v[2:5], v[246:249], v[214:217], v[2:5]
	ds_read_b128 v[214:217], v169 offset:6144
	v_xor_b32_e32 v169, 64, v206
	v_add3_u32 v169, s15, v167, v169
	ds_read_b128 v[246:249], v169 offset:47104
	s_waitcnt lgkmcnt(4)
	v_mfma_f32_16x16x32_bf16 v[158:161], v[218:221], v[184:187], v[158:161]
	s_waitcnt lgkmcnt(3)
	v_mfma_f32_16x16x32_bf16 v[130:133], v[218:221], v[198:201], v[130:133]
	s_waitcnt lgkmcnt(2)
	v_mfma_f32_16x16x32_bf16 v[66:69], v[218:221], v[210:213], v[66:69]
	s_waitcnt lgkmcnt(1)
	v_mfma_f32_16x16x32_bf16 v[34:37], v[218:221], v[214:217], v[34:37]
	s_waitcnt vmcnt(7)
	ds_write_b128 v171, v[94:97]
	v_mfma_f32_16x16x32_bf16 v[154:157], v[222:225], v[184:187], v[154:157]
	v_mfma_f32_16x16x32_bf16 v[122:125], v[222:225], v[198:201], v[122:125]
	global_load_dwordx4 v[94:97], v168, vcc offset:256
	v_mfma_f32_16x16x32_bf16 v[58:61], v[222:225], v[210:213], v[58:61]
	v_mfma_f32_16x16x32_bf16 v[26:29], v[222:225], v[214:217], v[26:29]
	s_waitcnt vmcnt(7)
	ds_write_b128 v171, v[86:89] offset:8192
	v_mfma_f32_16x16x32_bf16 v[150:153], v[226:229], v[184:187], v[150:153]
	v_mfma_f32_16x16x32_bf16 v[114:117], v[226:229], v[198:201], v[114:117]
	v_add_u32_e32 v86, s34, v168
	global_load_dwordx4 v[86:89], v86, vcc offset:256
	v_mfma_f32_16x16x32_bf16 v[54:57], v[226:229], v[210:213], v[54:57]
	v_mfma_f32_16x16x32_bf16 v[22:25], v[226:229], v[214:217], v[22:25]
	s_waitcnt vmcnt(7)
	ds_write_b128 v171, v[90:93] offset:16384
	v_mfma_f32_16x16x32_bf16 v[146:149], v[230:233], v[184:187], v[146:149]
	v_mfma_f32_16x16x32_bf16 v[82:85], v[230:233], v[198:201], v[82:85]
	v_add_u32_e32 v90, s35, v168
	global_load_dwordx4 v[90:93], v90, vcc offset:256
	v_mfma_f32_16x16x32_bf16 v[50:53], v[230:233], v[210:213], v[50:53]
	v_mfma_f32_16x16x32_bf16 v[18:21], v[230:233], v[214:217], v[18:21]
	s_waitcnt vmcnt(7)
	ds_write_b128 v171, v[106:109] offset:24576
	v_mfma_f32_16x16x32_bf16 v[142:145], v[234:237], v[184:187], v[142:145]
	v_mfma_f32_16x16x32_bf16 v[78:81], v[234:237], v[198:201], v[78:81]
	v_add_u32_e32 v106, s36, v168
	global_load_dwordx4 v[106:109], v106, vcc offset:256
	v_mfma_f32_16x16x32_bf16 v[46:49], v[234:237], v[210:213], v[46:49]
	v_mfma_f32_16x16x32_bf16 v[14:17], v[234:237], v[214:217], v[14:17]
	s_waitcnt vmcnt(7)
	ds_write_b128 v171, v[102:105] offset:32768
	v_mfma_f32_16x16x32_bf16 v[138:141], v[238:241], v[184:187], v[138:141]
	v_mfma_f32_16x16x32_bf16 v[74:77], v[238:241], v[198:201], v[74:77]
	global_load_dwordx4 v[102:105], v170, s[100:101] offset:256
	v_mfma_f32_16x16x32_bf16 v[42:45], v[238:241], v[210:213], v[42:45]
	v_mfma_f32_16x16x32_bf16 v[10:13], v[238:241], v[214:217], v[10:13]
	s_waitcnt vmcnt(7)
	ds_write_b128 v171, v[98:101] offset:40960
	v_mfma_f32_16x16x32_bf16 v[134:137], v[242:245], v[184:187], v[134:137]
	v_mfma_f32_16x16x32_bf16 v[70:73], v[242:245], v[198:201], v[70:73]
	v_add_u32_e32 v98, s34, v170
	global_load_dwordx4 v[98:101], v98, s[100:101] offset:256
	v_mfma_f32_16x16x32_bf16 v[38:41], v[242:245], v[210:213], v[38:41]
	v_mfma_f32_16x16x32_bf16 v[6:9], v[242:245], v[214:217], v[6:9]
	s_waitcnt vmcnt(7)
	ds_write_b128 v171, v[118:121] offset:49152
	s_waitcnt lgkmcnt(7)
	v_mfma_f32_16x16x32_bf16 v[126:129], v[246:249], v[184:187], v[126:129]
	v_mfma_f32_16x16x32_bf16 v[62:65], v[246:249], v[198:201], v[62:65]
	v_add_u32_e32 v118, s35, v170
	global_load_dwordx4 v[118:121], v118, s[100:101] offset:256
	v_mfma_f32_16x16x32_bf16 v[30:33], v[246:249], v[210:213], v[30:33]
	v_mfma_f32_16x16x32_bf16 v[2:5], v[246:249], v[214:217], v[2:5]
	s_waitcnt vmcnt(7)
	ds_write_b128 v171, v[110:113] offset:57344
	v_add_u32_e32 v110, s36, v170
	global_load_dwordx4 v[110:113], v110, s[100:101] offset:256
	v_add_u32_e32 v168, 0x80, v168
	v_add_u32_e32 v170, 0x80, v170
	s_waitcnt lgkmcnt(0)
	s_barrier
	s_cmp_eq_u32 s14, 16
	s_mov_b32 s4, s14
	s_cbranch_scc0 .LBB0_665
	s_branch .Lkdone_665
.Lg1_665:
	v_add_u32_e32 v171, 0x12000, v166
	s_waitcnt vmcnt(7)
	ds_write_b128 v171, v[94:97]
	global_load_dwordx4 v[94:97], v168, vcc offset:256
	s_waitcnt vmcnt(7)
	ds_write_b128 v171, v[86:89] offset:8192
	v_add_u32_e32 v86, s34, v168
	global_load_dwordx4 v[86:89], v86, vcc offset:256
	s_waitcnt vmcnt(7)
	ds_write_b128 v171, v[90:93] offset:16384
	v_add_u32_e32 v90, s35, v168
	global_load_dwordx4 v[90:93], v90, vcc offset:256
	s_waitcnt vmcnt(7)
	ds_write_b128 v171, v[106:109] offset:24576
	v_add_u32_e32 v106, s36, v168
	global_load_dwordx4 v[106:109], v106, vcc offset:256
	s_waitcnt vmcnt(7)
	ds_write_b128 v171, v[102:105] offset:32768
	global_load_dwordx4 v[102:105], v170, s[100:101] offset:256
	s_waitcnt vmcnt(7)
	ds_write_b128 v171, v[98:101] offset:40960
	v_add_u32_e32 v98, s34, v170
	global_load_dwordx4 v[98:101], v98, s[100:101] offset:256
	s_waitcnt vmcnt(7)
	ds_write_b128 v171, v[118:121] offset:49152
	v_add_u32_e32 v118, s35, v170
	global_load_dwordx4 v[118:121], v118, s[100:101] offset:256
	s_waitcnt vmcnt(7)
	ds_write_b128 v171, v[110:113] offset:57344
	v_add_u32_e32 v110, s36, v170
	global_load_dwordx4 v[110:113], v110, s[100:101] offset:256
	v_add_u32_e32 v168, 0x80, v168
	v_add_u32_e32 v170, 0x80, v170
.Lg1loop_665:
	s_bitcmp1_b32 s4, 0
	s_cselect_b32 s15, 0x12000, 0
	v_or_b32_e32 v208, s15, v206
	v_add_u32_e32 v214, v208, v0
	v_add_u32_e32 v208, v208, v167
	ds_read_b128 v[184:187], v214
	ds_read_b128 v[218:221], v208 offset:32768
	ds_read_b128 v[198:201], v214 offset:2048
	ds_read_b128 v[210:213], v214 offset:4096
	ds_read_b128 v[214:217], v214 offset:6144
	ds_read_b128 v[222:225], v208 offset:34816
	ds_read_b128 v[226:229], v208 offset:36864
	ds_read_b128 v[230:233], v208 offset:38912
	ds_read_b128 v[234:237], v208 offset:40960
	ds_read_b128 v[238:241], v208 offset:43008
	ds_read_b128 v[242:245], v208 offset:45056
	ds_read_b128 v[246:249], v208 offset:47104
	s_add_i32 s14, s4, 1
	s_bitcmp1_b32 s14, 0
	s_cselect_b32 s16, 0x12000, 0
	v_add_u32_e32 v208, s16, v166
	v_add_u32_e32 v171, s15, v166
	v_xor_b32_e32 v169, 64, v206
	v_add3_u32 v169, s15, v167, v169
	s_waitcnt lgkmcnt(10)
	v_mfma_f32_16x16x32_bf16 v[158:161], v[218:221], v[184:187], v[158:161]
	s_waitcnt lgkmcnt(9)
	v_mfma_f32_16x16x32_bf16 v[130:133], v[218:221], v[198:201], v[130:133]
	s_waitcnt lgkmcnt(8)
	v_mfma_f32_16x16x32_bf16 v[66:69], v[218:221], v[210:213], v[66:69]
	s_waitcnt lgkmcnt(7)
	v_mfma_f32_16x16x32_bf16 v[34:37], v[218:221], v[214:217], v[34:37]
	ds_read_b128 v[218:221], v169 offset:32768
	s_waitcnt lgkmcnt(7)
	v_mfma_f32_16x16x32_bf16 v[154:157], v[222:225], v[184:187], v[154:157]
	v_mfma_f32_16x16x32_bf16 v[122:125], v[222:225], v[198:201], v[122:125]
	v_mfma_f32_16x16x32_bf16 v[58:61], v[222:225], v[210:213], v[58:61]
	v_mfma_f32_16x16x32_bf16 v[26:29], v[222:225], v[214:217], v[26:29]
	ds_read_b128 v[222:225], v169 offset:34816
	s_waitcnt lgkmcnt(7)
	v_mfma_f32_16x16x32_bf16 v[150:153], v[226:229], v[184:187], v[150:153]
	v_mfma_f32_16x16x32_bf16 v[114:117], v[226:229], v[198:201], v[114:117]
	v_mfma_f32_16x16x32_bf16 v[54:57], v[226:229], v[210:213], v[54:57]
	v_mfma_f32_16x16x32_bf16 v[22:25], v[226:229], v[214:217], v[22:25]
	ds_read_b128 v[226:229], v169 offset:36864
	s_waitcnt lgkmcnt(7)
	v_mfma_f32_16x16x32_bf16 v[146:149], v[230:233], v[184:187], v[146:149]
	v_mfma_f32_16x16x32_bf16 v[82:85], v[230:233], v[198:201], v[82:85]
	v_mfma_f32_16x16x32_bf16 v[50:53], v[230:233], v[210:213], v[50:53]
	v_mfma_f32_16x16x32_bf16 v[18:21], v[230:233], v[214:217], v[18:21]
	ds_read_b128 v[230:233], v169 offset:38912
	s_waitcnt lgkmcnt(7)
	v_mfma_f32_16x16x32_bf16 v[142:145], v[234:237], v[184:187], v[142:145]
	v_mfma_f32_16x16x32_bf16 v[78:81], v[234:237], v[198:201], v[78:81]
	v_mfma_f32_16x16x32_bf16 v[46:49], v[234:237], v[210:213], v[46:49]
	v_mfma_f32_16x16x32_bf16 v[14:17], v[234:237], v[214:217], v[14:17]
	ds_read_b128 v[234:237], v169 offset:40960
	s_waitcnt lgkmcnt(7)
	v_mfma_f32_16x16x32_bf16 v[138:141], v[238:241], v[184:187], v[138:141]
	v_mfma_f32_16x16x32_bf16 v[74:77], v[238:241], v[198:201], v[74:77]
	v_mfma_f32_16x16x32_bf16 v[42:45], v[238:241], v[210:213], v[42:45]
	v_mfma_f32_16x16x32_bf16 v[10:13], v[238:241], v[214:217], v[10:13]
	ds_read_b128 v[238:241], v169 offset:43008
	s_waitcnt lgkmcnt(7)
	v_mfma_f32_16x16x32_bf16 v[134:137], v[242:245], v[184:187], v[134:137]
	v_mfma_f32_16x16x32_bf16 v[70:73], v[242:245], v[198:201], v[70:73]
	v_mfma_f32_16x16x32_bf16 v[38:41], v[242:245], v[210:213], v[38:41]
	v_mfma_f32_16x16x32_bf16 v[6:9], v[242:245], v[214:217], v[6:9]
	ds_read_b128 v[242:245], v169 offset:45056
	s_waitcnt lgkmcnt(7)
	v_mfma_f32_16x16x32_bf16 v[126:129], v[246:249], v[184:187], v[126:129]
	v_mfma_f32_16x16x32_bf16 v[62:65], v[246:249], v[198:201], v[62:65]
	v_xor_b32_e32 v169, 64, v206
	v_add3_u32 v169, s15, v0, v169
	ds_read_b128 v[184:187], v169
	ds_read_b128 v[198:201], v169 offset:2048
	v_mfma_f32_16x16x32_bf16 v[30:33], v[246:249], v[210:213], v[30:33]
	ds_read_b128 v[210:213], v169 offset:4096
	v_mfma_f32_16x16x32_bf16 v[2:5], v[246:249], v[214:217], v[2:5]
	ds_read_b128 v[214:217], v169 offset:6144
	v_xor_b32_e32 v169, 64, v206
	v_add3_u32 v169, s15, v167, v169
	ds_read_b128 v[246:249], v169 offset:47104
	s_waitcnt lgkmcnt(0)
	s_barrier
	s_waitcnt lgkmcnt(4)
	v_mfma_f32_16x16x32_bf16 v[158:161], v[218:221], v[184:187], v[158:161]
	s_waitcnt lgkmcnt(3)
	v_mfma_f32_16x16x32_bf16 v[130:133], v[218:221], v[198:201], v[130:133]
	s_waitcnt lgkmcnt(2)
	v_mfma_f32_16x16x32_bf16 v[66:69], v[218:221], v[210:213], v[66:69]
	s_waitcnt lgkmcnt(1)
	v_mfma_f32_16x16x32_bf16 v[34:37], v[218:221], v[214:217], v[34:37]
	s_waitcnt vmcnt(7)
	ds_write_b128 v171, v[94:97]
	v_mfma_f32_16x16x32_bf16 v[154:157], v[222:225], v[184:187], v[154:157]
	v_mfma_f32_16x16x32_bf16 v[122:125], v[222:225], v[198:201], v[122:125]
	global_load_dwordx4 v[94:97], v168, vcc offset:256
	v_mfma_f32_16x16x32_bf16 v[58:61], v[222:225], v[210:213], v[58:61]
	v_mfma_f32_16x16x32_bf16 v[26:29], v[222:225], v[214:217], v[26:29]
	s_waitcnt vmcnt(7)
	ds_write_b128 v171, v[86:89] offset:8192
	v_mfma_f32_16x16x32_bf16 v[150:153], v[226:229], v[184:187], v[150:153]
	v_mfma_f32_16x16x32_bf16 v[114:117], v[226:229], v[198:201], v[114:117]
	v_add_u32_e32 v86, s34, v168
	global_load_dwordx4 v[86:89], v86, vcc offset:256
	v_mfma_f32_16x16x32_bf16 v[54:57], v[226:229], v[210:213], v[54:57]
	v_mfma_f32_16x16x32_bf16 v[22:25], v[226:229], v[214:217], v[22:25]
	s_waitcnt vmcnt(7)
	ds_write_b128 v171, v[90:93] offset:16384
	v_mfma_f32_16x16x32_bf16 v[146:149], v[230:233], v[184:187], v[146:149]
	v_mfma_f32_16x16x32_bf16 v[82:85], v[230:233], v[198:201], v[82:85]
	v_add_u32_e32 v90, s35, v168
	global_load_dwordx4 v[90:93], v90, vcc offset:256
	v_mfma_f32_16x16x32_bf16 v[50:53], v[230:233], v[210:213], v[50:53]
	v_mfma_f32_16x16x32_bf16 v[18:21], v[230:233], v[214:217], v[18:21]
	s_waitcnt vmcnt(7)
	ds_write_b128 v171, v[106:109] offset:24576
	v_mfma_f32_16x16x32_bf16 v[142:145], v[234:237], v[184:187], v[142:145]
	v_mfma_f32_16x16x32_bf16 v[78:81], v[234:237], v[198:201], v[78:81]
	v_add_u32_e32 v106, s36, v168
	global_load_dwordx4 v[106:109], v106, vcc offset:256
	v_mfma_f32_16x16x32_bf16 v[46:49], v[234:237], v[210:213], v[46:49]
	v_mfma_f32_16x16x32_bf16 v[14:17], v[234:237], v[214:217], v[14:17]
	s_waitcnt vmcnt(7)
	ds_write_b128 v171, v[102:105] offset:32768
	v_mfma_f32_16x16x32_bf16 v[138:141], v[238:241], v[184:187], v[138:141]
	v_mfma_f32_16x16x32_bf16 v[74:77], v[238:241], v[198:201], v[74:77]
	global_load_dwordx4 v[102:105], v170, s[100:101] offset:256
	v_mfma_f32_16x16x32_bf16 v[42:45], v[238:241], v[210:213], v[42:45]
	v_mfma_f32_16x16x32_bf16 v[10:13], v[238:241], v[214:217], v[10:13]
	s_waitcnt vmcnt(7)
	ds_write_b128 v171, v[98:101] offset:40960
	v_mfma_f32_16x16x32_bf16 v[134:137], v[242:245], v[184:187], v[134:137]
	v_mfma_f32_16x16x32_bf16 v[70:73], v[242:245], v[198:201], v[70:73]
	v_add_u32_e32 v98, s34, v170
	global_load_dwordx4 v[98:101], v98, s[100:101] offset:256
	v_mfma_f32_16x16x32_bf16 v[38:41], v[242:245], v[210:213], v[38:41]
	v_mfma_f32_16x16x32_bf16 v[6:9], v[242:245], v[214:217], v[6:9]
	s_waitcnt vmcnt(7)
	ds_write_b128 v171, v[118:121] offset:49152
	s_waitcnt lgkmcnt(7)
	v_mfma_f32_16x16x32_bf16 v[126:129], v[246:249], v[184:187], v[126:129]
	v_mfma_f32_16x16x32_bf16 v[62:65], v[246:249], v[198:201], v[62:65]
	v_add_u32_e32 v118, s35, v170
	global_load_dwordx4 v[118:121], v118, s[100:101] offset:256
	v_mfma_f32_16x16x32_bf16 v[30:33], v[246:249], v[210:213], v[30:33]
	v_mfma_f32_16x16x32_bf16 v[2:5], v[246:249], v[214:217], v[2:5]
	s_waitcnt vmcnt(7)
	ds_write_b128 v171, v[110:113] offset:57344
	v_add_u32_e32 v110, s36, v170
	global_load_dwordx4 v[110:113], v110, s[100:101] offset:256
	v_add_u32_e32 v168, 0x80, v168
	v_add_u32_e32 v170, 0x80, v170
	s_cmp_eq_u32 s14, 16
	s_mov_b32 s4, s14
	s_cbranch_scc0 .Lg1loop_665
	s_waitcnt lgkmcnt(0)
.Lkdone_665:
	s_waitcnt vmcnt(3)
	v_and_b32_sdwa v93, v158, v177 dst_sel:DWORD dst_unused:UNUSED_PAD src0_sel:WORD_1 src1_sel:DWORD
	v_or_b32_e32 v88, s7, v207
	v_add3_u32 v95, v158, v93, s28
	v_and_b32_sdwa v93, v161, v177 dst_sel:DWORD dst_unused:UNUSED_PAD src0_sel:WORD_1 src1_sel:DWORD
	v_and_b32_sdwa v96, v159, v177 dst_sel:DWORD dst_unused:UNUSED_PAD src0_sel:WORD_1 src1_sel:DWORD
	v_add_u32_e32 v94, s6, v205
	v_mov_b64_e32 v[86:87], s[12:13]
	v_ashrrev_i32_e32 v89, 31, v88
	v_and_b32_sdwa v92, v160, v177 dst_sel:DWORD dst_unused:UNUSED_PAD src0_sel:WORD_1 src1_sel:DWORD
	v_add3_u32 v93, v161, v93, s28
	v_add3_u32 v96, v159, v96, s28
	v_mad_i64_i32 v[90:91], s[6:7], v94, s8, v[86:87]
	v_lshlrev_b64 v[88:89], 1, v[88:89]
	v_add3_u32 v92, v160, v92, s28
	v_and_b32_e32 v93, 0xffff0000, v93
	v_and_b32_e32 v96, 0xffff0000, v96
	v_lshl_add_u64 v[90:91], v[90:91], 0, v[88:89]
	v_or_b32_sdwa v93, v93, v92 dst_sel:DWORD dst_unused:UNUSED_PAD src0_sel:DWORD src1_sel:WORD_1
	v_or_b32_sdwa v92, v96, v95 dst_sel:DWORD dst_unused:UNUSED_PAD src0_sel:DWORD src1_sel:WORD_1
	s_waitcnt vmcnt(0)
	global_store_dwordx2 v[90:91], v[92:93], off
	v_and_b32_sdwa v93, v154, v177 dst_sel:DWORD dst_unused:UNUSED_PAD src0_sel:WORD_1 src1_sel:DWORD
	v_add3_u32 v95, v154, v93, s28
	v_and_b32_sdwa v93, v157, v177 dst_sel:DWORD dst_unused:UNUSED_PAD src0_sel:WORD_1 src1_sel:DWORD
	v_and_b32_sdwa v96, v155, v177 dst_sel:DWORD dst_unused:UNUSED_PAD src0_sel:WORD_1 src1_sel:DWORD
	v_and_b32_sdwa v92, v156, v177 dst_sel:DWORD dst_unused:UNUSED_PAD src0_sel:WORD_1 src1_sel:DWORD
	v_add3_u32 v93, v157, v93, s28
	v_add3_u32 v96, v155, v96, s28
	v_add3_u32 v92, v156, v92, s28
	v_and_b32_e32 v93, 0xffff0000, v93
	v_and_b32_e32 v96, 0xffff0000, v96
	v_or_b32_sdwa v93, v93, v92 dst_sel:DWORD dst_unused:UNUSED_PAD src0_sel:DWORD src1_sel:WORD_1
	v_or_b32_sdwa v92, v96, v95 dst_sel:DWORD dst_unused:UNUSED_PAD src0_sel:DWORD src1_sel:WORD_1
	global_store_dwordx2 v[90:91], v[92:93], off offset:32
	v_and_b32_sdwa v93, v150, v177 dst_sel:DWORD dst_unused:UNUSED_PAD src0_sel:WORD_1 src1_sel:DWORD
	v_add3_u32 v95, v150, v93, s28
	v_and_b32_sdwa v93, v153, v177 dst_sel:DWORD dst_unused:UNUSED_PAD src0_sel:WORD_1 src1_sel:DWORD
	v_and_b32_sdwa v96, v151, v177 dst_sel:DWORD dst_unused:UNUSED_PAD src0_sel:WORD_1 src1_sel:DWORD
	v_and_b32_sdwa v92, v152, v177 dst_sel:DWORD dst_unused:UNUSED_PAD src0_sel:WORD_1 src1_sel:DWORD
	v_add3_u32 v93, v153, v93, s28
	v_add3_u32 v96, v151, v96, s28
	v_add3_u32 v92, v152, v92, s28
	v_and_b32_e32 v93, 0xffff0000, v93
	v_and_b32_e32 v96, 0xffff0000, v96
	v_or_b32_sdwa v93, v93, v92 dst_sel:DWORD dst_unused:UNUSED_PAD src0_sel:DWORD src1_sel:WORD_1
	v_or_b32_sdwa v92, v96, v95 dst_sel:DWORD dst_unused:UNUSED_PAD src0_sel:DWORD src1_sel:WORD_1
	global_store_dwordx2 v[90:91], v[92:93], off offset:64
	v_and_b32_sdwa v93, v146, v177 dst_sel:DWORD dst_unused:UNUSED_PAD src0_sel:WORD_1 src1_sel:DWORD
	v_add3_u32 v95, v146, v93, s28
	v_and_b32_sdwa v93, v149, v177 dst_sel:DWORD dst_unused:UNUSED_PAD src0_sel:WORD_1 src1_sel:DWORD
	v_and_b32_sdwa v96, v147, v177 dst_sel:DWORD dst_unused:UNUSED_PAD src0_sel:WORD_1 src1_sel:DWORD
	v_and_b32_sdwa v92, v148, v177 dst_sel:DWORD dst_unused:UNUSED_PAD src0_sel:WORD_1 src1_sel:DWORD
	v_add3_u32 v93, v149, v93, s28
	v_add3_u32 v96, v147, v96, s28
	v_add3_u32 v92, v148, v92, s28
	v_and_b32_e32 v93, 0xffff0000, v93
	v_and_b32_e32 v96, 0xffff0000, v96
	v_or_b32_sdwa v93, v93, v92 dst_sel:DWORD dst_unused:UNUSED_PAD src0_sel:DWORD src1_sel:WORD_1
	v_or_b32_sdwa v92, v96, v95 dst_sel:DWORD dst_unused:UNUSED_PAD src0_sel:DWORD src1_sel:WORD_1
	global_store_dwordx2 v[90:91], v[92:93], off offset:96
	v_and_b32_sdwa v93, v142, v177 dst_sel:DWORD dst_unused:UNUSED_PAD src0_sel:WORD_1 src1_sel:DWORD
	v_add3_u32 v95, v142, v93, s28
	v_and_b32_sdwa v93, v145, v177 dst_sel:DWORD dst_unused:UNUSED_PAD src0_sel:WORD_1 src1_sel:DWORD
	v_and_b32_sdwa v96, v143, v177 dst_sel:DWORD dst_unused:UNUSED_PAD src0_sel:WORD_1 src1_sel:DWORD
	v_and_b32_sdwa v92, v144, v177 dst_sel:DWORD dst_unused:UNUSED_PAD src0_sel:WORD_1 src1_sel:DWORD
	v_add3_u32 v93, v145, v93, s28
	v_add3_u32 v96, v143, v96, s28
	v_add3_u32 v92, v144, v92, s28
	v_and_b32_e32 v93, 0xffff0000, v93
	v_and_b32_e32 v96, 0xffff0000, v96
	v_or_b32_sdwa v93, v93, v92 dst_sel:DWORD dst_unused:UNUSED_PAD src0_sel:DWORD src1_sel:WORD_1
	v_or_b32_sdwa v92, v96, v95 dst_sel:DWORD dst_unused:UNUSED_PAD src0_sel:DWORD src1_sel:WORD_1
	global_store_dwordx2 v[90:91], v[92:93], off offset:128
	v_and_b32_sdwa v93, v138, v177 dst_sel:DWORD dst_unused:UNUSED_PAD src0_sel:WORD_1 src1_sel:DWORD
	v_add3_u32 v95, v138, v93, s28
	v_and_b32_sdwa v93, v141, v177 dst_sel:DWORD dst_unused:UNUSED_PAD src0_sel:WORD_1 src1_sel:DWORD
	v_and_b32_sdwa v96, v139, v177 dst_sel:DWORD dst_unused:UNUSED_PAD src0_sel:WORD_1 src1_sel:DWORD
	v_and_b32_sdwa v92, v140, v177 dst_sel:DWORD dst_unused:UNUSED_PAD src0_sel:WORD_1 src1_sel:DWORD
	v_add3_u32 v93, v141, v93, s28
	v_add3_u32 v96, v139, v96, s28
	v_add3_u32 v92, v140, v92, s28
	v_and_b32_e32 v93, 0xffff0000, v93
	v_and_b32_e32 v96, 0xffff0000, v96
	v_or_b32_sdwa v93, v93, v92 dst_sel:DWORD dst_unused:UNUSED_PAD src0_sel:DWORD src1_sel:WORD_1
	v_or_b32_sdwa v92, v96, v95 dst_sel:DWORD dst_unused:UNUSED_PAD src0_sel:DWORD src1_sel:WORD_1
	global_store_dwordx2 v[90:91], v[92:93], off offset:160
	v_and_b32_sdwa v93, v134, v177 dst_sel:DWORD dst_unused:UNUSED_PAD src0_sel:WORD_1 src1_sel:DWORD
	v_add3_u32 v95, v134, v93, s28
	v_and_b32_sdwa v93, v137, v177 dst_sel:DWORD dst_unused:UNUSED_PAD src0_sel:WORD_1 src1_sel:DWORD
	v_and_b32_sdwa v96, v135, v177 dst_sel:DWORD dst_unused:UNUSED_PAD src0_sel:WORD_1 src1_sel:DWORD
	v_and_b32_sdwa v92, v136, v177 dst_sel:DWORD dst_unused:UNUSED_PAD src0_sel:WORD_1 src1_sel:DWORD
	v_add3_u32 v93, v137, v93, s28
	v_add3_u32 v96, v135, v96, s28
	v_add3_u32 v92, v136, v92, s28
	v_and_b32_e32 v93, 0xffff0000, v93
	v_and_b32_e32 v96, 0xffff0000, v96
	v_or_b32_sdwa v93, v93, v92 dst_sel:DWORD dst_unused:UNUSED_PAD src0_sel:DWORD src1_sel:WORD_1
	v_or_b32_sdwa v92, v96, v95 dst_sel:DWORD dst_unused:UNUSED_PAD src0_sel:DWORD src1_sel:WORD_1
	global_store_dwordx2 v[90:91], v[92:93], off offset:192
	v_and_b32_sdwa v93, v126, v177 dst_sel:DWORD dst_unused:UNUSED_PAD src0_sel:WORD_1 src1_sel:DWORD
	v_add3_u32 v95, v126, v93, s28
	v_and_b32_sdwa v93, v129, v177 dst_sel:DWORD dst_unused:UNUSED_PAD src0_sel:WORD_1 src1_sel:DWORD
	v_and_b32_sdwa v96, v127, v177 dst_sel:DWORD dst_unused:UNUSED_PAD src0_sel:WORD_1 src1_sel:DWORD
	v_and_b32_sdwa v92, v128, v177 dst_sel:DWORD dst_unused:UNUSED_PAD src0_sel:WORD_1 src1_sel:DWORD
	v_add3_u32 v93, v129, v93, s28
	v_add3_u32 v96, v127, v96, s28
	v_add3_u32 v92, v128, v92, s28
	v_and_b32_e32 v93, 0xffff0000, v93
	v_and_b32_e32 v96, 0xffff0000, v96
	v_or_b32_sdwa v93, v93, v92 dst_sel:DWORD dst_unused:UNUSED_PAD src0_sel:DWORD src1_sel:WORD_1
	v_or_b32_sdwa v92, v96, v95 dst_sel:DWORD dst_unused:UNUSED_PAD src0_sel:DWORD src1_sel:WORD_1
	global_store_dwordx2 v[90:91], v[92:93], off offset:224
	v_and_b32_sdwa v93, v130, v177 dst_sel:DWORD dst_unused:UNUSED_PAD src0_sel:WORD_1 src1_sel:DWORD
	v_add3_u32 v95, v130, v93, s28
	v_and_b32_sdwa v93, v133, v177 dst_sel:DWORD dst_unused:UNUSED_PAD src0_sel:WORD_1 src1_sel:DWORD
	v_and_b32_sdwa v96, v131, v177 dst_sel:DWORD dst_unused:UNUSED_PAD src0_sel:WORD_1 src1_sel:DWORD
	v_or_b32_e32 v90, 16, v94
	v_and_b32_sdwa v92, v132, v177 dst_sel:DWORD dst_unused:UNUSED_PAD src0_sel:WORD_1 src1_sel:DWORD
	v_add3_u32 v93, v133, v93, s28
	v_add3_u32 v96, v131, v96, s28
	v_mad_i64_i32 v[90:91], s[6:7], v90, s8, v[86:87]
	v_add3_u32 v92, v132, v92, s28
	v_and_b32_e32 v93, 0xffff0000, v93
	v_and_b32_e32 v96, 0xffff0000, v96
	v_lshl_add_u64 v[90:91], v[90:91], 0, v[88:89]
	v_or_b32_sdwa v93, v93, v92 dst_sel:DWORD dst_unused:UNUSED_PAD src0_sel:DWORD src1_sel:WORD_1
	v_or_b32_sdwa v92, v96, v95 dst_sel:DWORD dst_unused:UNUSED_PAD src0_sel:DWORD src1_sel:WORD_1
	global_store_dwordx2 v[90:91], v[92:93], off
	v_and_b32_sdwa v93, v122, v177 dst_sel:DWORD dst_unused:UNUSED_PAD src0_sel:WORD_1 src1_sel:DWORD
	v_add3_u32 v95, v122, v93, s28
	v_and_b32_sdwa v93, v125, v177 dst_sel:DWORD dst_unused:UNUSED_PAD src0_sel:WORD_1 src1_sel:DWORD
	v_and_b32_sdwa v96, v123, v177 dst_sel:DWORD dst_unused:UNUSED_PAD src0_sel:WORD_1 src1_sel:DWORD
	v_and_b32_sdwa v92, v124, v177 dst_sel:DWORD dst_unused:UNUSED_PAD src0_sel:WORD_1 src1_sel:DWORD
	v_add3_u32 v93, v125, v93, s28
	v_add3_u32 v96, v123, v96, s28
	v_add3_u32 v92, v124, v92, s28
	v_and_b32_e32 v93, 0xffff0000, v93
	v_and_b32_e32 v96, 0xffff0000, v96
	v_or_b32_sdwa v93, v93, v92 dst_sel:DWORD dst_unused:UNUSED_PAD src0_sel:DWORD src1_sel:WORD_1
	v_or_b32_sdwa v92, v96, v95 dst_sel:DWORD dst_unused:UNUSED_PAD src0_sel:DWORD src1_sel:WORD_1
	global_store_dwordx2 v[90:91], v[92:93], off offset:32
	v_and_b32_sdwa v93, v114, v177 dst_sel:DWORD dst_unused:UNUSED_PAD src0_sel:WORD_1 src1_sel:DWORD
	v_add3_u32 v95, v114, v93, s28
	v_and_b32_sdwa v93, v117, v177 dst_sel:DWORD dst_unused:UNUSED_PAD src0_sel:WORD_1 src1_sel:DWORD
	v_and_b32_sdwa v96, v115, v177 dst_sel:DWORD dst_unused:UNUSED_PAD src0_sel:WORD_1 src1_sel:DWORD
	v_and_b32_sdwa v92, v116, v177 dst_sel:DWORD dst_unused:UNUSED_PAD src0_sel:WORD_1 src1_sel:DWORD
	v_add3_u32 v93, v117, v93, s28
	v_add3_u32 v96, v115, v96, s28
	v_add3_u32 v92, v116, v92, s28
	v_and_b32_e32 v93, 0xffff0000, v93
	v_and_b32_e32 v96, 0xffff0000, v96
	v_or_b32_sdwa v93, v93, v92 dst_sel:DWORD dst_unused:UNUSED_PAD src0_sel:DWORD src1_sel:WORD_1
	v_or_b32_sdwa v92, v96, v95 dst_sel:DWORD dst_unused:UNUSED_PAD src0_sel:DWORD src1_sel:WORD_1
	global_store_dwordx2 v[90:91], v[92:93], off offset:64
	v_and_b32_sdwa v92, v84, v177 dst_sel:DWORD dst_unused:UNUSED_PAD src0_sel:WORD_1 src1_sel:DWORD
	v_and_b32_sdwa v93, v82, v177 dst_sel:DWORD dst_unused:UNUSED_PAD src0_sel:WORD_1 src1_sel:DWORD
	v_add3_u32 v82, v82, v93, s28
	v_add3_u32 v84, v84, v92, s28
	v_and_b32_sdwa v92, v85, v177 dst_sel:DWORD dst_unused:UNUSED_PAD src0_sel:WORD_1 src1_sel:DWORD
	v_and_b32_sdwa v93, v83, v177 dst_sel:DWORD dst_unused:UNUSED_PAD src0_sel:WORD_1 src1_sel:DWORD
	v_add3_u32 v85, v85, v92, s28
	v_add3_u32 v83, v83, v93, s28
	v_and_b32_e32 v85, 0xffff0000, v85
	v_and_b32_e32 v92, 0xffff0000, v83
	v_or_b32_sdwa v83, v85, v84 dst_sel:DWORD dst_unused:UNUSED_PAD src0_sel:DWORD src1_sel:WORD_1
	v_or_b32_sdwa v82, v92, v82 dst_sel:DWORD dst_unused:UNUSED_PAD src0_sel:DWORD src1_sel:WORD_1
	global_store_dwordx2 v[90:91], v[82:83], off offset:96
	v_and_b32_sdwa v82, v80, v177 dst_sel:DWORD dst_unused:UNUSED_PAD src0_sel:WORD_1 src1_sel:DWORD
	v_and_b32_sdwa v83, v78, v177 dst_sel:DWORD dst_unused:UNUSED_PAD src0_sel:WORD_1 src1_sel:DWORD
	v_add3_u32 v78, v78, v83, s28
	v_add3_u32 v80, v80, v82, s28
	v_and_b32_sdwa v82, v81, v177 dst_sel:DWORD dst_unused:UNUSED_PAD src0_sel:WORD_1 src1_sel:DWORD
	v_and_b32_sdwa v83, v79, v177 dst_sel:DWORD dst_unused:UNUSED_PAD src0_sel:WORD_1 src1_sel:DWORD
	v_add3_u32 v81, v81, v82, s28
	v_add3_u32 v79, v79, v83, s28
	v_and_b32_e32 v81, 0xffff0000, v81
	v_and_b32_e32 v82, 0xffff0000, v79
	v_or_b32_sdwa v79, v81, v80 dst_sel:DWORD dst_unused:UNUSED_PAD src0_sel:DWORD src1_sel:WORD_1
	v_or_b32_sdwa v78, v82, v78 dst_sel:DWORD dst_unused:UNUSED_PAD src0_sel:DWORD src1_sel:WORD_1
	global_store_dwordx2 v[90:91], v[78:79], off offset:128
	v_and_b32_sdwa v78, v76, v177 dst_sel:DWORD dst_unused:UNUSED_PAD src0_sel:WORD_1 src1_sel:DWORD
	v_and_b32_sdwa v79, v74, v177 dst_sel:DWORD dst_unused:UNUSED_PAD src0_sel:WORD_1 src1_sel:DWORD
	v_add3_u32 v74, v74, v79, s28
	v_add3_u32 v76, v76, v78, s28
	v_and_b32_sdwa v78, v77, v177 dst_sel:DWORD dst_unused:UNUSED_PAD src0_sel:WORD_1 src1_sel:DWORD
	v_and_b32_sdwa v79, v75, v177 dst_sel:DWORD dst_unused:UNUSED_PAD src0_sel:WORD_1 src1_sel:DWORD
	v_add3_u32 v77, v77, v78, s28
	v_add3_u32 v75, v75, v79, s28
	v_and_b32_e32 v77, 0xffff0000, v77
	v_and_b32_e32 v78, 0xffff0000, v75
	v_or_b32_sdwa v75, v77, v76 dst_sel:DWORD dst_unused:UNUSED_PAD src0_sel:DWORD src1_sel:WORD_1
	v_or_b32_sdwa v74, v78, v74 dst_sel:DWORD dst_unused:UNUSED_PAD src0_sel:DWORD src1_sel:WORD_1
	global_store_dwordx2 v[90:91], v[74:75], off offset:160
	v_and_b32_sdwa v74, v72, v177 dst_sel:DWORD dst_unused:UNUSED_PAD src0_sel:WORD_1 src1_sel:DWORD
	v_and_b32_sdwa v75, v70, v177 dst_sel:DWORD dst_unused:UNUSED_PAD src0_sel:WORD_1 src1_sel:DWORD
	v_add3_u32 v70, v70, v75, s28
	v_add3_u32 v72, v72, v74, s28
	v_and_b32_sdwa v74, v73, v177 dst_sel:DWORD dst_unused:UNUSED_PAD src0_sel:WORD_1 src1_sel:DWORD
	v_and_b32_sdwa v75, v71, v177 dst_sel:DWORD dst_unused:UNUSED_PAD src0_sel:WORD_1 src1_sel:DWORD
	v_add3_u32 v73, v73, v74, s28
	v_add3_u32 v71, v71, v75, s28
	v_and_b32_e32 v73, 0xffff0000, v73
	v_and_b32_e32 v74, 0xffff0000, v71
	v_or_b32_sdwa v71, v73, v72 dst_sel:DWORD dst_unused:UNUSED_PAD src0_sel:DWORD src1_sel:WORD_1
	v_or_b32_sdwa v70, v74, v70 dst_sel:DWORD dst_unused:UNUSED_PAD src0_sel:DWORD src1_sel:WORD_1
	global_store_dwordx2 v[90:91], v[70:71], off offset:192
	v_and_b32_sdwa v70, v64, v177 dst_sel:DWORD dst_unused:UNUSED_PAD src0_sel:WORD_1 src1_sel:DWORD
	v_and_b32_sdwa v71, v62, v177 dst_sel:DWORD dst_unused:UNUSED_PAD src0_sel:WORD_1 src1_sel:DWORD
	v_add3_u32 v64, v64, v70, s28
	v_and_b32_sdwa v70, v65, v177 dst_sel:DWORD dst_unused:UNUSED_PAD src0_sel:WORD_1 src1_sel:DWORD
	v_add3_u32 v62, v62, v71, s28
	v_and_b32_sdwa v71, v63, v177 dst_sel:DWORD dst_unused:UNUSED_PAD src0_sel:WORD_1 src1_sel:DWORD
	v_add3_u32 v65, v65, v70, s28
	v_add3_u32 v63, v63, v71, s28
	v_and_b32_e32 v65, 0xffff0000, v65
	v_and_b32_e32 v70, 0xffff0000, v63
	v_or_b32_sdwa v63, v65, v64 dst_sel:DWORD dst_unused:UNUSED_PAD src0_sel:DWORD src1_sel:WORD_1
	v_and_b32_sdwa v64, v68, v177 dst_sel:DWORD dst_unused:UNUSED_PAD src0_sel:WORD_1 src1_sel:DWORD
	v_and_b32_sdwa v65, v66, v177 dst_sel:DWORD dst_unused:UNUSED_PAD src0_sel:WORD_1 src1_sel:DWORD
	v_or_b32_sdwa v62, v70, v62 dst_sel:DWORD dst_unused:UNUSED_PAD src0_sel:DWORD src1_sel:WORD_1
	v_add3_u32 v66, v66, v65, s28
	v_add3_u32 v64, v68, v64, s28
	v_and_b32_sdwa v65, v69, v177 dst_sel:DWORD dst_unused:UNUSED_PAD src0_sel:WORD_1 src1_sel:DWORD
	v_and_b32_sdwa v68, v67, v177 dst_sel:DWORD dst_unused:UNUSED_PAD src0_sel:WORD_1 src1_sel:DWORD
	global_store_dwordx2 v[90:91], v[62:63], off offset:224
	v_or_b32_e32 v62, 32, v94
	v_add3_u32 v65, v69, v65, s28
	v_add3_u32 v67, v67, v68, s28
	v_mad_i64_i32 v[62:63], s[6:7], v62, s8, v[86:87]
	v_and_b32_e32 v65, 0xffff0000, v65
	v_and_b32_e32 v67, 0xffff0000, v67
	v_lshl_add_u64 v[62:63], v[62:63], 0, v[88:89]
	v_or_b32_sdwa v65, v65, v64 dst_sel:DWORD dst_unused:UNUSED_PAD src0_sel:DWORD src1_sel:WORD_1
	v_or_b32_sdwa v64, v67, v66 dst_sel:DWORD dst_unused:UNUSED_PAD src0_sel:DWORD src1_sel:WORD_1
	global_store_dwordx2 v[62:63], v[64:65], off
	v_and_b32_sdwa v64, v60, v177 dst_sel:DWORD dst_unused:UNUSED_PAD src0_sel:WORD_1 src1_sel:DWORD
	v_and_b32_sdwa v65, v58, v177 dst_sel:DWORD dst_unused:UNUSED_PAD src0_sel:WORD_1 src1_sel:DWORD
	v_add3_u32 v58, v58, v65, s28
	v_add3_u32 v60, v60, v64, s28
	v_and_b32_sdwa v64, v61, v177 dst_sel:DWORD dst_unused:UNUSED_PAD src0_sel:WORD_1 src1_sel:DWORD
	v_and_b32_sdwa v65, v59, v177 dst_sel:DWORD dst_unused:UNUSED_PAD src0_sel:WORD_1 src1_sel:DWORD
	v_add3_u32 v61, v61, v64, s28
	v_add3_u32 v59, v59, v65, s28
	v_and_b32_e32 v61, 0xffff0000, v61
	v_and_b32_e32 v64, 0xffff0000, v59
	v_or_b32_sdwa v59, v61, v60 dst_sel:DWORD dst_unused:UNUSED_PAD src0_sel:DWORD src1_sel:WORD_1
	v_or_b32_sdwa v58, v64, v58 dst_sel:DWORD dst_unused:UNUSED_PAD src0_sel:DWORD src1_sel:WORD_1
	global_store_dwordx2 v[62:63], v[58:59], off offset:32
	v_and_b32_sdwa v58, v56, v177 dst_sel:DWORD dst_unused:UNUSED_PAD src0_sel:WORD_1 src1_sel:DWORD
	v_and_b32_sdwa v59, v54, v177 dst_sel:DWORD dst_unused:UNUSED_PAD src0_sel:WORD_1 src1_sel:DWORD
	v_add3_u32 v54, v54, v59, s28
	v_add3_u32 v56, v56, v58, s28
	v_and_b32_sdwa v58, v57, v177 dst_sel:DWORD dst_unused:UNUSED_PAD src0_sel:WORD_1 src1_sel:DWORD
	v_and_b32_sdwa v59, v55, v177 dst_sel:DWORD dst_unused:UNUSED_PAD src0_sel:WORD_1 src1_sel:DWORD
	v_add3_u32 v57, v57, v58, s28
	v_add3_u32 v55, v55, v59, s28
	v_and_b32_e32 v57, 0xffff0000, v57
	v_and_b32_e32 v58, 0xffff0000, v55
	v_or_b32_sdwa v55, v57, v56 dst_sel:DWORD dst_unused:UNUSED_PAD src0_sel:DWORD src1_sel:WORD_1
	v_or_b32_sdwa v54, v58, v54 dst_sel:DWORD dst_unused:UNUSED_PAD src0_sel:DWORD src1_sel:WORD_1
	global_store_dwordx2 v[62:63], v[54:55], off offset:64
	v_and_b32_sdwa v54, v52, v177 dst_sel:DWORD dst_unused:UNUSED_PAD src0_sel:WORD_1 src1_sel:DWORD
	v_and_b32_sdwa v55, v50, v177 dst_sel:DWORD dst_unused:UNUSED_PAD src0_sel:WORD_1 src1_sel:DWORD
	v_add3_u32 v50, v50, v55, s28
	v_add3_u32 v52, v52, v54, s28
	v_and_b32_sdwa v54, v53, v177 dst_sel:DWORD dst_unused:UNUSED_PAD src0_sel:WORD_1 src1_sel:DWORD
	v_and_b32_sdwa v55, v51, v177 dst_sel:DWORD dst_unused:UNUSED_PAD src0_sel:WORD_1 src1_sel:DWORD
	v_add3_u32 v53, v53, v54, s28
	v_add3_u32 v51, v51, v55, s28
	v_and_b32_e32 v53, 0xffff0000, v53
	v_and_b32_e32 v54, 0xffff0000, v51
	v_or_b32_sdwa v51, v53, v52 dst_sel:DWORD dst_unused:UNUSED_PAD src0_sel:DWORD src1_sel:WORD_1
	v_or_b32_sdwa v50, v54, v50 dst_sel:DWORD dst_unused:UNUSED_PAD src0_sel:DWORD src1_sel:WORD_1
	global_store_dwordx2 v[62:63], v[50:51], off offset:96
	v_and_b32_sdwa v50, v48, v177 dst_sel:DWORD dst_unused:UNUSED_PAD src0_sel:WORD_1 src1_sel:DWORD
	v_and_b32_sdwa v51, v46, v177 dst_sel:DWORD dst_unused:UNUSED_PAD src0_sel:WORD_1 src1_sel:DWORD
	v_add3_u32 v46, v46, v51, s28
	v_add3_u32 v48, v48, v50, s28
	v_and_b32_sdwa v50, v49, v177 dst_sel:DWORD dst_unused:UNUSED_PAD src0_sel:WORD_1 src1_sel:DWORD
	v_and_b32_sdwa v51, v47, v177 dst_sel:DWORD dst_unused:UNUSED_PAD src0_sel:WORD_1 src1_sel:DWORD
	v_add3_u32 v49, v49, v50, s28
	v_add3_u32 v47, v47, v51, s28
	v_and_b32_e32 v49, 0xffff0000, v49
	v_and_b32_e32 v50, 0xffff0000, v47
	v_or_b32_sdwa v47, v49, v48 dst_sel:DWORD dst_unused:UNUSED_PAD src0_sel:DWORD src1_sel:WORD_1
	v_or_b32_sdwa v46, v50, v46 dst_sel:DWORD dst_unused:UNUSED_PAD src0_sel:DWORD src1_sel:WORD_1
	global_store_dwordx2 v[62:63], v[46:47], off offset:128
	v_and_b32_sdwa v46, v44, v177 dst_sel:DWORD dst_unused:UNUSED_PAD src0_sel:WORD_1 src1_sel:DWORD
	v_and_b32_sdwa v47, v42, v177 dst_sel:DWORD dst_unused:UNUSED_PAD src0_sel:WORD_1 src1_sel:DWORD
	v_add3_u32 v42, v42, v47, s28
	v_add3_u32 v44, v44, v46, s28
	v_and_b32_sdwa v46, v45, v177 dst_sel:DWORD dst_unused:UNUSED_PAD src0_sel:WORD_1 src1_sel:DWORD
	v_and_b32_sdwa v47, v43, v177 dst_sel:DWORD dst_unused:UNUSED_PAD src0_sel:WORD_1 src1_sel:DWORD
	v_add3_u32 v45, v45, v46, s28
	v_add3_u32 v43, v43, v47, s28
	v_and_b32_e32 v45, 0xffff0000, v45
	v_and_b32_e32 v46, 0xffff0000, v43
	v_or_b32_sdwa v43, v45, v44 dst_sel:DWORD dst_unused:UNUSED_PAD src0_sel:DWORD src1_sel:WORD_1
	v_or_b32_sdwa v42, v46, v42 dst_sel:DWORD dst_unused:UNUSED_PAD src0_sel:DWORD src1_sel:WORD_1
	global_store_dwordx2 v[62:63], v[42:43], off offset:160
	v_and_b32_sdwa v42, v40, v177 dst_sel:DWORD dst_unused:UNUSED_PAD src0_sel:WORD_1 src1_sel:DWORD
	v_and_b32_sdwa v43, v38, v177 dst_sel:DWORD dst_unused:UNUSED_PAD src0_sel:WORD_1 src1_sel:DWORD
	v_add3_u32 v38, v38, v43, s28
	v_add3_u32 v40, v40, v42, s28
	v_and_b32_sdwa v42, v41, v177 dst_sel:DWORD dst_unused:UNUSED_PAD src0_sel:WORD_1 src1_sel:DWORD
	v_and_b32_sdwa v43, v39, v177 dst_sel:DWORD dst_unused:UNUSED_PAD src0_sel:WORD_1 src1_sel:DWORD
	v_add3_u32 v41, v41, v42, s28
	v_add3_u32 v39, v39, v43, s28
	v_and_b32_e32 v41, 0xffff0000, v41
	v_and_b32_e32 v42, 0xffff0000, v39
	v_or_b32_sdwa v39, v41, v40 dst_sel:DWORD dst_unused:UNUSED_PAD src0_sel:DWORD src1_sel:WORD_1
	v_or_b32_sdwa v38, v42, v38 dst_sel:DWORD dst_unused:UNUSED_PAD src0_sel:DWORD src1_sel:WORD_1
	global_store_dwordx2 v[62:63], v[38:39], off offset:192
	v_and_b32_sdwa v38, v32, v177 dst_sel:DWORD dst_unused:UNUSED_PAD src0_sel:WORD_1 src1_sel:DWORD
	v_and_b32_sdwa v39, v30, v177 dst_sel:DWORD dst_unused:UNUSED_PAD src0_sel:WORD_1 src1_sel:DWORD
	v_add3_u32 v32, v32, v38, s28
	v_and_b32_sdwa v38, v33, v177 dst_sel:DWORD dst_unused:UNUSED_PAD src0_sel:WORD_1 src1_sel:DWORD
	v_add3_u32 v30, v30, v39, s28
	v_and_b32_sdwa v39, v31, v177 dst_sel:DWORD dst_unused:UNUSED_PAD src0_sel:WORD_1 src1_sel:DWORD
	v_add3_u32 v33, v33, v38, s28
	v_add3_u32 v31, v31, v39, s28
	v_and_b32_e32 v33, 0xffff0000, v33
	v_and_b32_e32 v38, 0xffff0000, v31
	v_or_b32_sdwa v31, v33, v32 dst_sel:DWORD dst_unused:UNUSED_PAD src0_sel:DWORD src1_sel:WORD_1
	v_and_b32_sdwa v32, v36, v177 dst_sel:DWORD dst_unused:UNUSED_PAD src0_sel:WORD_1 src1_sel:DWORD
	v_and_b32_sdwa v33, v34, v177 dst_sel:DWORD dst_unused:UNUSED_PAD src0_sel:WORD_1 src1_sel:DWORD
	v_or_b32_sdwa v30, v38, v30 dst_sel:DWORD dst_unused:UNUSED_PAD src0_sel:DWORD src1_sel:WORD_1
	v_add3_u32 v34, v34, v33, s28
	v_add3_u32 v32, v36, v32, s28
	v_and_b32_sdwa v33, v37, v177 dst_sel:DWORD dst_unused:UNUSED_PAD src0_sel:WORD_1 src1_sel:DWORD
	v_and_b32_sdwa v36, v35, v177 dst_sel:DWORD dst_unused:UNUSED_PAD src0_sel:WORD_1 src1_sel:DWORD
	global_store_dwordx2 v[62:63], v[30:31], off offset:224
	v_or_b32_e32 v30, 48, v94
	v_add3_u32 v33, v37, v33, s28
	v_add3_u32 v35, v35, v36, s28
	v_mad_i64_i32 v[30:31], s[6:7], v30, s8, v[86:87]
	v_and_b32_e32 v33, 0xffff0000, v33
	v_and_b32_e32 v35, 0xffff0000, v35
	v_lshl_add_u64 v[30:31], v[30:31], 0, v[88:89]
	v_or_b32_sdwa v33, v33, v32 dst_sel:DWORD dst_unused:UNUSED_PAD src0_sel:DWORD src1_sel:WORD_1
	v_or_b32_sdwa v32, v35, v34 dst_sel:DWORD dst_unused:UNUSED_PAD src0_sel:DWORD src1_sel:WORD_1
	global_store_dwordx2 v[30:31], v[32:33], off
	v_and_b32_sdwa v32, v28, v177 dst_sel:DWORD dst_unused:UNUSED_PAD src0_sel:WORD_1 src1_sel:DWORD
	v_and_b32_sdwa v33, v26, v177 dst_sel:DWORD dst_unused:UNUSED_PAD src0_sel:WORD_1 src1_sel:DWORD
	v_add3_u32 v26, v26, v33, s28
	v_add3_u32 v28, v28, v32, s28
	v_and_b32_sdwa v32, v29, v177 dst_sel:DWORD dst_unused:UNUSED_PAD src0_sel:WORD_1 src1_sel:DWORD
	v_and_b32_sdwa v33, v27, v177 dst_sel:DWORD dst_unused:UNUSED_PAD src0_sel:WORD_1 src1_sel:DWORD
	v_add3_u32 v29, v29, v32, s28
	v_add3_u32 v27, v27, v33, s28
	v_and_b32_e32 v29, 0xffff0000, v29
	v_and_b32_e32 v32, 0xffff0000, v27
	v_or_b32_sdwa v27, v29, v28 dst_sel:DWORD dst_unused:UNUSED_PAD src0_sel:DWORD src1_sel:WORD_1
	v_or_b32_sdwa v26, v32, v26 dst_sel:DWORD dst_unused:UNUSED_PAD src0_sel:DWORD src1_sel:WORD_1
	global_store_dwordx2 v[30:31], v[26:27], off offset:32
	v_and_b32_sdwa v26, v24, v177 dst_sel:DWORD dst_unused:UNUSED_PAD src0_sel:WORD_1 src1_sel:DWORD
	v_and_b32_sdwa v27, v22, v177 dst_sel:DWORD dst_unused:UNUSED_PAD src0_sel:WORD_1 src1_sel:DWORD
	v_add3_u32 v22, v22, v27, s28
	v_add3_u32 v24, v24, v26, s28
	v_and_b32_sdwa v26, v25, v177 dst_sel:DWORD dst_unused:UNUSED_PAD src0_sel:WORD_1 src1_sel:DWORD
	v_and_b32_sdwa v27, v23, v177 dst_sel:DWORD dst_unused:UNUSED_PAD src0_sel:WORD_1 src1_sel:DWORD
	v_add3_u32 v25, v25, v26, s28
	v_add3_u32 v23, v23, v27, s28
	v_and_b32_e32 v25, 0xffff0000, v25
	v_and_b32_e32 v26, 0xffff0000, v23
	v_or_b32_sdwa v23, v25, v24 dst_sel:DWORD dst_unused:UNUSED_PAD src0_sel:DWORD src1_sel:WORD_1
	v_or_b32_sdwa v22, v26, v22 dst_sel:DWORD dst_unused:UNUSED_PAD src0_sel:DWORD src1_sel:WORD_1
	global_store_dwordx2 v[30:31], v[22:23], off offset:64
	v_and_b32_sdwa v22, v20, v177 dst_sel:DWORD dst_unused:UNUSED_PAD src0_sel:WORD_1 src1_sel:DWORD
	v_and_b32_sdwa v23, v18, v177 dst_sel:DWORD dst_unused:UNUSED_PAD src0_sel:WORD_1 src1_sel:DWORD
	v_add3_u32 v18, v18, v23, s28
	v_add3_u32 v20, v20, v22, s28
	v_and_b32_sdwa v22, v21, v177 dst_sel:DWORD dst_unused:UNUSED_PAD src0_sel:WORD_1 src1_sel:DWORD
	v_and_b32_sdwa v23, v19, v177 dst_sel:DWORD dst_unused:UNUSED_PAD src0_sel:WORD_1 src1_sel:DWORD
	v_add3_u32 v21, v21, v22, s28
	v_add3_u32 v19, v19, v23, s28
	v_and_b32_e32 v21, 0xffff0000, v21
	v_and_b32_e32 v22, 0xffff0000, v19
	v_or_b32_sdwa v19, v21, v20 dst_sel:DWORD dst_unused:UNUSED_PAD src0_sel:DWORD src1_sel:WORD_1
	v_or_b32_sdwa v18, v22, v18 dst_sel:DWORD dst_unused:UNUSED_PAD src0_sel:DWORD src1_sel:WORD_1
	global_store_dwordx2 v[30:31], v[18:19], off offset:96
	v_and_b32_sdwa v18, v16, v177 dst_sel:DWORD dst_unused:UNUSED_PAD src0_sel:WORD_1 src1_sel:DWORD
	v_and_b32_sdwa v19, v14, v177 dst_sel:DWORD dst_unused:UNUSED_PAD src0_sel:WORD_1 src1_sel:DWORD
	v_add3_u32 v14, v14, v19, s28
	v_add3_u32 v16, v16, v18, s28
	v_and_b32_sdwa v18, v17, v177 dst_sel:DWORD dst_unused:UNUSED_PAD src0_sel:WORD_1 src1_sel:DWORD
	v_and_b32_sdwa v19, v15, v177 dst_sel:DWORD dst_unused:UNUSED_PAD src0_sel:WORD_1 src1_sel:DWORD
	v_add3_u32 v17, v17, v18, s28
	v_add3_u32 v15, v15, v19, s28
	v_and_b32_e32 v17, 0xffff0000, v17
	v_and_b32_e32 v18, 0xffff0000, v15
	v_or_b32_sdwa v15, v17, v16 dst_sel:DWORD dst_unused:UNUSED_PAD src0_sel:DWORD src1_sel:WORD_1
	v_or_b32_sdwa v14, v18, v14 dst_sel:DWORD dst_unused:UNUSED_PAD src0_sel:DWORD src1_sel:WORD_1
	global_store_dwordx2 v[30:31], v[14:15], off offset:128
	v_and_b32_sdwa v14, v12, v177 dst_sel:DWORD dst_unused:UNUSED_PAD src0_sel:WORD_1 src1_sel:DWORD
	v_and_b32_sdwa v15, v10, v177 dst_sel:DWORD dst_unused:UNUSED_PAD src0_sel:WORD_1 src1_sel:DWORD
	v_add3_u32 v10, v10, v15, s28
	v_add3_u32 v12, v12, v14, s28
	v_and_b32_sdwa v14, v13, v177 dst_sel:DWORD dst_unused:UNUSED_PAD src0_sel:WORD_1 src1_sel:DWORD
	v_and_b32_sdwa v15, v11, v177 dst_sel:DWORD dst_unused:UNUSED_PAD src0_sel:WORD_1 src1_sel:DWORD
	v_add3_u32 v13, v13, v14, s28
	v_add3_u32 v11, v11, v15, s28
	v_and_b32_e32 v13, 0xffff0000, v13
	v_and_b32_e32 v14, 0xffff0000, v11
	v_or_b32_sdwa v11, v13, v12 dst_sel:DWORD dst_unused:UNUSED_PAD src0_sel:DWORD src1_sel:WORD_1
	v_or_b32_sdwa v10, v14, v10 dst_sel:DWORD dst_unused:UNUSED_PAD src0_sel:DWORD src1_sel:WORD_1
	global_store_dwordx2 v[30:31], v[10:11], off offset:160
	v_and_b32_sdwa v10, v8, v177 dst_sel:DWORD dst_unused:UNUSED_PAD src0_sel:WORD_1 src1_sel:DWORD
	v_and_b32_sdwa v11, v6, v177 dst_sel:DWORD dst_unused:UNUSED_PAD src0_sel:WORD_1 src1_sel:DWORD
	v_add3_u32 v6, v6, v11, s28
	v_add3_u32 v8, v8, v10, s28
	v_and_b32_sdwa v10, v9, v177 dst_sel:DWORD dst_unused:UNUSED_PAD src0_sel:WORD_1 src1_sel:DWORD
	v_and_b32_sdwa v11, v7, v177 dst_sel:DWORD dst_unused:UNUSED_PAD src0_sel:WORD_1 src1_sel:DWORD
	v_add3_u32 v9, v9, v10, s28
	v_add3_u32 v7, v7, v11, s28
	v_and_b32_e32 v9, 0xffff0000, v9
	v_and_b32_e32 v10, 0xffff0000, v7
	v_or_b32_sdwa v7, v9, v8 dst_sel:DWORD dst_unused:UNUSED_PAD src0_sel:DWORD src1_sel:WORD_1
	v_or_b32_sdwa v6, v10, v6 dst_sel:DWORD dst_unused:UNUSED_PAD src0_sel:DWORD src1_sel:WORD_1
	global_store_dwordx2 v[30:31], v[6:7], off offset:192
	v_and_b32_sdwa v6, v4, v177 dst_sel:DWORD dst_unused:UNUSED_PAD src0_sel:WORD_1 src1_sel:DWORD
	v_and_b32_sdwa v7, v2, v177 dst_sel:DWORD dst_unused:UNUSED_PAD src0_sel:WORD_1 src1_sel:DWORD
	v_add3_u32 v2, v2, v7, s28
	v_add3_u32 v4, v4, v6, s28
	v_and_b32_sdwa v6, v5, v177 dst_sel:DWORD dst_unused:UNUSED_PAD src0_sel:WORD_1 src1_sel:DWORD
	v_and_b32_sdwa v7, v3, v177 dst_sel:DWORD dst_unused:UNUSED_PAD src0_sel:WORD_1 src1_sel:DWORD
	v_add3_u32 v5, v5, v6, s28
	v_add3_u32 v3, v3, v7, s28
	v_and_b32_e32 v5, 0xffff0000, v5
	v_and_b32_e32 v6, 0xffff0000, v3
	s_add_i32 s11, s11, s10
	v_or_b32_sdwa v3, v5, v4 dst_sel:DWORD dst_unused:UNUSED_PAD src0_sel:DWORD src1_sel:WORD_1
	v_or_b32_sdwa v2, v6, v2 dst_sel:DWORD dst_unused:UNUSED_PAD src0_sel:DWORD src1_sel:WORD_1
	s_cmpk_gt_i32 s11, 0x3ef
	global_store_dwordx2 v[30:31], v[2:3], off offset:224
	s_cbranch_scc0 .LBB0_664

.LBB0_1307:
	s_ashr_i32 s2, s19, 31
	s_lshr_b32 s2, s2, 26
	s_add_i32 s2, s19, s2
	s_and_b32 s3, s2, 0xffffc0
	s_sub_i32 s3, s19, s3
	s_lshl_b32 s7, s3, 8
	v_add_u32_e32 v2, s7, v204
	v_ashrrev_i32_e32 v3, 31, v2
	v_lshlrev_b64 v[2:3], 11, v[2:3]
	v_lshl_add_u64 v[168:169], v[162:163], 0, v[2:3]
	s_lshl_b32 s2, s2, 2
	v_add_co_u32_e32 v56, vcc, s34, v168
	s_and_b32 s6, s2, 0xffffff00
	s_nop 0
	v_addc_co_u32_e32 v57, vcc, 0, v169, vcc
	v_add_u32_e32 v2, s6, v204
	v_add_co_u32_e32 v58, vcc, s35, v168
	v_ashrrev_i32_e32 v3, 31, v2
	s_nop 0
	v_addc_co_u32_e32 v59, vcc, 0, v169, vcc
	v_add_co_u32_e32 v60, vcc, s36, v168
	v_lshlrev_b64 v[2:3], 11, v[2:3]
	s_nop 0
	v_addc_co_u32_e32 v61, vcc, 0, v169, vcc
	v_lshl_add_u64 v[170:171], v[164:165], 0, v[2:3]
	v_add_co_u32_e32 v62, vcc, s35, v170
	global_load_dwordx4 v[24:27], v[56:57], off
	global_load_dwordx4 v[28:31], v[58:59], off
	v_addc_co_u32_e32 v63, vcc, 0, v171, vcc
	v_add_co_u32_e32 v64, vcc, s36, v170
	global_load_dwordx4 v[32:35], v[168:169], off
	global_load_dwordx4 v[36:39], v[170:171], off
	v_addc_co_u32_e32 v65, vcc, 0, v171, vcc
	v_add_co_u32_e32 v66, vcc, s34, v170
	global_load_dwordx4 v[40:43], v[62:63], off
	global_load_dwordx4 v[44:47], v[64:65], off
	v_addc_co_u32_e32 v67, vcc, 0, v171, vcc
	global_load_dwordx4 v[48:51], v[60:61], off
	global_load_dwordx4 v[52:55], v[66:67], off
	s_barrier
	global_load_dwordx4 v[118:121], v[168:169], off offset:128
	global_load_dwordx4 v[110:113], v[56:57], off offset:128
	global_load_dwordx4 v[114:117], v[58:59], off offset:128
	global_load_dwordx4 v[130:133], v[60:61], off offset:128
	global_load_dwordx4 v[126:129], v[170:171], off offset:128
	global_load_dwordx4 v[122:125], v[66:67], off offset:128
	global_load_dwordx4 v[138:141], v[62:63], off offset:128
	global_load_dwordx4 v[134:137], v[64:65], off offset:128
	v_readfirstlane_b32 s100, v172
	s_nop 0
	s_lshr_b32 m0, s100, 8
	v_readfirstlane_b32 vcc_lo, v168
	v_readfirstlane_b32 vcc_hi, v169
	v_readfirstlane_b32 s100, v170
	v_readfirstlane_b32 s101, v171
	s_nop 1
	v_subrev_u32_e32 v168, vcc_lo, v168
	v_subrev_u32_e32 v170, s100, v170
	v_mov_b32_e32 v2, 0
	s_mov_b32 s4, 0
	v_mov_b32_e32 v3, v2
	v_mov_b32_e32 v4, v2
	v_mov_b32_e32 v5, v2
	v_mov_b32_e32 v6, v2
	v_mov_b32_e32 v7, v2
	v_mov_b32_e32 v8, v2
	v_mov_b32_e32 v9, v2
	v_mov_b32_e32 v10, v2
	v_mov_b32_e32 v11, v2
	v_mov_b32_e32 v12, v2
	v_mov_b32_e32 v13, v2
	v_mov_b32_e32 v14, v2
	v_mov_b32_e32 v15, v2
	v_mov_b32_e32 v16, v2
	v_mov_b32_e32 v17, v2
	v_mov_b32_e32 v18, v2
	v_mov_b32_e32 v19, v2
	v_mov_b32_e32 v20, v2
	v_mov_b32_e32 v21, v2
	v_mov_b32_e32 v22, v2
	v_mov_b32_e32 v23, v2
	v_mov_b32_e32 v56, v2
	v_mov_b32_e32 v57, v2
	v_mov_b32_e32 v58, v2
	v_mov_b32_e32 v59, v2
	v_mov_b32_e32 v60, v2
	v_mov_b32_e32 v61, v2
	v_mov_b32_e32 v66, v2
	v_mov_b32_e32 v67, v2
	v_mov_b32_e32 v68, v2
	v_mov_b32_e32 v69, v2
	v_mov_b32_e32 v62, v2
	v_mov_b32_e32 v63, v2
	v_mov_b32_e32 v64, v2
	v_mov_b32_e32 v65, v2
	v_mov_b32_e32 v70, v2
	v_mov_b32_e32 v71, v2
	v_mov_b32_e32 v72, v2
	v_mov_b32_e32 v73, v2
	v_mov_b32_e32 v74, v2
	v_mov_b32_e32 v75, v2
	v_mov_b32_e32 v76, v2
	v_mov_b32_e32 v77, v2
	v_mov_b32_e32 v78, v2
	v_mov_b32_e32 v79, v2
	v_mov_b32_e32 v80, v2
	v_mov_b32_e32 v81, v2
	v_mov_b32_e32 v82, v2
	v_mov_b32_e32 v83, v2
	v_mov_b32_e32 v84, v2
	v_mov_b32_e32 v85, v2
	s_waitcnt vmcnt(13)
	ds_write_b128 v166, v[32:35]
	s_waitcnt vmcnt(12)
	ds_write_b128 v166, v[36:39] offset:32768
	s_waitcnt vmcnt(11)
	ds_write_b128 v166, v[40:43] offset:49152
	s_waitcnt vmcnt(10)
	ds_write_b128 v166, v[44:47] offset:57344
	ds_write_b128 v166, v[24:27] offset:8192
	ds_write_b128 v166, v[28:31] offset:16384
	s_waitcnt vmcnt(9)
	ds_write_b128 v166, v[48:51] offset:24576
	s_waitcnt vmcnt(8)
	ds_write_b128 v166, v[52:55] offset:40960
	v_mov_b32_e32 v24, v2
	v_mov_b32_e32 v25, v2
	v_mov_b32_e32 v26, v2
	v_mov_b32_e32 v27, v2
	v_mov_b32_e32 v28, v2
	v_mov_b32_e32 v29, v2
	v_mov_b32_e32 v34, v2
	v_mov_b32_e32 v35, v2
	v_mov_b32_e32 v36, v2
	v_mov_b32_e32 v37, v2
	v_mov_b32_e32 v30, v2
	v_mov_b32_e32 v31, v2
	v_mov_b32_e32 v32, v2
	v_mov_b32_e32 v33, v2
	v_mov_b32_e32 v38, v2
	v_mov_b32_e32 v39, v2
	v_mov_b32_e32 v40, v2
	v_mov_b32_e32 v41, v2
	v_mov_b32_e32 v42, v2
	v_mov_b32_e32 v43, v2
	v_mov_b32_e32 v44, v2
	v_mov_b32_e32 v45, v2
	v_mov_b32_e32 v46, v2
	v_mov_b32_e32 v47, v2
	v_mov_b32_e32 v48, v2
	v_mov_b32_e32 v49, v2
	v_mov_b32_e32 v50, v2
	v_mov_b32_e32 v51, v2
	v_mov_b32_e32 v52, v2
	v_mov_b32_e32 v53, v2
	v_mov_b32_e32 v54, v2
	v_mov_b32_e32 v55, v2
	v_mov_b32_e32 v86, v2
	v_mov_b32_e32 v87, v2
	v_mov_b32_e32 v88, v2
	v_mov_b32_e32 v89, v2
	v_mov_b32_e32 v90, v2
	v_mov_b32_e32 v91, v2
	v_mov_b32_e32 v92, v2
	v_mov_b32_e32 v93, v2
	v_mov_b32_e32 v98, v2
	v_mov_b32_e32 v99, v2
	v_mov_b32_e32 v100, v2
	v_mov_b32_e32 v101, v2
	v_mov_b32_e32 v94, v2
	v_mov_b32_e32 v95, v2
	v_mov_b32_e32 v96, v2
	v_mov_b32_e32 v97, v2
	v_mov_b32_e32 v102, v2
	v_mov_b32_e32 v103, v2
	v_mov_b32_e32 v104, v2
	v_mov_b32_e32 v105, v2
	v_mov_b32_e32 v106, v2
	v_mov_b32_e32 v107, v2
	v_mov_b32_e32 v108, v2
	v_mov_b32_e32 v109, v2
	v_mov_b32_e32 v142, v2
	v_mov_b32_e32 v143, v2
	v_mov_b32_e32 v144, v2
	v_mov_b32_e32 v145, v2
	v_mov_b32_e32 v146, v2
	v_mov_b32_e32 v147, v2
	v_mov_b32_e32 v148, v2
	v_mov_b32_e32 v149, v2
	v_mov_b32_e32 v150, v2
	v_mov_b32_e32 v151, v2
	v_mov_b32_e32 v152, v2
	v_mov_b32_e32 v153, v2
	v_mov_b32_e32 v154, v2
	v_mov_b32_e32 v155, v2
	v_mov_b32_e32 v156, v2
	v_mov_b32_e32 v157, v2
	v_mov_b32_e32 v158, v2
	v_mov_b32_e32 v159, v2
	v_mov_b32_e32 v160, v2
	v_mov_b32_e32 v161, v2
	s_waitcnt lgkmcnt(0)
	s_barrier
	s_cmp_lg_u32 m0, 0
	s_cbranch_scc1 .Lg1_1308
.LBB0_1308:
	s_bitcmp1_b32 s4, 0
	s_cselect_b32 s2, 0x12000, 0
	v_or_b32_e32 v218, s2, v207
	v_add_u32_e32 v214, v218, v0
	v_add_u32_e32 v246, v218, v167
	ds_read_b128 v[184:187], v214
	ds_read_b128 v[218:221], v246 offset:32768
	ds_read_b128 v[198:201], v214 offset:2048
	ds_read_b128 v[210:213], v214 offset:4096
	ds_read_b128 v[214:217], v214 offset:6144
	ds_read_b128 v[222:225], v246 offset:34816
	ds_read_b128 v[226:229], v246 offset:36864
	ds_read_b128 v[230:233], v246 offset:38912
	ds_read_b128 v[234:237], v246 offset:40960
	ds_read_b128 v[238:241], v246 offset:43008
	ds_read_b128 v[242:245], v246 offset:45056
	ds_read_b128 v[246:249], v246 offset:47104
	s_add_i32 s10, s4, 1
	s_bitcmp1_b32 s10, 0
	s_cselect_b32 s3, 0x12000, 0
	v_add_u32_e32 v171, s3, v166
	v_xor_b32_e32 v169, 64, v207
	v_add3_u32 v169, s2, v167, v169
	s_waitcnt lgkmcnt(10)
	v_mfma_f32_16x16x32_bf16 v[158:161], v[218:221], v[184:187], v[158:161]
	s_waitcnt lgkmcnt(9)
	v_mfma_f32_16x16x32_bf16 v[98:101], v[218:221], v[198:201], v[98:101]
	s_waitcnt lgkmcnt(8)
	v_mfma_f32_16x16x32_bf16 v[66:69], v[218:221], v[210:213], v[66:69]
	s_waitcnt lgkmcnt(7)
	v_mfma_f32_16x16x32_bf16 v[34:37], v[218:221], v[214:217], v[34:37]
	ds_read_b128 v[218:221], v169 offset:32768
	s_waitcnt lgkmcnt(7)
	v_mfma_f32_16x16x32_bf16 v[154:157], v[222:225], v[184:187], v[154:157]
	v_mfma_f32_16x16x32_bf16 v[90:93], v[222:225], v[198:201], v[90:93]
	v_mfma_f32_16x16x32_bf16 v[58:61], v[222:225], v[210:213], v[58:61]
	v_mfma_f32_16x16x32_bf16 v[26:29], v[222:225], v[214:217], v[26:29]
	ds_read_b128 v[222:225], v169 offset:34816
	s_waitcnt lgkmcnt(7)
	v_mfma_f32_16x16x32_bf16 v[150:153], v[226:229], v[184:187], v[150:153]
	v_mfma_f32_16x16x32_bf16 v[86:89], v[226:229], v[198:201], v[86:89]
	v_mfma_f32_16x16x32_bf16 v[54:57], v[226:229], v[210:213], v[54:57]
	v_mfma_f32_16x16x32_bf16 v[22:25], v[226:229], v[214:217], v[22:25]
	ds_read_b128 v[226:229], v169 offset:36864
	s_waitcnt lgkmcnt(7)
	v_mfma_f32_16x16x32_bf16 v[146:149], v[230:233], v[184:187], v[146:149]
	v_mfma_f32_16x16x32_bf16 v[82:85], v[230:233], v[198:201], v[82:85]
	v_mfma_f32_16x16x32_bf16 v[50:53], v[230:233], v[210:213], v[50:53]
	v_mfma_f32_16x16x32_bf16 v[18:21], v[230:233], v[214:217], v[18:21]
	ds_read_b128 v[230:233], v169 offset:38912
	s_waitcnt lgkmcnt(7)
	v_mfma_f32_16x16x32_bf16 v[142:145], v[234:237], v[184:187], v[142:145]
	v_mfma_f32_16x16x32_bf16 v[78:81], v[234:237], v[198:201], v[78:81]
	v_mfma_f32_16x16x32_bf16 v[46:49], v[234:237], v[210:213], v[46:49]
	v_mfma_f32_16x16x32_bf16 v[14:17], v[234:237], v[214:217], v[14:17]
	ds_read_b128 v[234:237], v169 offset:40960
	s_waitcnt lgkmcnt(7)
	v_mfma_f32_16x16x32_bf16 v[106:109], v[238:241], v[184:187], v[106:109]
	v_mfma_f32_16x16x32_bf16 v[74:77], v[238:241], v[198:201], v[74:77]
	v_mfma_f32_16x16x32_bf16 v[42:45], v[238:241], v[210:213], v[42:45]
	v_mfma_f32_16x16x32_bf16 v[10:13], v[238:241], v[214:217], v[10:13]
	ds_read_b128 v[238:241], v169 offset:43008
	s_waitcnt lgkmcnt(7)
	v_mfma_f32_16x16x32_bf16 v[102:105], v[242:245], v[184:187], v[102:105]
	v_mfma_f32_16x16x32_bf16 v[70:73], v[242:245], v[198:201], v[70:73]
	v_mfma_f32_16x16x32_bf16 v[38:41], v[242:245], v[210:213], v[38:41]
	v_mfma_f32_16x16x32_bf16 v[6:9], v[242:245], v[214:217], v[6:9]
	ds_read_b128 v[242:245], v169 offset:45056
	s_waitcnt lgkmcnt(7)
	v_mfma_f32_16x16x32_bf16 v[94:97], v[246:249], v[184:187], v[94:97]
	v_mfma_f32_16x16x32_bf16 v[62:65], v[246:249], v[198:201], v[62:65]
	v_xor_b32_e32 v169, 64, v207
	v_add3_u32 v169, s2, v0, v169
	ds_read_b128 v[184:187], v169
	ds_read_b128 v[198:201], v169 offset:2048
	v_mfma_f32_16x16x32_bf16 v[30:33], v[246:249], v[210:213], v[30:33]
	ds_read_b128 v[210:213], v169 offset:4096
	v_mfma_f32_16x16x32_bf16 v[2:5], v[246:249], v[214:217], v[2:5]
	ds_read_b128 v[214:217], v169 offset:6144
	v_xor_b32_e32 v169, 64, v207
	v_add3_u32 v169, s2, v167, v169
	ds_read_b128 v[246:249], v169 offset:47104
	s_waitcnt lgkmcnt(4)
	v_mfma_f32_16x16x32_bf16 v[158:161], v[218:221], v[184:187], v[158:161]
	s_waitcnt lgkmcnt(3)
	v_mfma_f32_16x16x32_bf16 v[98:101], v[218:221], v[198:201], v[98:101]
	s_waitcnt lgkmcnt(2)
	v_mfma_f32_16x16x32_bf16 v[66:69], v[218:221], v[210:213], v[66:69]
	s_waitcnt lgkmcnt(1)
	v_mfma_f32_16x16x32_bf16 v[34:37], v[218:221], v[214:217], v[34:37]
	s_waitcnt vmcnt(7)
	ds_write_b128 v171, v[118:121]
	v_mfma_f32_16x16x32_bf16 v[154:157], v[222:225], v[184:187], v[154:157]
	v_mfma_f32_16x16x32_bf16 v[90:93], v[222:225], v[198:201], v[90:93]
	global_load_dwordx4 v[118:121], v168, vcc offset:256
	v_mfma_f32_16x16x32_bf16 v[58:61], v[222:225], v[210:213], v[58:61]
	v_mfma_f32_16x16x32_bf16 v[26:29], v[222:225], v[214:217], v[26:29]
	s_waitcnt vmcnt(7)
	ds_write_b128 v171, v[110:113] offset:8192
	v_mfma_f32_16x16x32_bf16 v[150:153], v[226:229], v[184:187], v[150:153]
	v_mfma_f32_16x16x32_bf16 v[86:89], v[226:229], v[198:201], v[86:89]
	v_add_u32_e32 v110, s34, v168
	global_load_dwordx4 v[110:113], v110, vcc offset:256
	v_mfma_f32_16x16x32_bf16 v[54:57], v[226:229], v[210:213], v[54:57]
	v_mfma_f32_16x16x32_bf16 v[22:25], v[226:229], v[214:217], v[22:25]
	s_waitcnt vmcnt(7)
	ds_write_b128 v171, v[114:117] offset:16384
	v_mfma_f32_16x16x32_bf16 v[146:149], v[230:233], v[184:187], v[146:149]
	v_mfma_f32_16x16x32_bf16 v[82:85], v[230:233], v[198:201], v[82:85]
	v_add_u32_e32 v114, s35, v168
	global_load_dwordx4 v[114:117], v114, vcc offset:256
	v_mfma_f32_16x16x32_bf16 v[50:53], v[230:233], v[210:213], v[50:53]
	v_mfma_f32_16x16x32_bf16 v[18:21], v[230:233], v[214:217], v[18:21]
	s_waitcnt vmcnt(7)
	ds_write_b128 v171, v[130:133] offset:24576
	v_mfma_f32_16x16x32_bf16 v[142:145], v[234:237], v[184:187], v[142:145]
	v_mfma_f32_16x16x32_bf16 v[78:81], v[234:237], v[198:201], v[78:81]
	v_add_u32_e32 v130, s36, v168
	global_load_dwordx4 v[130:133], v130, vcc offset:256
	v_mfma_f32_16x16x32_bf16 v[46:49], v[234:237], v[210:213], v[46:49]
	v_mfma_f32_16x16x32_bf16 v[14:17], v[234:237], v[214:217], v[14:17]
	s_waitcnt vmcnt(7)
	ds_write_b128 v171, v[126:129] offset:32768
	v_mfma_f32_16x16x32_bf16 v[106:109], v[238:241], v[184:187], v[106:109]
	v_mfma_f32_16x16x32_bf16 v[74:77], v[238:241], v[198:201], v[74:77]
	global_load_dwordx4 v[126:129], v170, s[100:101] offset:256
	v_mfma_f32_16x16x32_bf16 v[42:45], v[238:241], v[210:213], v[42:45]
	v_mfma_f32_16x16x32_bf16 v[10:13], v[238:241], v[214:217], v[10:13]
	s_waitcnt vmcnt(7)
	ds_write_b128 v171, v[122:125] offset:40960
	v_mfma_f32_16x16x32_bf16 v[102:105], v[242:245], v[184:187], v[102:105]
	v_mfma_f32_16x16x32_bf16 v[70:73], v[242:245], v[198:201], v[70:73]
	v_add_u32_e32 v122, s34, v170
	global_load_dwordx4 v[122:125], v122, s[100:101] offset:256
	v_mfma_f32_16x16x32_bf16 v[38:41], v[242:245], v[210:213], v[38:41]
	v_mfma_f32_16x16x32_bf16 v[6:9], v[242:245], v[214:217], v[6:9]
	s_waitcnt vmcnt(7)
	ds_write_b128 v171, v[138:141] offset:49152
	s_waitcnt lgkmcnt(7)
	v_mfma_f32_16x16x32_bf16 v[94:97], v[246:249], v[184:187], v[94:97]
	v_mfma_f32_16x16x32_bf16 v[62:65], v[246:249], v[198:201], v[62:65]
	v_add_u32_e32 v138, s35, v170
	global_load_dwordx4 v[138:141], v138, s[100:101] offset:256
	v_mfma_f32_16x16x32_bf16 v[30:33], v[246:249], v[210:213], v[30:33]
	v_mfma_f32_16x16x32_bf16 v[2:5], v[246:249], v[214:217], v[2:5]
	s_waitcnt vmcnt(7)
	ds_write_b128 v171, v[134:137] offset:57344
	v_add_u32_e32 v134, s36, v170
	global_load_dwordx4 v[134:137], v134, s[100:101] offset:256
	v_add_u32_e32 v168, 0x80, v168
	v_add_u32_e32 v170, 0x80, v170
	s_waitcnt lgkmcnt(0)
	s_barrier
	s_cmp_eq_u32 s10, 16
	s_mov_b32 s4, s10
	s_cbranch_scc0 .LBB0_1308
	s_branch .Lkdone_1308
.Lg1_1308:
	v_add_u32_e32 v171, 0x12000, v166
	s_waitcnt vmcnt(7)
	ds_write_b128 v171, v[118:121]
	global_load_dwordx4 v[118:121], v168, vcc offset:256
	s_waitcnt vmcnt(7)
	ds_write_b128 v171, v[110:113] offset:8192
	v_add_u32_e32 v110, s34, v168
	global_load_dwordx4 v[110:113], v110, vcc offset:256
	s_waitcnt vmcnt(7)
	ds_write_b128 v171, v[114:117] offset:16384
	v_add_u32_e32 v114, s35, v168
	global_load_dwordx4 v[114:117], v114, vcc offset:256
	s_waitcnt vmcnt(7)
	ds_write_b128 v171, v[130:133] offset:24576
	v_add_u32_e32 v130, s36, v168
	global_load_dwordx4 v[130:133], v130, vcc offset:256
	s_waitcnt vmcnt(7)
	ds_write_b128 v171, v[126:129] offset:32768
	global_load_dwordx4 v[126:129], v170, s[100:101] offset:256
	s_waitcnt vmcnt(7)
	ds_write_b128 v171, v[122:125] offset:40960
	v_add_u32_e32 v122, s34, v170
	global_load_dwordx4 v[122:125], v122, s[100:101] offset:256
	s_waitcnt vmcnt(7)
	ds_write_b128 v171, v[138:141] offset:49152
	v_add_u32_e32 v138, s35, v170
	global_load_dwordx4 v[138:141], v138, s[100:101] offset:256
	s_waitcnt vmcnt(7)
	ds_write_b128 v171, v[134:137] offset:57344
	v_add_u32_e32 v134, s36, v170
	global_load_dwordx4 v[134:137], v134, s[100:101] offset:256
	v_add_u32_e32 v168, 0x80, v168
	v_add_u32_e32 v170, 0x80, v170
.Lg1loop_1308:
	s_bitcmp1_b32 s4, 0
	s_cselect_b32 s2, 0x12000, 0
	v_or_b32_e32 v218, s2, v207
	v_add_u32_e32 v214, v218, v0
	v_add_u32_e32 v246, v218, v167
	ds_read_b128 v[184:187], v214
	ds_read_b128 v[218:221], v246 offset:32768
	ds_read_b128 v[198:201], v214 offset:2048
	ds_read_b128 v[210:213], v214 offset:4096
	ds_read_b128 v[214:217], v214 offset:6144
	ds_read_b128 v[222:225], v246 offset:34816
	ds_read_b128 v[226:229], v246 offset:36864
	ds_read_b128 v[230:233], v246 offset:38912
	ds_read_b128 v[234:237], v246 offset:40960
	ds_read_b128 v[238:241], v246 offset:43008
	ds_read_b128 v[242:245], v246 offset:45056
	ds_read_b128 v[246:249], v246 offset:47104
	s_add_i32 s10, s4, 1
	s_bitcmp1_b32 s10, 0
	s_cselect_b32 s3, 0x12000, 0
	v_add_u32_e32 v171, s2, v166
	v_xor_b32_e32 v169, 64, v207
	v_add3_u32 v169, s2, v167, v169
	s_waitcnt lgkmcnt(10)
	v_mfma_f32_16x16x32_bf16 v[158:161], v[218:221], v[184:187], v[158:161]
	s_waitcnt lgkmcnt(9)
	v_mfma_f32_16x16x32_bf16 v[98:101], v[218:221], v[198:201], v[98:101]
	s_waitcnt lgkmcnt(8)
	v_mfma_f32_16x16x32_bf16 v[66:69], v[218:221], v[210:213], v[66:69]
	s_waitcnt lgkmcnt(7)
	v_mfma_f32_16x16x32_bf16 v[34:37], v[218:221], v[214:217], v[34:37]
	ds_read_b128 v[218:221], v169 offset:32768
	s_waitcnt lgkmcnt(7)
	v_mfma_f32_16x16x32_bf16 v[154:157], v[222:225], v[184:187], v[154:157]
	v_mfma_f32_16x16x32_bf16 v[90:93], v[222:225], v[198:201], v[90:93]
	v_mfma_f32_16x16x32_bf16 v[58:61], v[222:225], v[210:213], v[58:61]
	v_mfma_f32_16x16x32_bf16 v[26:29], v[222:225], v[214:217], v[26:29]
	ds_read_b128 v[222:225], v169 offset:34816
	s_waitcnt lgkmcnt(7)
	v_mfma_f32_16x16x32_bf16 v[150:153], v[226:229], v[184:187], v[150:153]
	v_mfma_f32_16x16x32_bf16 v[86:89], v[226:229], v[198:201], v[86:89]
	v_mfma_f32_16x16x32_bf16 v[54:57], v[226:229], v[210:213], v[54:57]
	v_mfma_f32_16x16x32_bf16 v[22:25], v[226:229], v[214:217], v[22:25]
	ds_read_b128 v[226:229], v169 offset:36864
	s_waitcnt lgkmcnt(7)
	v_mfma_f32_16x16x32_bf16 v[146:149], v[230:233], v[184:187], v[146:149]
	v_mfma_f32_16x16x32_bf16 v[82:85], v[230:233], v[198:201], v[82:85]
	v_mfma_f32_16x16x32_bf16 v[50:53], v[230:233], v[210:213], v[50:53]
	v_mfma_f32_16x16x32_bf16 v[18:21], v[230:233], v[214:217], v[18:21]
	ds_read_b128 v[230:233], v169 offset:38912
	s_waitcnt lgkmcnt(7)
	v_mfma_f32_16x16x32_bf16 v[142:145], v[234:237], v[184:187], v[142:145]
	v_mfma_f32_16x16x32_bf16 v[78:81], v[234:237], v[198:201], v[78:81]
	v_mfma_f32_16x16x32_bf16 v[46:49], v[234:237], v[210:213], v[46:49]
	v_mfma_f32_16x16x32_bf16 v[14:17], v[234:237], v[214:217], v[14:17]
	ds_read_b128 v[234:237], v169 offset:40960
	s_waitcnt lgkmcnt(7)
	v_mfma_f32_16x16x32_bf16 v[106:109], v[238:241], v[184:187], v[106:109]
	v_mfma_f32_16x16x32_bf16 v[74:77], v[238:241], v[198:201], v[74:77]
	v_mfma_f32_16x16x32_bf16 v[42:45], v[238:241], v[210:213], v[42:45]
	v_mfma_f32_16x16x32_bf16 v[10:13], v[238:241], v[214:217], v[10:13]
	ds_read_b128 v[238:241], v169 offset:43008
	s_waitcnt lgkmcnt(7)
	v_mfma_f32_16x16x32_bf16 v[102:105], v[242:245], v[184:187], v[102:105]
	v_mfma_f32_16x16x32_bf16 v[70:73], v[242:245], v[198:201], v[70:73]
	v_mfma_f32_16x16x32_bf16 v[38:41], v[242:245], v[210:213], v[38:41]
	v_mfma_f32_16x16x32_bf16 v[6:9], v[242:245], v[214:217], v[6:9]
	ds_read_b128 v[242:245], v169 offset:45056
	s_waitcnt lgkmcnt(7)
	v_mfma_f32_16x16x32_bf16 v[94:97], v[246:249], v[184:187], v[94:97]
	v_mfma_f32_16x16x32_bf16 v[62:65], v[246:249], v[198:201], v[62:65]
	v_xor_b32_e32 v169, 64, v207
	v_add3_u32 v169, s2, v0, v169
	ds_read_b128 v[184:187], v169
	ds_read_b128 v[198:201], v169 offset:2048
	v_mfma_f32_16x16x32_bf16 v[30:33], v[246:249], v[210:213], v[30:33]
	ds_read_b128 v[210:213], v169 offset:4096
	v_mfma_f32_16x16x32_bf16 v[2:5], v[246:249], v[214:217], v[2:5]
	ds_read_b128 v[214:217], v169 offset:6144
	v_xor_b32_e32 v169, 64, v207
	v_add3_u32 v169, s2, v167, v169
	ds_read_b128 v[246:249], v169 offset:47104
	s_waitcnt lgkmcnt(0)
	s_barrier
	s_waitcnt lgkmcnt(4)
	v_mfma_f32_16x16x32_bf16 v[158:161], v[218:221], v[184:187], v[158:161]
	s_waitcnt lgkmcnt(3)
	v_mfma_f32_16x16x32_bf16 v[98:101], v[218:221], v[198:201], v[98:101]
	s_waitcnt lgkmcnt(2)
	v_mfma_f32_16x16x32_bf16 v[66:69], v[218:221], v[210:213], v[66:69]
	s_waitcnt lgkmcnt(1)
	v_mfma_f32_16x16x32_bf16 v[34:37], v[218:221], v[214:217], v[34:37]
	s_waitcnt vmcnt(7)
	ds_write_b128 v171, v[118:121]
	v_mfma_f32_16x16x32_bf16 v[154:157], v[222:225], v[184:187], v[154:157]
	v_mfma_f32_16x16x32_bf16 v[90:93], v[222:225], v[198:201], v[90:93]
	global_load_dwordx4 v[118:121], v168, vcc offset:256
	v_mfma_f32_16x16x32_bf16 v[58:61], v[222:225], v[210:213], v[58:61]
	v_mfma_f32_16x16x32_bf16 v[26:29], v[222:225], v[214:217], v[26:29]
	s_waitcnt vmcnt(7)
	ds_write_b128 v171, v[110:113] offset:8192
	v_mfma_f32_16x16x32_bf16 v[150:153], v[226:229], v[184:187], v[150:153]
	v_mfma_f32_16x16x32_bf16 v[86:89], v[226:229], v[198:201], v[86:89]
	v_add_u32_e32 v110, s34, v168
	global_load_dwordx4 v[110:113], v110, vcc offset:256
	v_mfma_f32_16x16x32_bf16 v[54:57], v[226:229], v[210:213], v[54:57]
	v_mfma_f32_16x16x32_bf16 v[22:25], v[226:229], v[214:217], v[22:25]
	s_waitcnt vmcnt(7)
	ds_write_b128 v171, v[114:117] offset:16384
	v_mfma_f32_16x16x32_bf16 v[146:149], v[230:233], v[184:187], v[146:149]
	v_mfma_f32_16x16x32_bf16 v[82:85], v[230:233], v[198:201], v[82:85]
	v_add_u32_e32 v114, s35, v168
	global_load_dwordx4 v[114:117], v114, vcc offset:256
	v_mfma_f32_16x16x32_bf16 v[50:53], v[230:233], v[210:213], v[50:53]
	v_mfma_f32_16x16x32_bf16 v[18:21], v[230:233], v[214:217], v[18:21]
	s_waitcnt vmcnt(7)
	ds_write_b128 v171, v[130:133] offset:24576
	v_mfma_f32_16x16x32_bf16 v[142:145], v[234:237], v[184:187], v[142:145]
	v_mfma_f32_16x16x32_bf16 v[78:81], v[234:237], v[198:201], v[78:81]
	v_add_u32_e32 v130, s36, v168
	global_load_dwordx4 v[130:133], v130, vcc offset:256
	v_mfma_f32_16x16x32_bf16 v[46:49], v[234:237], v[210:213], v[46:49]
	v_mfma_f32_16x16x32_bf16 v[14:17], v[234:237], v[214:217], v[14:17]
	s_waitcnt vmcnt(7)
	ds_write_b128 v171, v[126:129] offset:32768
	v_mfma_f32_16x16x32_bf16 v[106:109], v[238:241], v[184:187], v[106:109]
	v_mfma_f32_16x16x32_bf16 v[74:77], v[238:241], v[198:201], v[74:77]
	global_load_dwordx4 v[126:129], v170, s[100:101] offset:256
	v_mfma_f32_16x16x32_bf16 v[42:45], v[238:241], v[210:213], v[42:45]
	v_mfma_f32_16x16x32_bf16 v[10:13], v[238:241], v[214:217], v[10:13]
	s_waitcnt vmcnt(7)
	ds_write_b128 v171, v[122:125] offset:40960
	v_mfma_f32_16x16x32_bf16 v[102:105], v[242:245], v[184:187], v[102:105]
	v_mfma_f32_16x16x32_bf16 v[70:73], v[242:245], v[198:201], v[70:73]
	v_add_u32_e32 v122, s34, v170
	global_load_dwordx4 v[122:125], v122, s[100:101] offset:256
	v_mfma_f32_16x16x32_bf16 v[38:41], v[242:245], v[210:213], v[38:41]
	v_mfma_f32_16x16x32_bf16 v[6:9], v[242:245], v[214:217], v[6:9]
	s_waitcnt vmcnt(7)
	ds_write_b128 v171, v[138:141] offset:49152
	s_waitcnt lgkmcnt(7)
	v_mfma_f32_16x16x32_bf16 v[94:97], v[246:249], v[184:187], v[94:97]
	v_mfma_f32_16x16x32_bf16 v[62:65], v[246:249], v[198:201], v[62:65]
	v_add_u32_e32 v138, s35, v170
	global_load_dwordx4 v[138:141], v138, s[100:101] offset:256
	v_mfma_f32_16x16x32_bf16 v[30:33], v[246:249], v[210:213], v[30:33]
	v_mfma_f32_16x16x32_bf16 v[2:5], v[246:249], v[214:217], v[2:5]
	s_waitcnt vmcnt(7)
	ds_write_b128 v171, v[134:137] offset:57344
	v_add_u32_e32 v134, s36, v170
	global_load_dwordx4 v[134:137], v134, s[100:101] offset:256
	v_add_u32_e32 v168, 0x80, v168
	v_add_u32_e32 v170, 0x80, v170
	s_cmp_eq_u32 s10, 16
	s_mov_b32 s4, s10
	s_cbranch_scc0 .Lg1loop_1308
	s_waitcnt lgkmcnt(0)
.Lkdone_1308:
	s_waitcnt vmcnt(4)
	v_add_u32_e32 v110, s7, v206
	s_waitcnt vmcnt(3)
	v_or_b32_e32 v114, v110, v205
	v_cmp_lt_i32_e32 vcc, s97, v114
	v_ashrrev_i32_e32 v112, 31, v114
	v_add_u32_e32 v116, 0xffffc000, v114
	v_ashrrev_i32_e32 v115, 11, v110
	v_cndmask_b32_e64 v113, v112, 0, vcc
	v_cndmask_b32_e32 v112, v114, v116, vcc
	v_mov_b32_e32 v116, s45
	v_mov_b32_e32 v117, s13
	v_mov_b32_e32 v118, s44
	v_mov_b32_e32 v119, s12
	v_or_b32_e32 v110, s6, v208
	s_waitcnt vmcnt(2)
	v_cndmask_b32_e64 v122, v115, 8, vcc
	v_cndmask_b32_e32 v121, v116, v117, vcc
	v_cndmask_b32_e32 v120, v118, v119, vcc
	v_lshlrev_b64 v[112:113], 12, v[112:113]
	v_ashrrev_i32_e32 v111, 31, v110
	v_lshl_add_u64 v[112:113], v[120:121], 0, v[112:113]
	v_mul_hi_i32_i24_e32 v121, 0x9000, v122
	v_mul_i32_i24_e32 v120, 0x9000, v122
	v_lshl_add_u64 v[120:121], s[14:15], 0, v[120:121]
	v_lshlrev_b64 v[110:111], 2, v[110:111]
	s_waitcnt vmcnt(0)
	v_lshl_add_u64 v[128:129], v[120:121], 0, v[110:111]
	v_lshl_add_u64 v[112:113], v[112:113], 0, v[110:111]
	global_load_dwordx4 v[120:123], v[128:129], off
	global_load_dwordx4 v[124:127], v[112:113], off
	s_waitcnt vmcnt(0)
	v_pk_fma_f32 v[120:121], v[158:159], v[120:121], v[124:125]
	v_pk_fma_f32 v[122:123], v[160:161], v[122:123], v[126:127]
	global_store_dwordx4 v[112:113], v[120:123], off
	global_load_dwordx4 v[120:123], v[128:129], off offset:64
	s_nop 0
	global_load_dwordx4 v[124:127], v[112:113], off offset:64
	s_waitcnt vmcnt(0)
	v_pk_fma_f32 v[120:121], v[154:155], v[120:121], v[124:125]
	v_pk_fma_f32 v[122:123], v[156:157], v[122:123], v[126:127]
	global_store_dwordx4 v[112:113], v[120:123], off offset:64
	global_load_dwordx4 v[120:123], v[128:129], off offset:128
	s_nop 0
	global_load_dwordx4 v[124:127], v[112:113], off offset:128
	s_waitcnt vmcnt(0)
	v_pk_fma_f32 v[120:121], v[150:151], v[120:121], v[124:125]
	v_pk_fma_f32 v[122:123], v[152:153], v[122:123], v[126:127]
	global_store_dwordx4 v[112:113], v[120:123], off offset:128
	global_load_dwordx4 v[120:123], v[128:129], off offset:192
	s_nop 0
	global_load_dwordx4 v[124:127], v[112:113], off offset:192
	s_waitcnt vmcnt(0)
	v_pk_fma_f32 v[120:121], v[146:147], v[120:121], v[124:125]
	v_pk_fma_f32 v[122:123], v[148:149], v[122:123], v[126:127]
	global_store_dwordx4 v[112:113], v[120:123], off offset:192
	global_load_dwordx4 v[120:123], v[128:129], off offset:256
	s_nop 0
	global_load_dwordx4 v[124:127], v[112:113], off offset:256
	s_waitcnt vmcnt(0)
	v_pk_fma_f32 v[120:121], v[142:143], v[120:121], v[124:125]
	v_pk_fma_f32 v[122:123], v[144:145], v[122:123], v[126:127]
	global_store_dwordx4 v[112:113], v[120:123], off offset:256
	global_load_dwordx4 v[120:123], v[128:129], off offset:320
	s_nop 0
	global_load_dwordx4 v[124:127], v[112:113], off offset:320
	s_waitcnt vmcnt(0)
	v_pk_fma_f32 v[106:107], v[106:107], v[120:121], v[124:125]
	v_pk_fma_f32 v[108:109], v[108:109], v[122:123], v[126:127]
	global_store_dwordx4 v[112:113], v[106:109], off offset:320
	global_load_dwordx4 v[106:109], v[128:129], off offset:384
	s_nop 0
	global_load_dwordx4 v[120:123], v[112:113], off offset:384
	s_waitcnt vmcnt(0)
	v_pk_fma_f32 v[102:103], v[102:103], v[106:107], v[120:121]
	v_pk_fma_f32 v[104:105], v[104:105], v[108:109], v[122:123]
	global_store_dwordx4 v[112:113], v[102:105], off offset:384
	global_load_dwordx4 v[102:105], v[128:129], off offset:448
	s_nop 0
	global_load_dwordx4 v[106:109], v[112:113], off offset:448
	s_waitcnt vmcnt(0)
	v_pk_fma_f32 v[94:95], v[94:95], v[102:103], v[106:107]
	v_pk_fma_f32 v[96:97], v[96:97], v[104:105], v[108:109]
	global_store_dwordx4 v[112:113], v[94:97], off offset:448
	s_nop 1
	v_or_b32_e32 v94, 16, v114
	v_cmp_lt_i32_e32 vcc, s97, v94
	v_add_u32_e32 v96, 0xffffc010, v114
	v_ashrrev_i32_e32 v95, 31, v94
	v_cndmask_b32_e64 v95, v95, 0, vcc
	v_cndmask_b32_e32 v94, v94, v96, vcc
	v_cndmask_b32_e64 v102, v115, 8, vcc
	v_cndmask_b32_e32 v97, v116, v117, vcc
	v_cndmask_b32_e32 v96, v118, v119, vcc
	v_lshlrev_b64 v[94:95], 12, v[94:95]
	v_lshl_add_u64 v[94:95], v[96:97], 0, v[94:95]
	v_mul_hi_i32_i24_e32 v97, 0x9000, v102
	v_mul_i32_i24_e32 v96, 0x9000, v102
	v_lshl_add_u64 v[96:97], s[14:15], 0, v[96:97]
	v_lshl_add_u64 v[112:113], v[96:97], 0, v[110:111]
	v_lshl_add_u64 v[94:95], v[94:95], 0, v[110:111]
	global_load_dwordx4 v[102:105], v[112:113], off
	global_load_dwordx4 v[106:109], v[94:95], off
	s_waitcnt vmcnt(0)
	v_pk_fma_f32 v[96:97], v[98:99], v[102:103], v[106:107]
	v_pk_fma_f32 v[98:99], v[100:101], v[104:105], v[108:109]
	global_store_dwordx4 v[94:95], v[96:99], off
	global_load_dwordx4 v[96:99], v[112:113], off offset:64
	s_nop 0
	global_load_dwordx4 v[100:103], v[94:95], off offset:64
	s_waitcnt vmcnt(0)
	v_pk_fma_f32 v[90:91], v[90:91], v[96:97], v[100:101]
	v_pk_fma_f32 v[92:93], v[92:93], v[98:99], v[102:103]
	global_store_dwordx4 v[94:95], v[90:93], off offset:64
	global_load_dwordx4 v[90:93], v[112:113], off offset:128
	s_nop 0
	global_load_dwordx4 v[96:99], v[94:95], off offset:128
	s_waitcnt vmcnt(0)
	v_pk_fma_f32 v[86:87], v[86:87], v[90:91], v[96:97]
	v_pk_fma_f32 v[88:89], v[88:89], v[92:93], v[98:99]
	global_store_dwordx4 v[94:95], v[86:89], off offset:128
	global_load_dwordx4 v[86:89], v[112:113], off offset:192
	s_nop 0
	global_load_dwordx4 v[90:93], v[94:95], off offset:192
	s_waitcnt vmcnt(0)
	v_pk_fma_f32 v[82:83], v[82:83], v[86:87], v[90:91]
	v_pk_fma_f32 v[84:85], v[84:85], v[88:89], v[92:93]
	global_store_dwordx4 v[94:95], v[82:85], off offset:192
	global_load_dwordx4 v[82:85], v[112:113], off offset:256
	s_nop 0
	global_load_dwordx4 v[86:89], v[94:95], off offset:256
	s_waitcnt vmcnt(0)
	v_pk_fma_f32 v[78:79], v[78:79], v[82:83], v[86:87]
	v_pk_fma_f32 v[80:81], v[80:81], v[84:85], v[88:89]
	global_store_dwordx4 v[94:95], v[78:81], off offset:256
	global_load_dwordx4 v[78:81], v[112:113], off offset:320
	s_nop 0
	global_load_dwordx4 v[82:85], v[94:95], off offset:320
	s_waitcnt vmcnt(0)
	v_pk_fma_f32 v[74:75], v[74:75], v[78:79], v[82:83]
	v_pk_fma_f32 v[76:77], v[76:77], v[80:81], v[84:85]
	global_store_dwordx4 v[94:95], v[74:77], off offset:320
	global_load_dwordx4 v[74:77], v[112:113], off offset:384
	s_nop 0
	global_load_dwordx4 v[78:81], v[94:95], off offset:384
	s_waitcnt vmcnt(0)
	v_pk_fma_f32 v[70:71], v[70:71], v[74:75], v[78:79]
	v_pk_fma_f32 v[72:73], v[72:73], v[76:77], v[80:81]
	global_store_dwordx4 v[94:95], v[70:73], off offset:384
	global_load_dwordx4 v[70:73], v[112:113], off offset:448
	s_nop 0
	global_load_dwordx4 v[74:77], v[94:95], off offset:448
	s_waitcnt vmcnt(0)
	v_pk_fma_f32 v[62:63], v[62:63], v[70:71], v[74:75]
	v_pk_fma_f32 v[64:65], v[64:65], v[72:73], v[76:77]
	global_store_dwordx4 v[94:95], v[62:65], off offset:448
	s_nop 1
	v_or_b32_e32 v62, 32, v114
	v_cmp_lt_i32_e32 vcc, s97, v62
	v_add_u32_e32 v64, 0xffffc020, v114
	v_ashrrev_i32_e32 v63, 31, v62
	v_cndmask_b32_e64 v63, v63, 0, vcc
	v_cndmask_b32_e32 v62, v62, v64, vcc
	v_cndmask_b32_e64 v70, v115, 8, vcc
	v_cndmask_b32_e32 v65, v116, v117, vcc
	v_cndmask_b32_e32 v64, v118, v119, vcc
	v_lshlrev_b64 v[62:63], 12, v[62:63]
	v_lshl_add_u64 v[62:63], v[64:65], 0, v[62:63]
	v_mul_hi_i32_i24_e32 v65, 0x9000, v70
	v_mul_i32_i24_e32 v64, 0x9000, v70
	v_lshl_add_u64 v[64:65], s[14:15], 0, v[64:65]
	v_lshl_add_u64 v[78:79], v[64:65], 0, v[110:111]
	v_lshl_add_u64 v[62:63], v[62:63], 0, v[110:111]
	global_load_dwordx4 v[70:73], v[78:79], off
	global_load_dwordx4 v[74:77], v[62:63], off
	s_waitcnt vmcnt(0)
	v_pk_fma_f32 v[64:65], v[66:67], v[70:71], v[74:75]
	v_pk_fma_f32 v[66:67], v[68:69], v[72:73], v[76:77]
	global_store_dwordx4 v[62:63], v[64:67], off
	global_load_dwordx4 v[64:67], v[78:79], off offset:64
	s_nop 0
	global_load_dwordx4 v[68:71], v[62:63], off offset:64
	s_waitcnt vmcnt(0)
	v_pk_fma_f32 v[58:59], v[58:59], v[64:65], v[68:69]
	v_pk_fma_f32 v[60:61], v[60:61], v[66:67], v[70:71]
	global_store_dwordx4 v[62:63], v[58:61], off offset:64
	global_load_dwordx4 v[58:61], v[78:79], off offset:128
	s_nop 0
	global_load_dwordx4 v[64:67], v[62:63], off offset:128
	s_waitcnt vmcnt(0)
	v_pk_fma_f32 v[54:55], v[54:55], v[58:59], v[64:65]
	v_pk_fma_f32 v[56:57], v[56:57], v[60:61], v[66:67]
	global_store_dwordx4 v[62:63], v[54:57], off offset:128
	global_load_dwordx4 v[54:57], v[78:79], off offset:192
	s_nop 0
	global_load_dwordx4 v[58:61], v[62:63], off offset:192
	s_waitcnt vmcnt(0)
	v_pk_fma_f32 v[50:51], v[50:51], v[54:55], v[58:59]
	v_pk_fma_f32 v[52:53], v[52:53], v[56:57], v[60:61]
	global_store_dwordx4 v[62:63], v[50:53], off offset:192
	global_load_dwordx4 v[50:53], v[78:79], off offset:256
	s_nop 0
	global_load_dwordx4 v[54:57], v[62:63], off offset:256
	s_waitcnt vmcnt(0)
	v_pk_fma_f32 v[46:47], v[46:47], v[50:51], v[54:55]
	v_pk_fma_f32 v[48:49], v[48:49], v[52:53], v[56:57]
	global_store_dwordx4 v[62:63], v[46:49], off offset:256
	global_load_dwordx4 v[46:49], v[78:79], off offset:320
	s_nop 0
	global_load_dwordx4 v[50:53], v[62:63], off offset:320
	s_waitcnt vmcnt(0)
	v_pk_fma_f32 v[42:43], v[42:43], v[46:47], v[50:51]
	v_pk_fma_f32 v[44:45], v[44:45], v[48:49], v[52:53]
	global_store_dwordx4 v[62:63], v[42:45], off offset:320
	global_load_dwordx4 v[42:45], v[78:79], off offset:384
	s_nop 0
	global_load_dwordx4 v[46:49], v[62:63], off offset:384
	s_waitcnt vmcnt(0)
	v_pk_fma_f32 v[38:39], v[38:39], v[42:43], v[46:47]
	v_pk_fma_f32 v[40:41], v[40:41], v[44:45], v[48:49]
	global_store_dwordx4 v[62:63], v[38:41], off offset:384
	global_load_dwordx4 v[38:41], v[78:79], off offset:448
	s_nop 0
	global_load_dwordx4 v[42:45], v[62:63], off offset:448
	s_waitcnt vmcnt(0)
	v_pk_fma_f32 v[30:31], v[30:31], v[38:39], v[42:43]
	v_pk_fma_f32 v[32:33], v[32:33], v[40:41], v[44:45]
	global_store_dwordx4 v[62:63], v[30:33], off offset:448
	s_nop 1
	v_or_b32_e32 v30, 48, v114
	v_cmp_lt_i32_e32 vcc, s97, v30
	v_add_u32_e32 v32, 0xffffc030, v114
	v_ashrrev_i32_e32 v31, 31, v30
	v_cndmask_b32_e64 v31, v31, 0, vcc
	v_cndmask_b32_e32 v30, v30, v32, vcc
	v_cndmask_b32_e64 v38, v115, 8, vcc
	v_cndmask_b32_e32 v33, v116, v117, vcc
	v_cndmask_b32_e32 v32, v118, v119, vcc
	v_lshlrev_b64 v[30:31], 12, v[30:31]
	v_lshl_add_u64 v[30:31], v[32:33], 0, v[30:31]
	v_mul_hi_i32_i24_e32 v33, 0x9000, v38
	v_mul_i32_i24_e32 v32, 0x9000, v38
	v_lshl_add_u64 v[32:33], s[14:15], 0, v[32:33]
	v_lshl_add_u64 v[46:47], v[32:33], 0, v[110:111]
	v_lshl_add_u64 v[30:31], v[30:31], 0, v[110:111]
	global_load_dwordx4 v[38:41], v[46:47], off
	global_load_dwordx4 v[42:45], v[30:31], off
	s_waitcnt vmcnt(0)
	v_pk_fma_f32 v[32:33], v[34:35], v[38:39], v[42:43]
	v_pk_fma_f32 v[34:35], v[36:37], v[40:41], v[44:45]
	global_store_dwordx4 v[30:31], v[32:35], off
	global_load_dwordx4 v[32:35], v[46:47], off offset:64
	s_nop 0
	global_load_dwordx4 v[36:39], v[30:31], off offset:64
	s_waitcnt vmcnt(0)
	v_pk_fma_f32 v[26:27], v[26:27], v[32:33], v[36:37]
	v_pk_fma_f32 v[28:29], v[28:29], v[34:35], v[38:39]
	global_store_dwordx4 v[30:31], v[26:29], off offset:64
	global_load_dwordx4 v[26:29], v[46:47], off offset:128
	s_nop 0
	global_load_dwordx4 v[32:35], v[30:31], off offset:128
	s_waitcnt vmcnt(0)
	v_pk_fma_f32 v[22:23], v[22:23], v[26:27], v[32:33]
	v_pk_fma_f32 v[24:25], v[24:25], v[28:29], v[34:35]
	global_store_dwordx4 v[30:31], v[22:25], off offset:128
	global_load_dwordx4 v[22:25], v[46:47], off offset:192
	s_nop 0
	global_load_dwordx4 v[26:29], v[30:31], off offset:192
	s_waitcnt vmcnt(0)
	v_pk_fma_f32 v[18:19], v[18:19], v[22:23], v[26:27]
	v_pk_fma_f32 v[20:21], v[20:21], v[24:25], v[28:29]
	global_store_dwordx4 v[30:31], v[18:21], off offset:192
	global_load_dwordx4 v[18:21], v[46:47], off offset:256
	s_nop 0
	global_load_dwordx4 v[22:25], v[30:31], off offset:256
	s_waitcnt vmcnt(0)
	v_pk_fma_f32 v[14:15], v[14:15], v[18:19], v[22:23]
	v_pk_fma_f32 v[16:17], v[16:17], v[20:21], v[24:25]
	global_store_dwordx4 v[30:31], v[14:17], off offset:256
	global_load_dwordx4 v[14:17], v[46:47], off offset:320
	s_nop 0
	global_load_dwordx4 v[18:21], v[30:31], off offset:320
	s_waitcnt vmcnt(0)
	v_pk_fma_f32 v[10:11], v[10:11], v[14:15], v[18:19]
	v_pk_fma_f32 v[12:13], v[12:13], v[16:17], v[20:21]
	global_store_dwordx4 v[30:31], v[10:13], off offset:320
	global_load_dwordx4 v[10:13], v[46:47], off offset:384
	s_nop 0
	global_load_dwordx4 v[14:17], v[30:31], off offset:384
	s_waitcnt vmcnt(0)
	v_pk_fma_f32 v[6:7], v[6:7], v[10:11], v[14:15]
	v_pk_fma_f32 v[8:9], v[8:9], v[12:13], v[16:17]
	global_store_dwordx4 v[30:31], v[6:9], off offset:384
	global_load_dwordx4 v[6:9], v[46:47], off offset:448
	s_nop 0
	global_load_dwordx4 v[10:13], v[30:31], off offset:448
	s_waitcnt vmcnt(0)
	v_pk_fma_f32 v[2:3], v[2:3], v[6:7], v[10:11]
	v_pk_fma_f32 v[4:5], v[4:5], v[8:9], v[12:13]
	global_store_dwordx4 v[30:31], v[2:5], off offset:448
	s_add_i32 s19, s19, s18
	s_cmpk_gt_i32 s19, 0xff
	s_cbranch_scc0 .LBB0_1307

.LBB0_1440:
	s_ashr_i32 s2, s14, 31
	s_lshr_b32 s2, s2, 26
	s_add_i32 s2, s14, s2
	s_and_b32 s3, s2, 0xffffc0
	s_sub_i32 s3, s14, s3
	s_lshl_b32 s6, s3, 8
	v_add_u32_e32 v2, s6, v204
	v_ashrrev_i32_e32 v3, 31, v2
	v_lshlrev_b64 v[2:3], 11, v[2:3]
	v_lshl_add_u64 v[168:169], v[162:163], 0, v[2:3]
	s_lshl_b32 s2, s2, 2
	v_add_co_u32_e32 v56, vcc, s34, v168
	s_and_b32 s7, s2, 0xffffff00
	s_nop 0
	v_addc_co_u32_e32 v57, vcc, 0, v169, vcc
	v_add_u32_e32 v2, s7, v204
	v_add_co_u32_e32 v58, vcc, s35, v168
	v_ashrrev_i32_e32 v3, 31, v2
	s_nop 0
	v_addc_co_u32_e32 v59, vcc, 0, v169, vcc
	v_lshlrev_b64 v[2:3], 11, v[2:3]
	v_add_co_u32_e32 v60, vcc, s36, v168
	v_lshl_add_u64 v[170:171], v[164:165], 0, v[2:3]
	s_nop 0
	v_addc_co_u32_e32 v61, vcc, 0, v169, vcc
	v_add_co_u32_e32 v62, vcc, s35, v170
	global_load_dwordx4 v[24:27], v[56:57], off
	global_load_dwordx4 v[28:31], v[58:59], off
	v_addc_co_u32_e32 v63, vcc, 0, v171, vcc
	v_add_co_u32_e32 v64, vcc, s36, v170
	global_load_dwordx4 v[32:35], v[168:169], off
	global_load_dwordx4 v[36:39], v[170:171], off
	v_addc_co_u32_e32 v65, vcc, 0, v171, vcc
	v_add_co_u32_e32 v66, vcc, s34, v170
	global_load_dwordx4 v[40:43], v[62:63], off
	global_load_dwordx4 v[44:47], v[64:65], off
	v_addc_co_u32_e32 v67, vcc, 0, v171, vcc
	global_load_dwordx4 v[48:51], v[60:61], off
	global_load_dwordx4 v[52:55], v[66:67], off
	s_barrier
	global_load_dwordx4 v[114:117], v[168:169], off offset:128
	global_load_dwordx4 v[106:109], v[56:57], off offset:128
	global_load_dwordx4 v[110:113], v[58:59], off offset:128
	global_load_dwordx4 v[126:129], v[60:61], off offset:128
	global_load_dwordx4 v[122:125], v[170:171], off offset:128
	global_load_dwordx4 v[118:121], v[66:67], off offset:128
	global_load_dwordx4 v[134:137], v[62:63], off offset:128
	global_load_dwordx4 v[130:133], v[64:65], off offset:128
	v_readfirstlane_b32 s100, v172
	s_nop 0
	s_lshr_b32 m0, s100, 8
	v_readfirstlane_b32 vcc_lo, v168
	v_readfirstlane_b32 vcc_hi, v169
	v_readfirstlane_b32 s100, v170
	v_readfirstlane_b32 s101, v171
	s_nop 1
	v_subrev_u32_e32 v168, vcc_lo, v168
	v_subrev_u32_e32 v170, s100, v170
	v_mov_b32_e32 v2, 0
	s_mov_b32 s4, 0
	v_mov_b32_e32 v3, v2
	v_mov_b32_e32 v4, v2
	v_mov_b32_e32 v5, v2
	v_mov_b32_e32 v6, v2
	v_mov_b32_e32 v7, v2
	v_mov_b32_e32 v8, v2
	v_mov_b32_e32 v9, v2
	v_mov_b32_e32 v10, v2
	v_mov_b32_e32 v11, v2
	v_mov_b32_e32 v12, v2
	v_mov_b32_e32 v13, v2
	v_mov_b32_e32 v14, v2
	v_mov_b32_e32 v15, v2
	v_mov_b32_e32 v16, v2
	v_mov_b32_e32 v17, v2
	v_mov_b32_e32 v18, v2
	v_mov_b32_e32 v19, v2
	v_mov_b32_e32 v20, v2
	v_mov_b32_e32 v21, v2
	v_mov_b32_e32 v22, v2
	v_mov_b32_e32 v23, v2
	v_mov_b32_e32 v56, v2
	v_mov_b32_e32 v57, v2
	v_mov_b32_e32 v58, v2
	v_mov_b32_e32 v59, v2
	v_mov_b32_e32 v60, v2
	v_mov_b32_e32 v61, v2
	v_mov_b32_e32 v62, v2
	v_mov_b32_e32 v63, v2
	v_mov_b32_e32 v64, v2
	v_mov_b32_e32 v65, v2
	v_mov_b32_e32 v66, v2
	v_mov_b32_e32 v67, v2
	v_mov_b32_e32 v68, v2
	v_mov_b32_e32 v69, v2
	v_mov_b32_e32 v70, v2
	v_mov_b32_e32 v71, v2
	v_mov_b32_e32 v72, v2
	v_mov_b32_e32 v73, v2
	v_mov_b32_e32 v74, v2
	v_mov_b32_e32 v75, v2
	v_mov_b32_e32 v76, v2
	v_mov_b32_e32 v77, v2
	v_mov_b32_e32 v78, v2
	v_mov_b32_e32 v79, v2
	v_mov_b32_e32 v80, v2
	v_mov_b32_e32 v81, v2
	v_mov_b32_e32 v82, v2
	v_mov_b32_e32 v83, v2
	v_mov_b32_e32 v84, v2
	v_mov_b32_e32 v85, v2
	s_waitcnt vmcnt(13)
	ds_write_b128 v166, v[32:35]
	s_waitcnt vmcnt(12)
	ds_write_b128 v166, v[36:39] offset:32768
	s_waitcnt vmcnt(11)
	ds_write_b128 v166, v[40:43] offset:49152
	s_waitcnt vmcnt(10)
	ds_write_b128 v166, v[44:47] offset:57344
	ds_write_b128 v166, v[24:27] offset:8192
	ds_write_b128 v166, v[28:31] offset:16384
	s_waitcnt vmcnt(9)
	ds_write_b128 v166, v[48:51] offset:24576
	s_waitcnt vmcnt(8)
	ds_write_b128 v166, v[52:55] offset:40960
	v_mov_b32_e32 v24, v2
	v_mov_b32_e32 v25, v2
	v_mov_b32_e32 v26, v2
	v_mov_b32_e32 v27, v2
	v_mov_b32_e32 v28, v2
	v_mov_b32_e32 v29, v2
	v_mov_b32_e32 v30, v2
	v_mov_b32_e32 v31, v2
	v_mov_b32_e32 v32, v2
	v_mov_b32_e32 v33, v2
	v_mov_b32_e32 v34, v2
	v_mov_b32_e32 v35, v2
	v_mov_b32_e32 v36, v2
	v_mov_b32_e32 v37, v2
	v_mov_b32_e32 v38, v2
	v_mov_b32_e32 v39, v2
	v_mov_b32_e32 v40, v2
	v_mov_b32_e32 v41, v2
	v_mov_b32_e32 v42, v2
	v_mov_b32_e32 v43, v2
	v_mov_b32_e32 v44, v2
	v_mov_b32_e32 v45, v2
	v_mov_b32_e32 v46, v2
	v_mov_b32_e32 v47, v2
	v_mov_b32_e32 v48, v2
	v_mov_b32_e32 v49, v2
	v_mov_b32_e32 v50, v2
	v_mov_b32_e32 v51, v2
	v_mov_b32_e32 v52, v2
	v_mov_b32_e32 v53, v2
	v_mov_b32_e32 v54, v2
	v_mov_b32_e32 v55, v2
	v_mov_b32_e32 v86, v2
	v_mov_b32_e32 v87, v2
	v_mov_b32_e32 v88, v2
	v_mov_b32_e32 v89, v2
	v_mov_b32_e32 v90, v2
	v_mov_b32_e32 v91, v2
	v_mov_b32_e32 v92, v2
	v_mov_b32_e32 v93, v2
	v_mov_b32_e32 v94, v2
	v_mov_b32_e32 v95, v2
	v_mov_b32_e32 v96, v2
	v_mov_b32_e32 v97, v2
	v_mov_b32_e32 v98, v2
	v_mov_b32_e32 v99, v2
	v_mov_b32_e32 v100, v2
	v_mov_b32_e32 v101, v2
	v_mov_b32_e32 v102, v2
	v_mov_b32_e32 v103, v2
	v_mov_b32_e32 v104, v2
	v_mov_b32_e32 v105, v2
	v_mov_b32_e32 v138, v2
	v_mov_b32_e32 v139, v2
	v_mov_b32_e32 v140, v2
	v_mov_b32_e32 v141, v2
	v_mov_b32_e32 v142, v2
	v_mov_b32_e32 v143, v2
	v_mov_b32_e32 v144, v2
	v_mov_b32_e32 v145, v2
	v_mov_b32_e32 v146, v2
	v_mov_b32_e32 v147, v2
	v_mov_b32_e32 v148, v2
	v_mov_b32_e32 v149, v2
	v_mov_b32_e32 v150, v2
	v_mov_b32_e32 v151, v2
	v_mov_b32_e32 v152, v2
	v_mov_b32_e32 v153, v2
	v_mov_b32_e32 v154, v2
	v_mov_b32_e32 v155, v2
	v_mov_b32_e32 v156, v2
	v_mov_b32_e32 v157, v2
	v_mov_b32_e32 v158, v2
	v_mov_b32_e32 v159, v2
	v_mov_b32_e32 v160, v2
	v_mov_b32_e32 v161, v2
	s_waitcnt lgkmcnt(0)
	s_barrier
	s_cmp_lg_u32 m0, 0
	s_cbranch_scc1 .Lg1_1441
.LBB0_1441:
	s_bitcmp1_b32 s4, 0
	s_cselect_b32 s2, 0x12000, 0
	v_or_b32_e32 v218, s2, v206
	v_add_u32_e32 v214, v218, v0
	v_add_u32_e32 v246, v218, v167
	ds_read_b128 v[184:187], v214
	ds_read_b128 v[218:221], v246 offset:32768
	ds_read_b128 v[198:201], v214 offset:2048
	ds_read_b128 v[210:213], v214 offset:4096
	ds_read_b128 v[214:217], v214 offset:6144
	ds_read_b128 v[222:225], v246 offset:34816
	ds_read_b128 v[226:229], v246 offset:36864
	ds_read_b128 v[230:233], v246 offset:38912
	ds_read_b128 v[234:237], v246 offset:40960
	ds_read_b128 v[238:241], v246 offset:43008
	ds_read_b128 v[242:245], v246 offset:45056
	ds_read_b128 v[246:249], v246 offset:47104
	s_add_i32 s10, s4, 1
	s_bitcmp1_b32 s10, 0
	s_cselect_b32 s3, 0x12000, 0
	v_add_u32_e32 v171, s3, v166
	v_xor_b32_e32 v169, 64, v206
	v_add3_u32 v169, s2, v167, v169
	s_waitcnt lgkmcnt(10)
	v_mfma_f32_16x16x32_bf16 v[158:161], v[218:221], v[184:187], v[158:161]
	s_waitcnt lgkmcnt(9)
	v_mfma_f32_16x16x32_bf16 v[94:97], v[218:221], v[198:201], v[94:97]
	s_waitcnt lgkmcnt(8)
	v_mfma_f32_16x16x32_bf16 v[62:65], v[218:221], v[210:213], v[62:65]
	s_waitcnt lgkmcnt(7)
	v_mfma_f32_16x16x32_bf16 v[30:33], v[218:221], v[214:217], v[30:33]
	ds_read_b128 v[218:221], v169 offset:32768
	s_waitcnt lgkmcnt(7)
	v_mfma_f32_16x16x32_bf16 v[154:157], v[222:225], v[184:187], v[154:157]
	v_mfma_f32_16x16x32_bf16 v[90:93], v[222:225], v[198:201], v[90:93]
	v_mfma_f32_16x16x32_bf16 v[58:61], v[222:225], v[210:213], v[58:61]
	v_mfma_f32_16x16x32_bf16 v[26:29], v[222:225], v[214:217], v[26:29]
	ds_read_b128 v[222:225], v169 offset:34816
	s_waitcnt lgkmcnt(7)
	v_mfma_f32_16x16x32_bf16 v[150:153], v[226:229], v[184:187], v[150:153]
	v_mfma_f32_16x16x32_bf16 v[86:89], v[226:229], v[198:201], v[86:89]
	v_mfma_f32_16x16x32_bf16 v[54:57], v[226:229], v[210:213], v[54:57]
	v_mfma_f32_16x16x32_bf16 v[22:25], v[226:229], v[214:217], v[22:25]
	ds_read_b128 v[226:229], v169 offset:36864
	s_waitcnt lgkmcnt(7)
	v_mfma_f32_16x16x32_bf16 v[146:149], v[230:233], v[184:187], v[146:149]
	v_mfma_f32_16x16x32_bf16 v[82:85], v[230:233], v[198:201], v[82:85]
	v_mfma_f32_16x16x32_bf16 v[50:53], v[230:233], v[210:213], v[50:53]
	v_mfma_f32_16x16x32_bf16 v[18:21], v[230:233], v[214:217], v[18:21]
	ds_read_b128 v[230:233], v169 offset:38912
	s_waitcnt lgkmcnt(7)
	v_mfma_f32_16x16x32_bf16 v[142:145], v[234:237], v[184:187], v[142:145]
	v_mfma_f32_16x16x32_bf16 v[78:81], v[234:237], v[198:201], v[78:81]
	v_mfma_f32_16x16x32_bf16 v[46:49], v[234:237], v[210:213], v[46:49]
	v_mfma_f32_16x16x32_bf16 v[14:17], v[234:237], v[214:217], v[14:17]
	ds_read_b128 v[234:237], v169 offset:40960
	s_waitcnt lgkmcnt(7)
	v_mfma_f32_16x16x32_bf16 v[138:141], v[238:241], v[184:187], v[138:141]
	v_mfma_f32_16x16x32_bf16 v[74:77], v[238:241], v[198:201], v[74:77]
	v_mfma_f32_16x16x32_bf16 v[42:45], v[238:241], v[210:213], v[42:45]
	v_mfma_f32_16x16x32_bf16 v[10:13], v[238:241], v[214:217], v[10:13]
	ds_read_b128 v[238:241], v169 offset:43008
	s_waitcnt lgkmcnt(7)
	v_mfma_f32_16x16x32_bf16 v[102:105], v[242:245], v[184:187], v[102:105]
	v_mfma_f32_16x16x32_bf16 v[70:73], v[242:245], v[198:201], v[70:73]
	v_mfma_f32_16x16x32_bf16 v[38:41], v[242:245], v[210:213], v[38:41]
	v_mfma_f32_16x16x32_bf16 v[6:9], v[242:245], v[214:217], v[6:9]
	ds_read_b128 v[242:245], v169 offset:45056
	s_waitcnt lgkmcnt(7)
	v_mfma_f32_16x16x32_bf16 v[98:101], v[246:249], v[184:187], v[98:101]
	v_mfma_f32_16x16x32_bf16 v[66:69], v[246:249], v[198:201], v[66:69]
	v_xor_b32_e32 v169, 64, v206
	v_add3_u32 v169, s2, v0, v169
	ds_read_b128 v[184:187], v169
	ds_read_b128 v[198:201], v169 offset:2048
	v_mfma_f32_16x16x32_bf16 v[34:37], v[246:249], v[210:213], v[34:37]
	ds_read_b128 v[210:213], v169 offset:4096
	v_mfma_f32_16x16x32_bf16 v[2:5], v[246:249], v[214:217], v[2:5]
	ds_read_b128 v[214:217], v169 offset:6144
	v_xor_b32_e32 v169, 64, v206
	v_add3_u32 v169, s2, v167, v169
	ds_read_b128 v[246:249], v169 offset:47104
	s_waitcnt lgkmcnt(4)
	v_mfma_f32_16x16x32_bf16 v[158:161], v[218:221], v[184:187], v[158:161]
	s_waitcnt lgkmcnt(3)
	v_mfma_f32_16x16x32_bf16 v[94:97], v[218:221], v[198:201], v[94:97]
	s_waitcnt lgkmcnt(2)
	v_mfma_f32_16x16x32_bf16 v[62:65], v[218:221], v[210:213], v[62:65]
	s_waitcnt lgkmcnt(1)
	v_mfma_f32_16x16x32_bf16 v[30:33], v[218:221], v[214:217], v[30:33]
	s_waitcnt vmcnt(7)
	ds_write_b128 v171, v[114:117]
	v_mfma_f32_16x16x32_bf16 v[154:157], v[222:225], v[184:187], v[154:157]
	v_mfma_f32_16x16x32_bf16 v[90:93], v[222:225], v[198:201], v[90:93]
	global_load_dwordx4 v[114:117], v168, vcc offset:256
	v_mfma_f32_16x16x32_bf16 v[58:61], v[222:225], v[210:213], v[58:61]
	v_mfma_f32_16x16x32_bf16 v[26:29], v[222:225], v[214:217], v[26:29]
	s_waitcnt vmcnt(7)
	ds_write_b128 v171, v[106:109] offset:8192
	v_mfma_f32_16x16x32_bf16 v[150:153], v[226:229], v[184:187], v[150:153]
	v_mfma_f32_16x16x32_bf16 v[86:89], v[226:229], v[198:201], v[86:89]
	v_add_u32_e32 v106, s34, v168
	global_load_dwordx4 v[106:109], v106, vcc offset:256
	v_mfma_f32_16x16x32_bf16 v[54:57], v[226:229], v[210:213], v[54:57]
	v_mfma_f32_16x16x32_bf16 v[22:25], v[226:229], v[214:217], v[22:25]
	s_waitcnt vmcnt(7)
	ds_write_b128 v171, v[110:113] offset:16384
	v_mfma_f32_16x16x32_bf16 v[146:149], v[230:233], v[184:187], v[146:149]
	v_mfma_f32_16x16x32_bf16 v[82:85], v[230:233], v[198:201], v[82:85]
	v_add_u32_e32 v110, s35, v168
	global_load_dwordx4 v[110:113], v110, vcc offset:256
	v_mfma_f32_16x16x32_bf16 v[50:53], v[230:233], v[210:213], v[50:53]
	v_mfma_f32_16x16x32_bf16 v[18:21], v[230:233], v[214:217], v[18:21]
	s_waitcnt vmcnt(7)
	ds_write_b128 v171, v[126:129] offset:24576
	v_mfma_f32_16x16x32_bf16 v[142:145], v[234:237], v[184:187], v[142:145]
	v_mfma_f32_16x16x32_bf16 v[78:81], v[234:237], v[198:201], v[78:81]
	v_add_u32_e32 v126, s36, v168
	global_load_dwordx4 v[126:129], v126, vcc offset:256
	v_mfma_f32_16x16x32_bf16 v[46:49], v[234:237], v[210:213], v[46:49]
	v_mfma_f32_16x16x32_bf16 v[14:17], v[234:237], v[214:217], v[14:17]
	s_waitcnt vmcnt(7)
	ds_write_b128 v171, v[122:125] offset:32768
	v_mfma_f32_16x16x32_bf16 v[138:141], v[238:241], v[184:187], v[138:141]
	v_mfma_f32_16x16x32_bf16 v[74:77], v[238:241], v[198:201], v[74:77]
	global_load_dwordx4 v[122:125], v170, s[100:101] offset:256
	v_mfma_f32_16x16x32_bf16 v[42:45], v[238:241], v[210:213], v[42:45]
	v_mfma_f32_16x16x32_bf16 v[10:13], v[238:241], v[214:217], v[10:13]
	s_waitcnt vmcnt(7)
	ds_write_b128 v171, v[118:121] offset:40960
	v_mfma_f32_16x16x32_bf16 v[102:105], v[242:245], v[184:187], v[102:105]
	v_mfma_f32_16x16x32_bf16 v[70:73], v[242:245], v[198:201], v[70:73]
	v_add_u32_e32 v118, s34, v170
	global_load_dwordx4 v[118:121], v118, s[100:101] offset:256
	v_mfma_f32_16x16x32_bf16 v[38:41], v[242:245], v[210:213], v[38:41]
	v_mfma_f32_16x16x32_bf16 v[6:9], v[242:245], v[214:217], v[6:9]
	s_waitcnt vmcnt(7)
	ds_write_b128 v171, v[134:137] offset:49152
	s_waitcnt lgkmcnt(7)
	v_mfma_f32_16x16x32_bf16 v[98:101], v[246:249], v[184:187], v[98:101]
	v_mfma_f32_16x16x32_bf16 v[66:69], v[246:249], v[198:201], v[66:69]
	v_add_u32_e32 v134, s35, v170
	global_load_dwordx4 v[134:137], v134, s[100:101] offset:256
	v_mfma_f32_16x16x32_bf16 v[34:37], v[246:249], v[210:213], v[34:37]
	v_mfma_f32_16x16x32_bf16 v[2:5], v[246:249], v[214:217], v[2:5]
	s_waitcnt vmcnt(7)
	ds_write_b128 v171, v[130:133] offset:57344
	v_add_u32_e32 v130, s36, v170
	global_load_dwordx4 v[130:133], v130, s[100:101] offset:256
	v_add_u32_e32 v168, 0x80, v168
	v_add_u32_e32 v170, 0x80, v170
	s_waitcnt lgkmcnt(0)
	s_barrier
	s_cmp_eq_u32 s10, 16
	s_mov_b32 s4, s10
	s_cbranch_scc0 .LBB0_1441
	s_branch .Lkdone_1441

.Lg1loop_1441:
	s_bitcmp1_b32 s4, 0
	s_cselect_b32 s2, 0x12000, 0
	v_or_b32_e32 v218, s2, v206
	v_add_u32_e32 v214, v218, v0
	v_add_u32_e32 v246, v218, v167
	ds_read_b128 v[184:187], v214
	ds_read_b128 v[218:221], v246 offset:32768
	ds_read_b128 v[198:201], v214 offset:2048
	ds_read_b128 v[210:213], v214 offset:4096
	ds_read_b128 v[214:217], v214 offset:6144
	ds_read_b128 v[222:225], v246 offset:34816
	ds_read_b128 v[226:229], v246 offset:36864
	ds_read_b128 v[230:233], v246 offset:38912
	ds_read_b128 v[234:237], v246 offset:40960
	ds_read_b128 v[238:241], v246 offset:43008
	ds_read_b128 v[242:245], v246 offset:45056
	ds_read_b128 v[246:249], v246 offset:47104
	s_add_i32 s10, s4, 1
	s_bitcmp1_b32 s10, 0
	s_cselect_b32 s3, 0x12000, 0
	v_add_u32_e32 v171, s2, v166
	v_xor_b32_e32 v169, 64, v206
	v_add3_u32 v169, s2, v167, v169
	s_waitcnt lgkmcnt(10)
	v_mfma_f32_16x16x32_bf16 v[158:161], v[218:221], v[184:187], v[158:161]
	s_waitcnt lgkmcnt(9)
	v_mfma_f32_16x16x32_bf16 v[94:97], v[218:221], v[198:201], v[94:97]
	s_waitcnt lgkmcnt(8)
	v_mfma_f32_16x16x32_bf16 v[62:65], v[218:221], v[210:213], v[62:65]
	s_waitcnt lgkmcnt(7)
	v_mfma_f32_16x16x32_bf16 v[30:33], v[218:221], v[214:217], v[30:33]
	ds_read_b128 v[218:221], v169 offset:32768
	s_waitcnt lgkmcnt(7)
	v_mfma_f32_16x16x32_bf16 v[154:157], v[222:225], v[184:187], v[154:157]
	v_mfma_f32_16x16x32_bf16 v[90:93], v[222:225], v[198:201], v[90:93]
	v_mfma_f32_16x16x32_bf16 v[58:61], v[222:225], v[210:213], v[58:61]
	v_mfma_f32_16x16x32_bf16 v[26:29], v[222:225], v[214:217], v[26:29]
	ds_read_b128 v[222:225], v169 offset:34816
	s_waitcnt lgkmcnt(7)
	v_mfma_f32_16x16x32_bf16 v[150:153], v[226:229], v[184:187], v[150:153]
	v_mfma_f32_16x16x32_bf16 v[86:89], v[226:229], v[198:201], v[86:89]
	v_mfma_f32_16x16x32_bf16 v[54:57], v[226:229], v[210:213], v[54:57]
	v_mfma_f32_16x16x32_bf16 v[22:25], v[226:229], v[214:217], v[22:25]
	ds_read_b128 v[226:229], v169 offset:36864
	s_waitcnt lgkmcnt(7)
	v_mfma_f32_16x16x32_bf16 v[146:149], v[230:233], v[184:187], v[146:149]
	v_mfma_f32_16x16x32_bf16 v[82:85], v[230:233], v[198:201], v[82:85]
	v_mfma_f32_16x16x32_bf16 v[50:53], v[230:233], v[210:213], v[50:53]
	v_mfma_f32_16x16x32_bf16 v[18:21], v[230:233], v[214:217], v[18:21]
	ds_read_b128 v[230:233], v169 offset:38912
	s_waitcnt lgkmcnt(7)
	v_mfma_f32_16x16x32_bf16 v[142:145], v[234:237], v[184:187], v[142:145]
	v_mfma_f32_16x16x32_bf16 v[78:81], v[234:237], v[198:201], v[78:81]
	v_mfma_f32_16x16x32_bf16 v[46:49], v[234:237], v[210:213], v[46:49]
	v_mfma_f32_16x16x32_bf16 v[14:17], v[234:237], v[214:217], v[14:17]
	ds_read_b128 v[234:237], v169 offset:40960
	s_waitcnt lgkmcnt(7)
	v_mfma_f32_16x16x32_bf16 v[138:141], v[238:241], v[184:187], v[138:141]
	v_mfma_f32_16x16x32_bf16 v[74:77], v[238:241], v[198:201], v[74:77]
	v_mfma_f32_16x16x32_bf16 v[42:45], v[238:241], v[210:213], v[42:45]
	v_mfma_f32_16x16x32_bf16 v[10:13], v[238:241], v[214:217], v[10:13]
	ds_read_b128 v[238:241], v169 offset:43008
	s_waitcnt lgkmcnt(7)
	v_mfma_f32_16x16x32_bf16 v[102:105], v[242:245], v[184:187], v[102:105]
	v_mfma_f32_16x16x32_bf16 v[70:73], v[242:245], v[198:201], v[70:73]
	v_mfma_f32_16x16x32_bf16 v[38:41], v[242:245], v[210:213], v[38:41]
	v_mfma_f32_16x16x32_bf16 v[6:9], v[242:245], v[214:217], v[6:9]
	ds_read_b128 v[242:245], v169 offset:45056
	s_waitcnt lgkmcnt(7)
	v_mfma_f32_16x16x32_bf16 v[98:101], v[246:249], v[184:187], v[98:101]
	v_mfma_f32_16x16x32_bf16 v[66:69], v[246:249], v[198:201], v[66:69]
	v_xor_b32_e32 v169, 64, v206
	v_add3_u32 v169, s2, v0, v169
	ds_read_b128 v[184:187], v169
	ds_read_b128 v[198:201], v169 offset:2048
	v_mfma_f32_16x16x32_bf16 v[34:37], v[246:249], v[210:213], v[34:37]
	ds_read_b128 v[210:213], v169 offset:4096
	v_mfma_f32_16x16x32_bf16 v[2:5], v[246:249], v[214:217], v[2:5]
	ds_read_b128 v[214:217], v169 offset:6144
	v_xor_b32_e32 v169, 64, v206
	v_add3_u32 v169, s2, v167, v169
	ds_read_b128 v[246:249], v169 offset:47104
	s_waitcnt lgkmcnt(0)
	s_barrier
	s_waitcnt lgkmcnt(4)
	v_mfma_f32_16x16x32_bf16 v[158:161], v[218:221], v[184:187], v[158:161]
	s_waitcnt lgkmcnt(3)
	v_mfma_f32_16x16x32_bf16 v[94:97], v[218:221], v[198:201], v[94:97]
	s_waitcnt lgkmcnt(2)
	v_mfma_f32_16x16x32_bf16 v[62:65], v[218:221], v[210:213], v[62:65]
	s_waitcnt lgkmcnt(1)
	v_mfma_f32_16x16x32_bf16 v[30:33], v[218:221], v[214:217], v[30:33]
	s_waitcnt vmcnt(7)
	ds_write_b128 v171, v[114:117]
	v_mfma_f32_16x16x32_bf16 v[154:157], v[222:225], v[184:187], v[154:157]
	v_mfma_f32_16x16x32_bf16 v[90:93], v[222:225], v[198:201], v[90:93]
	global_load_dwordx4 v[114:117], v168, vcc offset:256
	v_mfma_f32_16x16x32_bf16 v[58:61], v[222:225], v[210:213], v[58:61]
	v_mfma_f32_16x16x32_bf16 v[26:29], v[222:225], v[214:217], v[26:29]
	s_waitcnt vmcnt(7)
	ds_write_b128 v171, v[106:109] offset:8192
	v_mfma_f32_16x16x32_bf16 v[150:153], v[226:229], v[184:187], v[150:153]
	v_mfma_f32_16x16x32_bf16 v[86:89], v[226:229], v[198:201], v[86:89]
	v_add_u32_e32 v106, s34, v168
	global_load_dwordx4 v[106:109], v106, vcc offset:256
	v_mfma_f32_16x16x32_bf16 v[54:57], v[226:229], v[210:213], v[54:57]
	v_mfma_f32_16x16x32_bf16 v[22:25], v[226:229], v[214:217], v[22:25]
	s_waitcnt vmcnt(7)
	ds_write_b128 v171, v[110:113] offset:16384
	v_mfma_f32_16x16x32_bf16 v[146:149], v[230:233], v[184:187], v[146:149]
	v_mfma_f32_16x16x32_bf16 v[82:85], v[230:233], v[198:201], v[82:85]
	v_add_u32_e32 v110, s35, v168
	global_load_dwordx4 v[110:113], v110, vcc offset:256
	v_mfma_f32_16x16x32_bf16 v[50:53], v[230:233], v[210:213], v[50:53]
	v_mfma_f32_16x16x32_bf16 v[18:21], v[230:233], v[214:217], v[18:21]
	s_waitcnt vmcnt(7)
	ds_write_b128 v171, v[126:129] offset:24576
	v_mfma_f32_16x16x32_bf16 v[142:145], v[234:237], v[184:187], v[142:145]
	v_mfma_f32_16x16x32_bf16 v[78:81], v[234:237], v[198:201], v[78:81]
	v_add_u32_e32 v126, s36, v168
	global_load_dwordx4 v[126:129], v126, vcc offset:256
	v_mfma_f32_16x16x32_bf16 v[46:49], v[234:237], v[210:213], v[46:49]
	v_mfma_f32_16x16x32_bf16 v[14:17], v[234:237], v[214:217], v[14:17]
	s_waitcnt vmcnt(7)
	ds_write_b128 v171, v[122:125] offset:32768
	v_mfma_f32_16x16x32_bf16 v[138:141], v[238:241], v[184:187], v[138:141]
	v_mfma_f32_16x16x32_bf16 v[74:77], v[238:241], v[198:201], v[74:77]
	global_load_dwordx4 v[122:125], v170, s[100:101] offset:256
	v_mfma_f32_16x16x32_bf16 v[42:45], v[238:241], v[210:213], v[42:45]
	v_mfma_f32_16x16x32_bf16 v[10:13], v[238:241], v[214:217], v[10:13]
	s_waitcnt vmcnt(7)
	ds_write_b128 v171, v[118:121] offset:40960
	v_mfma_f32_16x16x32_bf16 v[102:105], v[242:245], v[184:187], v[102:105]
	v_mfma_f32_16x16x32_bf16 v[70:73], v[242:245], v[198:201], v[70:73]
	v_add_u32_e32 v118, s34, v170
	global_load_dwordx4 v[118:121], v118, s[100:101] offset:256
	v_mfma_f32_16x16x32_bf16 v[38:41], v[242:245], v[210:213], v[38:41]
	v_mfma_f32_16x16x32_bf16 v[6:9], v[242:245], v[214:217], v[6:9]
	s_waitcnt vmcnt(7)
	ds_write_b128 v171, v[134:137] offset:49152
	s_waitcnt lgkmcnt(7)
	v_mfma_f32_16x16x32_bf16 v[98:101], v[246:249], v[184:187], v[98:101]
	v_mfma_f32_16x16x32_bf16 v[66:69], v[246:249], v[198:201], v[66:69]
	v_add_u32_e32 v134, s35, v170
	global_load_dwordx4 v[134:137], v134, s[100:101] offset:256
	v_mfma_f32_16x16x32_bf16 v[34:37], v[246:249], v[210:213], v[34:37]
	v_mfma_f32_16x16x32_bf16 v[2:5], v[246:249], v[214:217], v[2:5]
	s_waitcnt vmcnt(7)
	ds_write_b128 v171, v[130:133] offset:57344
	v_add_u32_e32 v130, s36, v170
	global_load_dwordx4 v[130:133], v130, s[100:101] offset:256
	v_add_u32_e32 v168, 0x80, v168
	v_add_u32_e32 v170, 0x80, v170
	s_cmp_eq_u32 s10, 16
	s_mov_b32 s4, s10
	s_cbranch_scc0 .Lg1loop_1441
	s_waitcnt lgkmcnt(0)
.Lkdone_1441:
	s_waitcnt vmcnt(4)
	v_mul_f32_e32 v109, 0xbfb8aa3b, v158
	v_exp_f32_e32 v109, v109
	s_waitcnt vmcnt(3)
	v_mul_f32_e32 v111, 0xbfb8aa3b, v159
	v_exp_f32_e32 v111, v111
	v_mul_f32_e32 v115, 0xbfb8aa3b, v161
	v_add_f32_e32 v109, 1.0, v109
	v_rcp_f32_e32 v114, v109
	v_add_f32_e32 v109, 1.0, v111
	v_mul_f32_e32 v111, 0xbfb8aa3b, v160
	v_exp_f32_e32 v111, v111
	v_exp_f32_e32 v117, v115
	v_rcp_f32_e32 v116, v109
	s_waitcnt vmcnt(2)
	v_mov_b32_e32 v118, v158
	v_add_f32_e32 v109, 1.0, v111
	v_rcp_f32_e32 v115, v109
	v_add_f32_e32 v109, 1.0, v117
	v_rcp_f32_e32 v117, v109
	v_mov_b32_e32 v119, v160
	v_pk_mul_f32 v[114:115], v[118:119], v[114:115]
	v_mov_b32_e32 v118, v154
	v_mov_b32_e32 v119, v156
	v_mov_b32_e32 v160, v159
	v_pk_mul_f32 v[114:115], v[118:119], v[114:115]
	v_pk_mul_f32 v[116:117], v[160:161], v[116:117]
	v_mov_b32_e32 v156, v155
	v_pk_mul_f32 v[116:117], v[156:157], v[116:117]
	v_and_b32_sdwa v111, v115, v177 dst_sel:DWORD dst_unused:UNUSED_PAD src0_sel:WORD_1 src1_sel:DWORD
	v_and_b32_sdwa v118, v114, v177 dst_sel:DWORD dst_unused:UNUSED_PAD src0_sel:WORD_1 src1_sel:DWORD
	v_add3_u32 v111, v115, v111, s28
	v_and_b32_sdwa v115, v117, v177 dst_sel:DWORD dst_unused:UNUSED_PAD src0_sel:WORD_1 src1_sel:DWORD
	v_add3_u32 v114, v114, v118, s28
	v_and_b32_sdwa v118, v116, v177 dst_sel:DWORD dst_unused:UNUSED_PAD src0_sel:WORD_1 src1_sel:DWORD
	v_add3_u32 v115, v117, v115, s28
	v_or_b32_e32 v106, s7, v207
	v_add3_u32 v116, v116, v118, s28
	v_and_b32_e32 v115, 0xffff0000, v115
	v_ashrrev_i32_e32 v106, 1, v106
	v_and_b32_e32 v116, 0xffff0000, v116
	v_or_b32_sdwa v115, v115, v111 dst_sel:DWORD dst_unused:UNUSED_PAD src0_sel:DWORD src1_sel:WORD_1
	v_mul_f32_e32 v111, 0xbfb8aa3b, v150
	v_or_b32_e32 v108, v106, v208
	v_or_b32_sdwa v114, v116, v114 dst_sel:DWORD dst_unused:UNUSED_PAD src0_sel:DWORD src1_sel:WORD_1
	v_exp_f32_e32 v111, v111
	v_mul_f32_e32 v116, 0xbfb8aa3b, v151
	v_add_u32_e32 v110, s6, v205
	v_mov_b64_e32 v[106:107], s[12:13]
	v_ashrrev_i32_e32 v109, 31, v108
	v_exp_f32_e32 v116, v116
	v_mad_i64_i32 v[112:113], s[6:7], v110, s52, v[106:107]
	v_lshlrev_b64 v[108:109], 1, v[108:109]
	v_lshl_add_u64 v[112:113], v[112:113], 0, v[108:109]
	s_waitcnt vmcnt(0)
	global_store_dwordx2 v[112:113], v[114:115], off
	v_add_f32_e32 v111, 1.0, v111
	v_mul_f32_e32 v115, 0xbfb8aa3b, v152
	v_rcp_f32_e32 v114, v111
	v_add_f32_e32 v111, 1.0, v116
	v_exp_f32_e32 v115, v115
	v_mul_f32_e32 v116, 0xbfb8aa3b, v153
	v_exp_f32_e32 v117, v116
	v_rcp_f32_e32 v116, v111
	v_add_f32_e32 v111, 1.0, v115
	v_rcp_f32_e32 v115, v111
	v_add_f32_e32 v111, 1.0, v117
	v_rcp_f32_e32 v117, v111
	v_mov_b32_e32 v118, v150
	v_mov_b32_e32 v119, v152
	v_pk_mul_f32 v[114:115], v[118:119], v[114:115]
	v_mov_b32_e32 v118, v146
	v_mov_b32_e32 v119, v148
	v_mov_b32_e32 v152, v151
	v_pk_mul_f32 v[114:115], v[118:119], v[114:115]
	v_pk_mul_f32 v[116:117], v[152:153], v[116:117]
	v_mov_b32_e32 v148, v147
	v_pk_mul_f32 v[116:117], v[148:149], v[116:117]
	v_and_b32_sdwa v111, v115, v177 dst_sel:DWORD dst_unused:UNUSED_PAD src0_sel:WORD_1 src1_sel:DWORD
	v_and_b32_sdwa v118, v114, v177 dst_sel:DWORD dst_unused:UNUSED_PAD src0_sel:WORD_1 src1_sel:DWORD
	v_add3_u32 v111, v115, v111, s28
	v_and_b32_sdwa v115, v117, v177 dst_sel:DWORD dst_unused:UNUSED_PAD src0_sel:WORD_1 src1_sel:DWORD
	v_add3_u32 v114, v114, v118, s28
	v_and_b32_sdwa v118, v116, v177 dst_sel:DWORD dst_unused:UNUSED_PAD src0_sel:WORD_1 src1_sel:DWORD
	v_add3_u32 v115, v117, v115, s28
	v_add3_u32 v116, v116, v118, s28
	v_and_b32_e32 v115, 0xffff0000, v115
	v_and_b32_e32 v116, 0xffff0000, v116
	v_or_b32_sdwa v115, v115, v111 dst_sel:DWORD dst_unused:UNUSED_PAD src0_sel:DWORD src1_sel:WORD_1
	v_mul_f32_e32 v111, 0xbfb8aa3b, v142
	v_or_b32_sdwa v114, v116, v114 dst_sel:DWORD dst_unused:UNUSED_PAD src0_sel:DWORD src1_sel:WORD_1
	v_exp_f32_e32 v111, v111
	v_mul_f32_e32 v116, 0xbfb8aa3b, v143
	v_exp_f32_e32 v116, v116
	global_store_dwordx2 v[112:113], v[114:115], off offset:32
	v_add_f32_e32 v111, 1.0, v111
	v_mul_f32_e32 v115, 0xbfb8aa3b, v144
	v_rcp_f32_e32 v114, v111
	v_add_f32_e32 v111, 1.0, v116
	v_exp_f32_e32 v115, v115
	v_mul_f32_e32 v116, 0xbfb8aa3b, v145
	v_exp_f32_e32 v117, v116
	v_rcp_f32_e32 v116, v111
	v_add_f32_e32 v111, 1.0, v115
	v_rcp_f32_e32 v115, v111
	v_add_f32_e32 v111, 1.0, v117
	v_rcp_f32_e32 v117, v111
	v_mov_b32_e32 v118, v142
	v_mov_b32_e32 v119, v144
	v_pk_mul_f32 v[114:115], v[118:119], v[114:115]
	v_mov_b32_e32 v118, v138
	v_mov_b32_e32 v119, v140
	v_mov_b32_e32 v144, v143
	v_pk_mul_f32 v[114:115], v[118:119], v[114:115]
	v_pk_mul_f32 v[116:117], v[144:145], v[116:117]
	v_mov_b32_e32 v140, v139
	v_pk_mul_f32 v[116:117], v[140:141], v[116:117]
	v_and_b32_sdwa v111, v115, v177 dst_sel:DWORD dst_unused:UNUSED_PAD src0_sel:WORD_1 src1_sel:DWORD
	v_and_b32_sdwa v118, v114, v177 dst_sel:DWORD dst_unused:UNUSED_PAD src0_sel:WORD_1 src1_sel:DWORD
	v_add3_u32 v111, v115, v111, s28
	v_and_b32_sdwa v115, v117, v177 dst_sel:DWORD dst_unused:UNUSED_PAD src0_sel:WORD_1 src1_sel:DWORD
	v_add3_u32 v114, v114, v118, s28
	v_and_b32_sdwa v118, v116, v177 dst_sel:DWORD dst_unused:UNUSED_PAD src0_sel:WORD_1 src1_sel:DWORD
	v_add3_u32 v115, v117, v115, s28
	v_add3_u32 v116, v116, v118, s28
	v_and_b32_e32 v115, 0xffff0000, v115
	v_and_b32_e32 v116, 0xffff0000, v116
	v_or_b32_sdwa v115, v115, v111 dst_sel:DWORD dst_unused:UNUSED_PAD src0_sel:DWORD src1_sel:WORD_1
	v_mul_f32_e32 v111, 0xbfb8aa3b, v102
	v_or_b32_sdwa v114, v116, v114 dst_sel:DWORD dst_unused:UNUSED_PAD src0_sel:DWORD src1_sel:WORD_1
	v_exp_f32_e32 v111, v111
	v_mul_f32_e32 v116, 0xbfb8aa3b, v103
	v_exp_f32_e32 v116, v116
	global_store_dwordx2 v[112:113], v[114:115], off offset:64
	v_add_f32_e32 v111, 1.0, v111
	v_mul_f32_e32 v115, 0xbfb8aa3b, v104
	v_rcp_f32_e32 v114, v111
	v_add_f32_e32 v111, 1.0, v116
	v_exp_f32_e32 v115, v115
	v_mul_f32_e32 v116, 0xbfb8aa3b, v105
	v_exp_f32_e32 v117, v116
	v_rcp_f32_e32 v116, v111
	v_add_f32_e32 v111, 1.0, v115
	v_rcp_f32_e32 v115, v111
	v_add_f32_e32 v111, 1.0, v117
	v_rcp_f32_e32 v117, v111
	v_mov_b32_e32 v118, v102
	v_mov_b32_e32 v119, v104
	v_mov_b32_e32 v104, v103
	v_pk_mul_f32 v[114:115], v[118:119], v[114:115]
	v_mov_b32_e32 v119, v100
	v_pk_mul_f32 v[102:103], v[104:105], v[116:117]
	v_mov_b32_e32 v100, v99
	v_mov_b32_e32 v118, v98
	v_pk_mul_f32 v[98:99], v[100:101], v[102:103]
	v_pk_mul_f32 v[114:115], v[118:119], v[114:115]
	v_and_b32_sdwa v102, v99, v177 dst_sel:DWORD dst_unused:UNUSED_PAD src0_sel:WORD_1 src1_sel:DWORD
	v_and_b32_sdwa v103, v98, v177 dst_sel:DWORD dst_unused:UNUSED_PAD src0_sel:WORD_1 src1_sel:DWORD
	v_and_b32_sdwa v100, v115, v177 dst_sel:DWORD dst_unused:UNUSED_PAD src0_sel:WORD_1 src1_sel:DWORD
	v_and_b32_sdwa v101, v114, v177 dst_sel:DWORD dst_unused:UNUSED_PAD src0_sel:WORD_1 src1_sel:DWORD
	v_add3_u32 v99, v99, v102, s28
	v_add3_u32 v98, v98, v103, s28
	v_add3_u32 v101, v114, v101, s28
	v_add3_u32 v100, v115, v100, s28
	v_and_b32_e32 v99, 0xffff0000, v99
	v_and_b32_e32 v98, 0xffff0000, v98
	v_or_b32_sdwa v99, v99, v100 dst_sel:DWORD dst_unused:UNUSED_PAD src0_sel:DWORD src1_sel:WORD_1
	v_or_b32_sdwa v98, v98, v101 dst_sel:DWORD dst_unused:UNUSED_PAD src0_sel:DWORD src1_sel:WORD_1
	global_store_dwordx2 v[112:113], v[98:99], off offset:96
	v_mul_f32_e32 v99, 0xbfb8aa3b, v94
	v_exp_f32_e32 v100, v99
	v_mul_f32_e32 v99, 0xbfb8aa3b, v95
	v_mul_f32_e32 v102, 0xbfb8aa3b, v96
	v_exp_f32_e32 v101, v99
	v_exp_f32_e32 v103, v102
	v_mul_f32_e32 v102, 0xbfb8aa3b, v97
	v_exp_f32_e32 v104, v102
	v_add_f32_e32 v101, 1.0, v101
	v_add_f32_e32 v100, 1.0, v100
	v_rcp_f32_e32 v102, v101
	v_add_f32_e32 v101, 1.0, v103
	v_add_f32_e32 v103, 1.0, v104
	v_rcp_f32_e32 v100, v100
	v_rcp_f32_e32 v101, v101
	v_rcp_f32_e32 v103, v103
	v_mov_b32_e32 v104, v94
	v_mov_b32_e32 v105, v96
	v_mov_b32_e32 v96, v95
	v_pk_mul_f32 v[100:101], v[104:105], v[100:101]
	v_mov_b32_e32 v105, v92
	v_pk_mul_f32 v[94:95], v[96:97], v[102:103]
	v_mov_b32_e32 v92, v91
	v_mov_b32_e32 v104, v90
	v_pk_mul_f32 v[90:91], v[92:93], v[94:95]
	v_pk_mul_f32 v[100:101], v[104:105], v[100:101]
	v_and_b32_sdwa v94, v91, v177 dst_sel:DWORD dst_unused:UNUSED_PAD src0_sel:WORD_1 src1_sel:DWORD
	v_and_b32_sdwa v92, v101, v177 dst_sel:DWORD dst_unused:UNUSED_PAD src0_sel:WORD_1 src1_sel:DWORD
	v_and_b32_sdwa v95, v90, v177 dst_sel:DWORD dst_unused:UNUSED_PAD src0_sel:WORD_1 src1_sel:DWORD
	v_add3_u32 v91, v91, v94, s28
	v_and_b32_sdwa v93, v100, v177 dst_sel:DWORD dst_unused:UNUSED_PAD src0_sel:WORD_1 src1_sel:DWORD
	v_add3_u32 v92, v101, v92, s28
	v_add3_u32 v90, v90, v95, s28
	v_and_b32_e32 v91, 0xffff0000, v91
	v_add3_u32 v93, v100, v93, s28
	v_and_b32_e32 v90, 0xffff0000, v90
	v_or_b32_sdwa v91, v91, v92 dst_sel:DWORD dst_unused:UNUSED_PAD src0_sel:DWORD src1_sel:WORD_1
	v_mul_f32_e32 v92, 0xbfb8aa3b, v86
	v_or_b32_sdwa v90, v90, v93 dst_sel:DWORD dst_unused:UNUSED_PAD src0_sel:DWORD src1_sel:WORD_1
	v_exp_f32_e32 v92, v92
	v_mul_f32_e32 v93, 0xbfb8aa3b, v87
	v_or_b32_e32 v98, 16, v110
	v_exp_f32_e32 v93, v93
	v_mad_i64_i32 v[98:99], s[6:7], v98, s52, v[106:107]
	v_lshl_add_u64 v[98:99], v[98:99], 0, v[108:109]
	global_store_dwordx2 v[98:99], v[90:91], off
	v_add_f32_e32 v90, 1.0, v92
	v_mul_f32_e32 v92, 0xbfb8aa3b, v88
	v_add_f32_e32 v91, 1.0, v93
	v_exp_f32_e32 v93, v92
	v_mul_f32_e32 v92, 0xbfb8aa3b, v89
	v_exp_f32_e32 v94, v92
	v_rcp_f32_e32 v92, v91
	v_add_f32_e32 v91, 1.0, v93
	v_rcp_f32_e32 v90, v90
	v_add_f32_e32 v93, 1.0, v94
	v_rcp_f32_e32 v91, v91
	v_rcp_f32_e32 v93, v93
	v_mov_b32_e32 v94, v86
	v_mov_b32_e32 v95, v88
	v_mov_b32_e32 v88, v87
	v_pk_mul_f32 v[90:91], v[94:95], v[90:91]
	v_mov_b32_e32 v95, v84
	v_pk_mul_f32 v[86:87], v[88:89], v[92:93]
	v_mov_b32_e32 v84, v83
	v_mov_b32_e32 v94, v82
	v_pk_mul_f32 v[82:83], v[84:85], v[86:87]
	v_pk_mul_f32 v[90:91], v[94:95], v[90:91]
	v_and_b32_sdwa v86, v83, v177 dst_sel:DWORD dst_unused:UNUSED_PAD src0_sel:WORD_1 src1_sel:DWORD
	v_and_b32_sdwa v84, v91, v177 dst_sel:DWORD dst_unused:UNUSED_PAD src0_sel:WORD_1 src1_sel:DWORD
	v_and_b32_sdwa v87, v82, v177 dst_sel:DWORD dst_unused:UNUSED_PAD src0_sel:WORD_1 src1_sel:DWORD
	v_add3_u32 v83, v83, v86, s28
	v_and_b32_sdwa v85, v90, v177 dst_sel:DWORD dst_unused:UNUSED_PAD src0_sel:WORD_1 src1_sel:DWORD
	v_add3_u32 v84, v91, v84, s28
	v_add3_u32 v82, v82, v87, s28
	v_and_b32_e32 v83, 0xffff0000, v83
	v_add3_u32 v85, v90, v85, s28
	v_and_b32_e32 v82, 0xffff0000, v82
	v_or_b32_sdwa v83, v83, v84 dst_sel:DWORD dst_unused:UNUSED_PAD src0_sel:DWORD src1_sel:WORD_1
	v_mul_f32_e32 v84, 0xbfb8aa3b, v78
	v_or_b32_sdwa v82, v82, v85 dst_sel:DWORD dst_unused:UNUSED_PAD src0_sel:DWORD src1_sel:WORD_1
	v_exp_f32_e32 v84, v84
	v_mul_f32_e32 v85, 0xbfb8aa3b, v79
	v_exp_f32_e32 v85, v85
	global_store_dwordx2 v[98:99], v[82:83], off offset:32
	v_add_f32_e32 v82, 1.0, v84
	v_mul_f32_e32 v84, 0xbfb8aa3b, v80
	v_add_f32_e32 v83, 1.0, v85
	v_exp_f32_e32 v85, v84
	v_mul_f32_e32 v84, 0xbfb8aa3b, v81
	v_exp_f32_e32 v86, v84
	v_rcp_f32_e32 v84, v83
	v_add_f32_e32 v83, 1.0, v85
	v_rcp_f32_e32 v82, v82
	v_add_f32_e32 v85, 1.0, v86
	v_rcp_f32_e32 v83, v83
	v_rcp_f32_e32 v85, v85
	v_mov_b32_e32 v86, v78
	v_mov_b32_e32 v87, v80
	v_mov_b32_e32 v80, v79
	v_pk_mul_f32 v[82:83], v[86:87], v[82:83]
	v_mov_b32_e32 v87, v76
	v_pk_mul_f32 v[78:79], v[80:81], v[84:85]
	v_mov_b32_e32 v76, v75
	v_mov_b32_e32 v86, v74
	v_pk_mul_f32 v[74:75], v[76:77], v[78:79]
	v_pk_mul_f32 v[82:83], v[86:87], v[82:83]
	v_and_b32_sdwa v78, v75, v177 dst_sel:DWORD dst_unused:UNUSED_PAD src0_sel:WORD_1 src1_sel:DWORD
	v_and_b32_sdwa v76, v83, v177 dst_sel:DWORD dst_unused:UNUSED_PAD src0_sel:WORD_1 src1_sel:DWORD
	v_and_b32_sdwa v79, v74, v177 dst_sel:DWORD dst_unused:UNUSED_PAD src0_sel:WORD_1 src1_sel:DWORD
	v_add3_u32 v75, v75, v78, s28
	v_and_b32_sdwa v77, v82, v177 dst_sel:DWORD dst_unused:UNUSED_PAD src0_sel:WORD_1 src1_sel:DWORD
	v_add3_u32 v76, v83, v76, s28
	v_add3_u32 v74, v74, v79, s28
	v_and_b32_e32 v75, 0xffff0000, v75
	v_add3_u32 v77, v82, v77, s28
	v_and_b32_e32 v74, 0xffff0000, v74
	v_or_b32_sdwa v75, v75, v76 dst_sel:DWORD dst_unused:UNUSED_PAD src0_sel:DWORD src1_sel:WORD_1
	v_mul_f32_e32 v76, 0xbfb8aa3b, v70
	v_or_b32_sdwa v74, v74, v77 dst_sel:DWORD dst_unused:UNUSED_PAD src0_sel:DWORD src1_sel:WORD_1
	v_exp_f32_e32 v76, v76
	v_mul_f32_e32 v77, 0xbfb8aa3b, v71
	v_exp_f32_e32 v77, v77
	global_store_dwordx2 v[98:99], v[74:75], off offset:64
	v_add_f32_e32 v74, 1.0, v76
	v_mul_f32_e32 v76, 0xbfb8aa3b, v72
	v_add_f32_e32 v75, 1.0, v77
	v_exp_f32_e32 v77, v76
	v_mul_f32_e32 v76, 0xbfb8aa3b, v73
	v_exp_f32_e32 v78, v76
	v_rcp_f32_e32 v76, v75
	v_add_f32_e32 v75, 1.0, v77
	v_rcp_f32_e32 v74, v74
	v_add_f32_e32 v77, 1.0, v78
	v_rcp_f32_e32 v75, v75
	v_rcp_f32_e32 v77, v77
	v_mov_b32_e32 v78, v70
	v_mov_b32_e32 v79, v72
	v_mov_b32_e32 v72, v71
	v_pk_mul_f32 v[74:75], v[78:79], v[74:75]
	v_mov_b32_e32 v79, v68
	v_pk_mul_f32 v[70:71], v[72:73], v[76:77]
	v_mov_b32_e32 v68, v67
	v_mov_b32_e32 v78, v66
	v_pk_mul_f32 v[66:67], v[68:69], v[70:71]
	v_pk_mul_f32 v[74:75], v[78:79], v[74:75]
	v_and_b32_sdwa v70, v67, v177 dst_sel:DWORD dst_unused:UNUSED_PAD src0_sel:WORD_1 src1_sel:DWORD
	v_and_b32_sdwa v71, v66, v177 dst_sel:DWORD dst_unused:UNUSED_PAD src0_sel:WORD_1 src1_sel:DWORD
	v_and_b32_sdwa v68, v75, v177 dst_sel:DWORD dst_unused:UNUSED_PAD src0_sel:WORD_1 src1_sel:DWORD
	v_and_b32_sdwa v69, v74, v177 dst_sel:DWORD dst_unused:UNUSED_PAD src0_sel:WORD_1 src1_sel:DWORD
	v_add3_u32 v67, v67, v70, s28
	v_add3_u32 v66, v66, v71, s28
	v_add3_u32 v69, v74, v69, s28
	v_add3_u32 v68, v75, v68, s28
	v_and_b32_e32 v67, 0xffff0000, v67
	v_and_b32_e32 v66, 0xffff0000, v66
	v_or_b32_sdwa v67, v67, v68 dst_sel:DWORD dst_unused:UNUSED_PAD src0_sel:DWORD src1_sel:WORD_1
	v_or_b32_sdwa v66, v66, v69 dst_sel:DWORD dst_unused:UNUSED_PAD src0_sel:DWORD src1_sel:WORD_1
	global_store_dwordx2 v[98:99], v[66:67], off offset:96
	v_mul_f32_e32 v67, 0xbfb8aa3b, v62
	v_exp_f32_e32 v68, v67
	v_mul_f32_e32 v67, 0xbfb8aa3b, v63
	v_mul_f32_e32 v70, 0xbfb8aa3b, v64
	v_exp_f32_e32 v69, v67
	v_exp_f32_e32 v71, v70
	v_mul_f32_e32 v70, 0xbfb8aa3b, v65
	v_exp_f32_e32 v72, v70
	v_add_f32_e32 v69, 1.0, v69
	v_add_f32_e32 v68, 1.0, v68
	v_rcp_f32_e32 v70, v69
	v_add_f32_e32 v69, 1.0, v71
	v_add_f32_e32 v71, 1.0, v72
	v_rcp_f32_e32 v68, v68
	v_rcp_f32_e32 v69, v69
	v_rcp_f32_e32 v71, v71
	v_mov_b32_e32 v72, v62
	v_mov_b32_e32 v73, v64
	v_mov_b32_e32 v64, v63
	v_pk_mul_f32 v[68:69], v[72:73], v[68:69]
	v_mov_b32_e32 v73, v60
	v_pk_mul_f32 v[62:63], v[64:65], v[70:71]
	v_mov_b32_e32 v60, v59
	v_mov_b32_e32 v72, v58
	v_pk_mul_f32 v[58:59], v[60:61], v[62:63]
	v_pk_mul_f32 v[68:69], v[72:73], v[68:69]
	v_and_b32_sdwa v62, v59, v177 dst_sel:DWORD dst_unused:UNUSED_PAD src0_sel:WORD_1 src1_sel:DWORD
	v_and_b32_sdwa v60, v69, v177 dst_sel:DWORD dst_unused:UNUSED_PAD src0_sel:WORD_1 src1_sel:DWORD
	v_and_b32_sdwa v63, v58, v177 dst_sel:DWORD dst_unused:UNUSED_PAD src0_sel:WORD_1 src1_sel:DWORD
	v_add3_u32 v59, v59, v62, s28
	v_and_b32_sdwa v61, v68, v177 dst_sel:DWORD dst_unused:UNUSED_PAD src0_sel:WORD_1 src1_sel:DWORD
	v_add3_u32 v60, v69, v60, s28
	v_add3_u32 v58, v58, v63, s28
	v_and_b32_e32 v59, 0xffff0000, v59
	v_add3_u32 v61, v68, v61, s28
	v_and_b32_e32 v58, 0xffff0000, v58
	v_or_b32_sdwa v59, v59, v60 dst_sel:DWORD dst_unused:UNUSED_PAD src0_sel:DWORD src1_sel:WORD_1
	v_mul_f32_e32 v60, 0xbfb8aa3b, v54
	v_or_b32_sdwa v58, v58, v61 dst_sel:DWORD dst_unused:UNUSED_PAD src0_sel:DWORD src1_sel:WORD_1
	v_exp_f32_e32 v60, v60
	v_mul_f32_e32 v61, 0xbfb8aa3b, v55
	v_or_b32_e32 v66, 32, v110
	v_exp_f32_e32 v61, v61
	v_mad_i64_i32 v[66:67], s[6:7], v66, s52, v[106:107]
	v_lshl_add_u64 v[66:67], v[66:67], 0, v[108:109]
	global_store_dwordx2 v[66:67], v[58:59], off
	v_add_f32_e32 v58, 1.0, v60
	v_mul_f32_e32 v60, 0xbfb8aa3b, v56
	v_add_f32_e32 v59, 1.0, v61
	v_exp_f32_e32 v61, v60
	v_mul_f32_e32 v60, 0xbfb8aa3b, v57
	v_exp_f32_e32 v62, v60
	v_rcp_f32_e32 v60, v59
	v_add_f32_e32 v59, 1.0, v61
	v_rcp_f32_e32 v58, v58
	v_add_f32_e32 v61, 1.0, v62
	v_rcp_f32_e32 v59, v59
	v_rcp_f32_e32 v61, v61
	v_mov_b32_e32 v62, v54
	v_mov_b32_e32 v63, v56
	v_mov_b32_e32 v56, v55
	v_pk_mul_f32 v[58:59], v[62:63], v[58:59]
	v_mov_b32_e32 v63, v52
	v_pk_mul_f32 v[54:55], v[56:57], v[60:61]
	v_mov_b32_e32 v52, v51
	v_mov_b32_e32 v62, v50
	v_pk_mul_f32 v[50:51], v[52:53], v[54:55]
	v_pk_mul_f32 v[58:59], v[62:63], v[58:59]
	v_and_b32_sdwa v54, v51, v177 dst_sel:DWORD dst_unused:UNUSED_PAD src0_sel:WORD_1 src1_sel:DWORD
	v_and_b32_sdwa v52, v59, v177 dst_sel:DWORD dst_unused:UNUSED_PAD src0_sel:WORD_1 src1_sel:DWORD
	v_and_b32_sdwa v55, v50, v177 dst_sel:DWORD dst_unused:UNUSED_PAD src0_sel:WORD_1 src1_sel:DWORD
	v_add3_u32 v51, v51, v54, s28
	v_and_b32_sdwa v53, v58, v177 dst_sel:DWORD dst_unused:UNUSED_PAD src0_sel:WORD_1 src1_sel:DWORD
	v_add3_u32 v52, v59, v52, s28
	v_add3_u32 v50, v50, v55, s28
	v_and_b32_e32 v51, 0xffff0000, v51
	v_add3_u32 v53, v58, v53, s28
	v_and_b32_e32 v50, 0xffff0000, v50
	v_or_b32_sdwa v51, v51, v52 dst_sel:DWORD dst_unused:UNUSED_PAD src0_sel:DWORD src1_sel:WORD_1
	v_mul_f32_e32 v52, 0xbfb8aa3b, v46
	v_or_b32_sdwa v50, v50, v53 dst_sel:DWORD dst_unused:UNUSED_PAD src0_sel:DWORD src1_sel:WORD_1
	v_exp_f32_e32 v52, v52
	v_mul_f32_e32 v53, 0xbfb8aa3b, v47
	v_exp_f32_e32 v53, v53
	global_store_dwordx2 v[66:67], v[50:51], off offset:32
	v_add_f32_e32 v50, 1.0, v52
	v_mul_f32_e32 v52, 0xbfb8aa3b, v48
	v_add_f32_e32 v51, 1.0, v53
	v_exp_f32_e32 v53, v52
	v_mul_f32_e32 v52, 0xbfb8aa3b, v49
	v_exp_f32_e32 v54, v52
	v_rcp_f32_e32 v52, v51
	v_add_f32_e32 v51, 1.0, v53
	v_rcp_f32_e32 v50, v50
	v_add_f32_e32 v53, 1.0, v54
	v_rcp_f32_e32 v51, v51
	v_rcp_f32_e32 v53, v53
	v_mov_b32_e32 v54, v46
	v_mov_b32_e32 v55, v48
	v_mov_b32_e32 v48, v47
	v_pk_mul_f32 v[50:51], v[54:55], v[50:51]
	v_mov_b32_e32 v55, v44
	v_pk_mul_f32 v[46:47], v[48:49], v[52:53]
	v_mov_b32_e32 v44, v43
	v_mov_b32_e32 v54, v42
	v_pk_mul_f32 v[42:43], v[44:45], v[46:47]
	v_pk_mul_f32 v[50:51], v[54:55], v[50:51]
	v_and_b32_sdwa v46, v43, v177 dst_sel:DWORD dst_unused:UNUSED_PAD src0_sel:WORD_1 src1_sel:DWORD
	v_and_b32_sdwa v44, v51, v177 dst_sel:DWORD dst_unused:UNUSED_PAD src0_sel:WORD_1 src1_sel:DWORD
	v_and_b32_sdwa v47, v42, v177 dst_sel:DWORD dst_unused:UNUSED_PAD src0_sel:WORD_1 src1_sel:DWORD
	v_add3_u32 v43, v43, v46, s28
	v_and_b32_sdwa v45, v50, v177 dst_sel:DWORD dst_unused:UNUSED_PAD src0_sel:WORD_1 src1_sel:DWORD
	v_add3_u32 v44, v51, v44, s28
	v_add3_u32 v42, v42, v47, s28
	v_and_b32_e32 v43, 0xffff0000, v43
	v_add3_u32 v45, v50, v45, s28
	v_and_b32_e32 v42, 0xffff0000, v42
	v_or_b32_sdwa v43, v43, v44 dst_sel:DWORD dst_unused:UNUSED_PAD src0_sel:DWORD src1_sel:WORD_1
	v_mul_f32_e32 v44, 0xbfb8aa3b, v38
	v_or_b32_sdwa v42, v42, v45 dst_sel:DWORD dst_unused:UNUSED_PAD src0_sel:DWORD src1_sel:WORD_1
	v_exp_f32_e32 v44, v44
	v_mul_f32_e32 v45, 0xbfb8aa3b, v39
	v_exp_f32_e32 v45, v45
	global_store_dwordx2 v[66:67], v[42:43], off offset:64
	v_add_f32_e32 v42, 1.0, v44
	v_mul_f32_e32 v44, 0xbfb8aa3b, v40
	v_add_f32_e32 v43, 1.0, v45
	v_exp_f32_e32 v45, v44
	v_mul_f32_e32 v44, 0xbfb8aa3b, v41
	v_exp_f32_e32 v46, v44
	v_rcp_f32_e32 v44, v43
	v_add_f32_e32 v43, 1.0, v45
	v_rcp_f32_e32 v42, v42
	v_add_f32_e32 v45, 1.0, v46
	v_rcp_f32_e32 v43, v43
	v_rcp_f32_e32 v45, v45
	v_mov_b32_e32 v46, v38
	v_mov_b32_e32 v47, v40
	v_mov_b32_e32 v40, v39
	v_pk_mul_f32 v[42:43], v[46:47], v[42:43]
	v_mov_b32_e32 v47, v36
	v_pk_mul_f32 v[38:39], v[40:41], v[44:45]
	v_mov_b32_e32 v36, v35
	v_mov_b32_e32 v46, v34
	v_pk_mul_f32 v[34:35], v[36:37], v[38:39]
	v_pk_mul_f32 v[42:43], v[46:47], v[42:43]
	v_and_b32_sdwa v38, v35, v177 dst_sel:DWORD dst_unused:UNUSED_PAD src0_sel:WORD_1 src1_sel:DWORD
	v_and_b32_sdwa v39, v34, v177 dst_sel:DWORD dst_unused:UNUSED_PAD src0_sel:WORD_1 src1_sel:DWORD
	v_and_b32_sdwa v36, v43, v177 dst_sel:DWORD dst_unused:UNUSED_PAD src0_sel:WORD_1 src1_sel:DWORD
	v_and_b32_sdwa v37, v42, v177 dst_sel:DWORD dst_unused:UNUSED_PAD src0_sel:WORD_1 src1_sel:DWORD
	v_add3_u32 v35, v35, v38, s28
	v_add3_u32 v34, v34, v39, s28
	v_add3_u32 v37, v42, v37, s28
	v_add3_u32 v36, v43, v36, s28
	v_and_b32_e32 v35, 0xffff0000, v35
	v_and_b32_e32 v34, 0xffff0000, v34
	v_or_b32_sdwa v35, v35, v36 dst_sel:DWORD dst_unused:UNUSED_PAD src0_sel:DWORD src1_sel:WORD_1
	v_or_b32_sdwa v34, v34, v37 dst_sel:DWORD dst_unused:UNUSED_PAD src0_sel:DWORD src1_sel:WORD_1
	global_store_dwordx2 v[66:67], v[34:35], off offset:96
	v_mul_f32_e32 v35, 0xbfb8aa3b, v30
	v_exp_f32_e32 v36, v35
	v_mul_f32_e32 v35, 0xbfb8aa3b, v31
	v_mul_f32_e32 v38, 0xbfb8aa3b, v32
	v_exp_f32_e32 v37, v35
	v_exp_f32_e32 v39, v38
	v_mul_f32_e32 v38, 0xbfb8aa3b, v33
	v_exp_f32_e32 v40, v38
	v_add_f32_e32 v37, 1.0, v37
	v_add_f32_e32 v36, 1.0, v36
	v_rcp_f32_e32 v38, v37
	v_add_f32_e32 v37, 1.0, v39
	v_add_f32_e32 v39, 1.0, v40
	v_rcp_f32_e32 v36, v36
	v_rcp_f32_e32 v37, v37
	v_rcp_f32_e32 v39, v39
	v_mov_b32_e32 v40, v30
	v_mov_b32_e32 v41, v32
	v_mov_b32_e32 v32, v31
	v_pk_mul_f32 v[36:37], v[40:41], v[36:37]
	v_mov_b32_e32 v41, v28
	v_pk_mul_f32 v[30:31], v[32:33], v[38:39]
	v_mov_b32_e32 v28, v27
	v_mov_b32_e32 v40, v26
	v_pk_mul_f32 v[26:27], v[28:29], v[30:31]
	v_pk_mul_f32 v[36:37], v[40:41], v[36:37]
	v_and_b32_sdwa v30, v27, v177 dst_sel:DWORD dst_unused:UNUSED_PAD src0_sel:WORD_1 src1_sel:DWORD
	v_and_b32_sdwa v28, v37, v177 dst_sel:DWORD dst_unused:UNUSED_PAD src0_sel:WORD_1 src1_sel:DWORD
	v_and_b32_sdwa v31, v26, v177 dst_sel:DWORD dst_unused:UNUSED_PAD src0_sel:WORD_1 src1_sel:DWORD
	v_add3_u32 v27, v27, v30, s28
	v_and_b32_sdwa v29, v36, v177 dst_sel:DWORD dst_unused:UNUSED_PAD src0_sel:WORD_1 src1_sel:DWORD
	v_add3_u32 v28, v37, v28, s28
	v_add3_u32 v26, v26, v31, s28
	v_and_b32_e32 v27, 0xffff0000, v27
	v_add3_u32 v29, v36, v29, s28
	v_and_b32_e32 v26, 0xffff0000, v26
	v_or_b32_sdwa v27, v27, v28 dst_sel:DWORD dst_unused:UNUSED_PAD src0_sel:DWORD src1_sel:WORD_1
	v_mul_f32_e32 v28, 0xbfb8aa3b, v22
	v_or_b32_sdwa v26, v26, v29 dst_sel:DWORD dst_unused:UNUSED_PAD src0_sel:DWORD src1_sel:WORD_1
	v_exp_f32_e32 v28, v28
	v_mul_f32_e32 v29, 0xbfb8aa3b, v23
	v_or_b32_e32 v34, 48, v110
	v_exp_f32_e32 v29, v29
	v_mad_i64_i32 v[34:35], s[6:7], v34, s52, v[106:107]
	v_lshl_add_u64 v[34:35], v[34:35], 0, v[108:109]
	global_store_dwordx2 v[34:35], v[26:27], off
	v_add_f32_e32 v26, 1.0, v28
	v_mul_f32_e32 v28, 0xbfb8aa3b, v24
	v_add_f32_e32 v27, 1.0, v29
	v_exp_f32_e32 v29, v28
	v_mul_f32_e32 v28, 0xbfb8aa3b, v25
	v_exp_f32_e32 v30, v28
	v_rcp_f32_e32 v28, v27
	v_add_f32_e32 v27, 1.0, v29
	v_rcp_f32_e32 v26, v26
	v_add_f32_e32 v29, 1.0, v30
	v_rcp_f32_e32 v27, v27
	v_rcp_f32_e32 v29, v29
	v_mov_b32_e32 v30, v22
	v_mov_b32_e32 v31, v24
	v_mov_b32_e32 v24, v23
	v_pk_mul_f32 v[26:27], v[30:31], v[26:27]
	v_mov_b32_e32 v31, v20
	v_pk_mul_f32 v[22:23], v[24:25], v[28:29]
	v_mov_b32_e32 v20, v19
	v_mov_b32_e32 v30, v18
	v_pk_mul_f32 v[18:19], v[20:21], v[22:23]
	v_pk_mul_f32 v[26:27], v[30:31], v[26:27]
	v_and_b32_sdwa v22, v19, v177 dst_sel:DWORD dst_unused:UNUSED_PAD src0_sel:WORD_1 src1_sel:DWORD
	v_and_b32_sdwa v20, v27, v177 dst_sel:DWORD dst_unused:UNUSED_PAD src0_sel:WORD_1 src1_sel:DWORD
	v_and_b32_sdwa v23, v18, v177 dst_sel:DWORD dst_unused:UNUSED_PAD src0_sel:WORD_1 src1_sel:DWORD
	v_add3_u32 v19, v19, v22, s28
	v_and_b32_sdwa v21, v26, v177 dst_sel:DWORD dst_unused:UNUSED_PAD src0_sel:WORD_1 src1_sel:DWORD
	v_add3_u32 v20, v27, v20, s28
	v_add3_u32 v18, v18, v23, s28
	v_and_b32_e32 v19, 0xffff0000, v19
	v_add3_u32 v21, v26, v21, s28
	v_and_b32_e32 v18, 0xffff0000, v18
	v_or_b32_sdwa v19, v19, v20 dst_sel:DWORD dst_unused:UNUSED_PAD src0_sel:DWORD src1_sel:WORD_1
	v_mul_f32_e32 v20, 0xbfb8aa3b, v14
	v_or_b32_sdwa v18, v18, v21 dst_sel:DWORD dst_unused:UNUSED_PAD src0_sel:DWORD src1_sel:WORD_1
	v_exp_f32_e32 v20, v20
	v_mul_f32_e32 v21, 0xbfb8aa3b, v15
	v_exp_f32_e32 v21, v21
	global_store_dwordx2 v[34:35], v[18:19], off offset:32
	v_add_f32_e32 v18, 1.0, v20
	v_mul_f32_e32 v20, 0xbfb8aa3b, v16
	v_add_f32_e32 v19, 1.0, v21
	v_exp_f32_e32 v21, v20
	v_mul_f32_e32 v20, 0xbfb8aa3b, v17
	v_exp_f32_e32 v22, v20
	v_rcp_f32_e32 v20, v19
	v_add_f32_e32 v19, 1.0, v21
	v_rcp_f32_e32 v18, v18
	v_add_f32_e32 v21, 1.0, v22
	v_rcp_f32_e32 v19, v19
	v_rcp_f32_e32 v21, v21
	v_mov_b32_e32 v22, v14
	v_mov_b32_e32 v23, v16
	v_mov_b32_e32 v16, v15
	v_pk_mul_f32 v[18:19], v[22:23], v[18:19]
	v_mov_b32_e32 v23, v12
	v_pk_mul_f32 v[14:15], v[16:17], v[20:21]
	v_mov_b32_e32 v12, v11
	v_mov_b32_e32 v22, v10
	v_pk_mul_f32 v[10:11], v[12:13], v[14:15]
	v_pk_mul_f32 v[18:19], v[22:23], v[18:19]
	v_and_b32_sdwa v14, v11, v177 dst_sel:DWORD dst_unused:UNUSED_PAD src0_sel:WORD_1 src1_sel:DWORD
	v_and_b32_sdwa v12, v19, v177 dst_sel:DWORD dst_unused:UNUSED_PAD src0_sel:WORD_1 src1_sel:DWORD
	v_and_b32_sdwa v15, v10, v177 dst_sel:DWORD dst_unused:UNUSED_PAD src0_sel:WORD_1 src1_sel:DWORD
	v_add3_u32 v11, v11, v14, s28
	v_and_b32_sdwa v13, v18, v177 dst_sel:DWORD dst_unused:UNUSED_PAD src0_sel:WORD_1 src1_sel:DWORD
	v_add3_u32 v12, v19, v12, s28
	v_add3_u32 v10, v10, v15, s28
	v_and_b32_e32 v11, 0xffff0000, v11
	v_add3_u32 v13, v18, v13, s28
	v_and_b32_e32 v10, 0xffff0000, v10
	v_or_b32_sdwa v11, v11, v12 dst_sel:DWORD dst_unused:UNUSED_PAD src0_sel:DWORD src1_sel:WORD_1
	v_mul_f32_e32 v12, 0xbfb8aa3b, v6
	v_or_b32_sdwa v10, v10, v13 dst_sel:DWORD dst_unused:UNUSED_PAD src0_sel:DWORD src1_sel:WORD_1
	v_exp_f32_e32 v12, v12
	v_mul_f32_e32 v13, 0xbfb8aa3b, v7
	v_exp_f32_e32 v13, v13
	global_store_dwordx2 v[34:35], v[10:11], off offset:64
	v_add_f32_e32 v10, 1.0, v12
	v_mul_f32_e32 v12, 0xbfb8aa3b, v8
	v_add_f32_e32 v11, 1.0, v13
	v_exp_f32_e32 v13, v12
	v_mul_f32_e32 v12, 0xbfb8aa3b, v9
	v_exp_f32_e32 v14, v12
	v_rcp_f32_e32 v12, v11
	v_add_f32_e32 v11, 1.0, v13
	v_rcp_f32_e32 v10, v10
	v_add_f32_e32 v13, 1.0, v14
	v_rcp_f32_e32 v11, v11
	v_rcp_f32_e32 v13, v13
	v_mov_b32_e32 v14, v6
	v_mov_b32_e32 v15, v8
	v_mov_b32_e32 v8, v7
	v_pk_mul_f32 v[10:11], v[14:15], v[10:11]
	v_mov_b32_e32 v15, v4
	v_pk_mul_f32 v[6:7], v[8:9], v[12:13]
	v_mov_b32_e32 v4, v3
	v_mov_b32_e32 v14, v2
	v_pk_mul_f32 v[2:3], v[4:5], v[6:7]
	v_pk_mul_f32 v[10:11], v[14:15], v[10:11]
	v_and_b32_sdwa v6, v3, v177 dst_sel:DWORD dst_unused:UNUSED_PAD src0_sel:WORD_1 src1_sel:DWORD
	v_and_b32_sdwa v7, v2, v177 dst_sel:DWORD dst_unused:UNUSED_PAD src0_sel:WORD_1 src1_sel:DWORD
	v_and_b32_sdwa v4, v11, v177 dst_sel:DWORD dst_unused:UNUSED_PAD src0_sel:WORD_1 src1_sel:DWORD
	v_and_b32_sdwa v5, v10, v177 dst_sel:DWORD dst_unused:UNUSED_PAD src0_sel:WORD_1 src1_sel:DWORD
	v_add3_u32 v3, v3, v6, s28
	v_add3_u32 v2, v2, v7, s28
	v_add3_u32 v5, v10, v5, s28
	v_add3_u32 v4, v11, v4, s28
	v_and_b32_e32 v3, 0xffff0000, v3
	v_and_b32_e32 v2, 0xffff0000, v2
	s_add_i32 s14, s14, s11
	v_or_b32_sdwa v3, v3, v4 dst_sel:DWORD dst_unused:UNUSED_PAD src0_sel:DWORD src1_sel:WORD_1
	v_or_b32_sdwa v2, v2, v5 dst_sel:DWORD dst_unused:UNUSED_PAD src0_sel:DWORD src1_sel:WORD_1
	s_cmpk_gt_i32 s14, 0x4ff
	global_store_dwordx2 v[34:35], v[2:3], off offset:96
	s_cbranch_scc0 .LBB0_1440

.LBB0_1461:
	s_mul_hi_i32 s2, s14, 0x38e38e39
	s_lshr_b32 s3, s2, 31
	s_ashr_i32 s2, s2, 4
	s_add_i32 s2, s2, s3
	s_mul_i32 s3, s2, 0x48
	s_sub_i32 s3, s14, s3
	s_lshl_b32 s6, s3, 8
	v_add_u32_e32 v2, s6, v204
	v_ashrrev_i32_e32 v3, 31, v2
	v_lshlrev_b64 v[2:3], 11, v[2:3]
	v_lshl_add_u64 v[168:169], v[162:163], 0, v[2:3]
	v_add_co_u32_e32 v56, vcc, s34, v168
	s_lshl_b32 s7, s2, 8
	s_nop 0
	v_addc_co_u32_e32 v57, vcc, 0, v169, vcc
	v_add_u32_e32 v2, s7, v204
	s_waitcnt vmcnt(9)
	v_add_co_u32_e32 v58, vcc, s35, v168
	v_ashrrev_i32_e32 v3, 31, v2
	s_nop 0
	v_addc_co_u32_e32 v59, vcc, 0, v169, vcc
	v_lshlrev_b64 v[2:3], 11, v[2:3]
	v_add_co_u32_e32 v60, vcc, s36, v168
	v_lshl_add_u64 v[170:171], v[164:165], 0, v[2:3]
	s_nop 0
	v_addc_co_u32_e32 v61, vcc, 0, v169, vcc
	s_waitcnt vmcnt(8)
	v_add_co_u32_e32 v62, vcc, s35, v170
	global_load_dwordx4 v[24:27], v[56:57], off
	global_load_dwordx4 v[28:31], v[58:59], off
	v_addc_co_u32_e32 v63, vcc, 0, v171, vcc
	v_add_co_u32_e32 v64, vcc, s36, v170
	global_load_dwordx4 v[32:35], v[168:169], off
	global_load_dwordx4 v[36:39], v[170:171], off
	v_addc_co_u32_e32 v65, vcc, 0, v171, vcc
	v_add_co_u32_e32 v66, vcc, s34, v170
	global_load_dwordx4 v[40:43], v[62:63], off
	global_load_dwordx4 v[44:47], v[64:65], off
	v_addc_co_u32_e32 v67, vcc, 0, v171, vcc
	global_load_dwordx4 v[48:51], v[60:61], off
	global_load_dwordx4 v[52:55], v[66:67], off
	s_waitcnt lgkmcnt(0)
	s_barrier
	global_load_dwordx4 v[114:117], v[168:169], off offset:128
	global_load_dwordx4 v[106:109], v[56:57], off offset:128
	global_load_dwordx4 v[110:113], v[58:59], off offset:128
	global_load_dwordx4 v[126:129], v[60:61], off offset:128
	global_load_dwordx4 v[122:125], v[170:171], off offset:128
	global_load_dwordx4 v[118:121], v[66:67], off offset:128
	global_load_dwordx4 v[134:137], v[62:63], off offset:128
	global_load_dwordx4 v[130:133], v[64:65], off offset:128
	v_readfirstlane_b32 s100, v172
	s_nop 0
	s_lshr_b32 m0, s100, 8
	v_readfirstlane_b32 vcc_lo, v168
	v_readfirstlane_b32 vcc_hi, v169
	v_readfirstlane_b32 s100, v170
	v_readfirstlane_b32 s101, v171
	s_nop 1
	v_subrev_u32_e32 v168, vcc_lo, v168
	v_subrev_u32_e32 v170, s100, v170
	v_mov_b32_e32 v2, 0
	s_mov_b32 s4, 0
	v_mov_b32_e32 v3, v2
	v_mov_b32_e32 v4, v2
	v_mov_b32_e32 v5, v2
	v_mov_b32_e32 v6, v2
	v_mov_b32_e32 v7, v2
	v_mov_b32_e32 v8, v2
	v_mov_b32_e32 v9, v2
	v_mov_b32_e32 v10, v2
	v_mov_b32_e32 v11, v2
	v_mov_b32_e32 v12, v2
	v_mov_b32_e32 v13, v2
	v_mov_b32_e32 v14, v2
	v_mov_b32_e32 v15, v2
	v_mov_b32_e32 v16, v2
	v_mov_b32_e32 v17, v2
	v_mov_b32_e32 v18, v2
	v_mov_b32_e32 v19, v2
	v_mov_b32_e32 v20, v2
	v_mov_b32_e32 v21, v2
	v_mov_b32_e32 v22, v2
	v_mov_b32_e32 v23, v2
	v_mov_b32_e32 v56, v2
	v_mov_b32_e32 v57, v2
	v_mov_b32_e32 v58, v2
	v_mov_b32_e32 v59, v2
	v_mov_b32_e32 v60, v2
	v_mov_b32_e32 v61, v2
	v_mov_b32_e32 v62, v2
	v_mov_b32_e32 v63, v2
	v_mov_b32_e32 v64, v2
	v_mov_b32_e32 v65, v2
	v_mov_b32_e32 v66, v2
	v_mov_b32_e32 v67, v2
	v_mov_b32_e32 v68, v2
	v_mov_b32_e32 v69, v2
	v_mov_b32_e32 v70, v2
	v_mov_b32_e32 v71, v2
	v_mov_b32_e32 v72, v2
	v_mov_b32_e32 v73, v2
	v_mov_b32_e32 v74, v2
	v_mov_b32_e32 v75, v2
	v_mov_b32_e32 v76, v2
	v_mov_b32_e32 v77, v2
	v_mov_b32_e32 v78, v2
	v_mov_b32_e32 v79, v2
	v_mov_b32_e32 v80, v2
	v_mov_b32_e32 v81, v2
	v_mov_b32_e32 v82, v2
	v_mov_b32_e32 v83, v2
	v_mov_b32_e32 v84, v2
	v_mov_b32_e32 v85, v2
	s_waitcnt vmcnt(11)
	ds_write_b128 v166, v[40:43] offset:49152
	s_waitcnt vmcnt(10)
	ds_write_b128 v166, v[44:47] offset:57344
	ds_write_b128 v166, v[32:35]
	ds_write_b128 v166, v[36:39] offset:32768
	ds_write_b128 v166, v[24:27] offset:8192
	ds_write_b128 v166, v[28:31] offset:16384
	s_waitcnt vmcnt(9)
	ds_write_b128 v166, v[48:51] offset:24576
	s_waitcnt vmcnt(8)
	ds_write_b128 v166, v[52:55] offset:40960
	v_mov_b32_e32 v24, v2
	v_mov_b32_e32 v25, v2
	v_mov_b32_e32 v26, v2
	v_mov_b32_e32 v27, v2
	v_mov_b32_e32 v28, v2
	v_mov_b32_e32 v29, v2
	v_mov_b32_e32 v30, v2
	v_mov_b32_e32 v31, v2
	v_mov_b32_e32 v32, v2
	v_mov_b32_e32 v33, v2
	v_mov_b32_e32 v34, v2
	v_mov_b32_e32 v35, v2
	v_mov_b32_e32 v36, v2
	v_mov_b32_e32 v37, v2
	v_mov_b32_e32 v38, v2
	v_mov_b32_e32 v39, v2
	v_mov_b32_e32 v40, v2
	v_mov_b32_e32 v41, v2
	v_mov_b32_e32 v42, v2
	v_mov_b32_e32 v43, v2
	v_mov_b32_e32 v44, v2
	v_mov_b32_e32 v45, v2
	v_mov_b32_e32 v46, v2
	v_mov_b32_e32 v47, v2
	v_mov_b32_e32 v48, v2
	v_mov_b32_e32 v49, v2
	v_mov_b32_e32 v50, v2
	v_mov_b32_e32 v51, v2
	v_mov_b32_e32 v52, v2
	v_mov_b32_e32 v53, v2
	v_mov_b32_e32 v54, v2
	v_mov_b32_e32 v55, v2
	v_mov_b32_e32 v86, v2
	v_mov_b32_e32 v87, v2
	v_mov_b32_e32 v88, v2
	v_mov_b32_e32 v89, v2
	v_mov_b32_e32 v90, v2
	v_mov_b32_e32 v91, v2
	v_mov_b32_e32 v92, v2
	v_mov_b32_e32 v93, v2
	v_mov_b32_e32 v94, v2
	v_mov_b32_e32 v95, v2
	v_mov_b32_e32 v96, v2
	v_mov_b32_e32 v97, v2
	v_mov_b32_e32 v98, v2
	v_mov_b32_e32 v99, v2
	v_mov_b32_e32 v100, v2
	v_mov_b32_e32 v101, v2
	v_mov_b32_e32 v102, v2
	v_mov_b32_e32 v103, v2
	v_mov_b32_e32 v104, v2
	v_mov_b32_e32 v105, v2
	v_mov_b32_e32 v138, v2
	v_mov_b32_e32 v139, v2
	v_mov_b32_e32 v140, v2
	v_mov_b32_e32 v141, v2
	v_mov_b32_e32 v142, v2
	v_mov_b32_e32 v143, v2
	v_mov_b32_e32 v144, v2
	v_mov_b32_e32 v145, v2
	v_mov_b32_e32 v146, v2
	v_mov_b32_e32 v147, v2
	v_mov_b32_e32 v148, v2
	v_mov_b32_e32 v149, v2
	v_mov_b32_e32 v150, v2
	v_mov_b32_e32 v151, v2
	v_mov_b32_e32 v152, v2
	v_mov_b32_e32 v153, v2
	v_mov_b32_e32 v154, v2
	v_mov_b32_e32 v155, v2
	v_mov_b32_e32 v156, v2
	v_mov_b32_e32 v157, v2
	v_mov_b32_e32 v158, v2
	v_mov_b32_e32 v159, v2
	v_mov_b32_e32 v160, v2
	v_mov_b32_e32 v161, v2
	s_waitcnt lgkmcnt(0)
	s_barrier
	s_cmp_lg_u32 m0, 0
	s_cbranch_scc1 .Lg1_1462

.Lkdone_1462:
	s_waitcnt vmcnt(4)
	v_mul_f32_e32 v109, 0xbfb8aa3b, v158
	v_exp_f32_e32 v109, v109
	s_waitcnt vmcnt(3)
	v_mul_f32_e32 v111, 0xbfb8aa3b, v159
	v_exp_f32_e32 v111, v111
	v_mul_f32_e32 v115, 0xbfb8aa3b, v161
	v_add_f32_e32 v109, 1.0, v109
	v_rcp_f32_e32 v114, v109
	v_add_f32_e32 v109, 1.0, v111
	v_mul_f32_e32 v111, 0xbfb8aa3b, v160
	v_exp_f32_e32 v111, v111
	v_exp_f32_e32 v117, v115
	v_rcp_f32_e32 v116, v109
	s_waitcnt vmcnt(2)
	v_mov_b32_e32 v118, v158
	v_add_f32_e32 v109, 1.0, v111
	v_rcp_f32_e32 v115, v109
	v_add_f32_e32 v109, 1.0, v117
	v_rcp_f32_e32 v117, v109
	v_mov_b32_e32 v119, v160
	v_pk_mul_f32 v[114:115], v[118:119], v[114:115]
	v_mov_b32_e32 v118, v154
	v_mov_b32_e32 v119, v156
	v_mov_b32_e32 v160, v159
	v_pk_mul_f32 v[114:115], v[118:119], v[114:115]
	v_pk_mul_f32 v[116:117], v[160:161], v[116:117]
	v_mov_b32_e32 v156, v155
	v_pk_mul_f32 v[116:117], v[156:157], v[116:117]
	v_and_b32_sdwa v111, v115, v177 dst_sel:DWORD dst_unused:UNUSED_PAD src0_sel:WORD_1 src1_sel:DWORD
	v_and_b32_sdwa v118, v114, v177 dst_sel:DWORD dst_unused:UNUSED_PAD src0_sel:WORD_1 src1_sel:DWORD
	v_add3_u32 v111, v115, v111, s28
	v_and_b32_sdwa v115, v117, v177 dst_sel:DWORD dst_unused:UNUSED_PAD src0_sel:WORD_1 src1_sel:DWORD
	v_add3_u32 v114, v114, v118, s28
	v_and_b32_sdwa v118, v116, v177 dst_sel:DWORD dst_unused:UNUSED_PAD src0_sel:WORD_1 src1_sel:DWORD
	v_add3_u32 v115, v117, v115, s28
	v_or_b32_e32 v106, s7, v207
	v_add3_u32 v116, v116, v118, s28
	v_and_b32_e32 v115, 0xffff0000, v115
	v_ashrrev_i32_e32 v106, 1, v106
	v_and_b32_e32 v116, 0xffff0000, v116
	v_or_b32_sdwa v115, v115, v111 dst_sel:DWORD dst_unused:UNUSED_PAD src0_sel:DWORD src1_sel:WORD_1
	v_mul_f32_e32 v111, 0xbfb8aa3b, v150
	v_or_b32_e32 v108, v106, v208
	v_or_b32_sdwa v114, v116, v114 dst_sel:DWORD dst_unused:UNUSED_PAD src0_sel:DWORD src1_sel:WORD_1
	v_exp_f32_e32 v111, v111
	v_mul_f32_e32 v116, 0xbfb8aa3b, v151
	v_add_u32_e32 v110, s6, v205
	v_mov_b64_e32 v[106:107], s[12:13]
	v_ashrrev_i32_e32 v109, 31, v108
	v_exp_f32_e32 v116, v116
	v_mad_i64_i32 v[112:113], s[6:7], v110, s52, v[106:107]
	v_lshlrev_b64 v[108:109], 1, v[108:109]
	v_lshl_add_u64 v[112:113], v[112:113], 0, v[108:109]
	s_waitcnt vmcnt(0)
	global_store_dwordx2 v[112:113], v[114:115], off
	v_add_f32_e32 v111, 1.0, v111
	v_mul_f32_e32 v115, 0xbfb8aa3b, v152
	v_rcp_f32_e32 v114, v111
	v_add_f32_e32 v111, 1.0, v116
	v_exp_f32_e32 v115, v115
	v_mul_f32_e32 v116, 0xbfb8aa3b, v153
	v_exp_f32_e32 v117, v116
	v_rcp_f32_e32 v116, v111
	v_add_f32_e32 v111, 1.0, v115
	v_rcp_f32_e32 v115, v111
	v_add_f32_e32 v111, 1.0, v117
	v_rcp_f32_e32 v117, v111
	v_mov_b32_e32 v118, v150
	v_mov_b32_e32 v119, v152
	v_pk_mul_f32 v[114:115], v[118:119], v[114:115]
	v_mov_b32_e32 v118, v146
	v_mov_b32_e32 v119, v148
	v_mov_b32_e32 v152, v151
	v_pk_mul_f32 v[114:115], v[118:119], v[114:115]
	v_pk_mul_f32 v[116:117], v[152:153], v[116:117]
	v_mov_b32_e32 v148, v147
	v_pk_mul_f32 v[116:117], v[148:149], v[116:117]
	v_and_b32_sdwa v111, v115, v177 dst_sel:DWORD dst_unused:UNUSED_PAD src0_sel:WORD_1 src1_sel:DWORD
	v_and_b32_sdwa v118, v114, v177 dst_sel:DWORD dst_unused:UNUSED_PAD src0_sel:WORD_1 src1_sel:DWORD
	v_add3_u32 v111, v115, v111, s28
	v_and_b32_sdwa v115, v117, v177 dst_sel:DWORD dst_unused:UNUSED_PAD src0_sel:WORD_1 src1_sel:DWORD
	v_add3_u32 v114, v114, v118, s28
	v_and_b32_sdwa v118, v116, v177 dst_sel:DWORD dst_unused:UNUSED_PAD src0_sel:WORD_1 src1_sel:DWORD
	v_add3_u32 v115, v117, v115, s28
	v_add3_u32 v116, v116, v118, s28
	v_and_b32_e32 v115, 0xffff0000, v115
	v_and_b32_e32 v116, 0xffff0000, v116
	v_or_b32_sdwa v115, v115, v111 dst_sel:DWORD dst_unused:UNUSED_PAD src0_sel:DWORD src1_sel:WORD_1
	v_mul_f32_e32 v111, 0xbfb8aa3b, v142
	v_or_b32_sdwa v114, v116, v114 dst_sel:DWORD dst_unused:UNUSED_PAD src0_sel:DWORD src1_sel:WORD_1
	v_exp_f32_e32 v111, v111
	v_mul_f32_e32 v116, 0xbfb8aa3b, v143
	v_exp_f32_e32 v116, v116
	global_store_dwordx2 v[112:113], v[114:115], off offset:32
	v_add_f32_e32 v111, 1.0, v111
	v_mul_f32_e32 v115, 0xbfb8aa3b, v144
	v_rcp_f32_e32 v114, v111
	v_add_f32_e32 v111, 1.0, v116
	v_exp_f32_e32 v115, v115
	v_mul_f32_e32 v116, 0xbfb8aa3b, v145
	v_exp_f32_e32 v117, v116
	v_rcp_f32_e32 v116, v111
	v_add_f32_e32 v111, 1.0, v115
	v_rcp_f32_e32 v115, v111
	v_add_f32_e32 v111, 1.0, v117
	v_rcp_f32_e32 v117, v111
	v_mov_b32_e32 v118, v142
	v_mov_b32_e32 v119, v144
	v_pk_mul_f32 v[114:115], v[118:119], v[114:115]
	v_mov_b32_e32 v118, v138
	v_mov_b32_e32 v119, v140
	v_mov_b32_e32 v144, v143
	v_pk_mul_f32 v[114:115], v[118:119], v[114:115]
	v_pk_mul_f32 v[116:117], v[144:145], v[116:117]
	v_mov_b32_e32 v140, v139
	v_pk_mul_f32 v[116:117], v[140:141], v[116:117]
	v_and_b32_sdwa v111, v115, v177 dst_sel:DWORD dst_unused:UNUSED_PAD src0_sel:WORD_1 src1_sel:DWORD
	v_and_b32_sdwa v118, v114, v177 dst_sel:DWORD dst_unused:UNUSED_PAD src0_sel:WORD_1 src1_sel:DWORD
	v_add3_u32 v111, v115, v111, s28
	v_and_b32_sdwa v115, v117, v177 dst_sel:DWORD dst_unused:UNUSED_PAD src0_sel:WORD_1 src1_sel:DWORD
	v_add3_u32 v114, v114, v118, s28
	v_and_b32_sdwa v118, v116, v177 dst_sel:DWORD dst_unused:UNUSED_PAD src0_sel:WORD_1 src1_sel:DWORD
	v_add3_u32 v115, v117, v115, s28
	v_add3_u32 v116, v116, v118, s28
	v_and_b32_e32 v115, 0xffff0000, v115
	v_and_b32_e32 v116, 0xffff0000, v116
	v_or_b32_sdwa v115, v115, v111 dst_sel:DWORD dst_unused:UNUSED_PAD src0_sel:DWORD src1_sel:WORD_1
	v_mul_f32_e32 v111, 0xbfb8aa3b, v102
	v_or_b32_sdwa v114, v116, v114 dst_sel:DWORD dst_unused:UNUSED_PAD src0_sel:DWORD src1_sel:WORD_1
	v_exp_f32_e32 v111, v111
	v_mul_f32_e32 v116, 0xbfb8aa3b, v103
	v_exp_f32_e32 v116, v116
	global_store_dwordx2 v[112:113], v[114:115], off offset:64
	v_add_f32_e32 v111, 1.0, v111
	v_mul_f32_e32 v115, 0xbfb8aa3b, v104
	v_rcp_f32_e32 v114, v111
	v_add_f32_e32 v111, 1.0, v116
	v_exp_f32_e32 v115, v115
	v_mul_f32_e32 v116, 0xbfb8aa3b, v105
	v_exp_f32_e32 v117, v116
	v_rcp_f32_e32 v116, v111
	v_add_f32_e32 v111, 1.0, v115
	v_rcp_f32_e32 v115, v111
	v_add_f32_e32 v111, 1.0, v117
	v_rcp_f32_e32 v117, v111
	v_mov_b32_e32 v118, v102
	v_mov_b32_e32 v119, v104
	v_mov_b32_e32 v104, v103
	v_pk_mul_f32 v[114:115], v[118:119], v[114:115]
	v_mov_b32_e32 v119, v100
	v_pk_mul_f32 v[102:103], v[104:105], v[116:117]
	v_mov_b32_e32 v100, v99
	v_mov_b32_e32 v118, v98
	v_pk_mul_f32 v[98:99], v[100:101], v[102:103]
	v_pk_mul_f32 v[114:115], v[118:119], v[114:115]
	v_and_b32_sdwa v102, v99, v177 dst_sel:DWORD dst_unused:UNUSED_PAD src0_sel:WORD_1 src1_sel:DWORD
	v_and_b32_sdwa v103, v98, v177 dst_sel:DWORD dst_unused:UNUSED_PAD src0_sel:WORD_1 src1_sel:DWORD
	v_and_b32_sdwa v100, v115, v177 dst_sel:DWORD dst_unused:UNUSED_PAD src0_sel:WORD_1 src1_sel:DWORD
	v_and_b32_sdwa v101, v114, v177 dst_sel:DWORD dst_unused:UNUSED_PAD src0_sel:WORD_1 src1_sel:DWORD
	v_add3_u32 v99, v99, v102, s28
	v_add3_u32 v98, v98, v103, s28
	v_add3_u32 v101, v114, v101, s28
	v_add3_u32 v100, v115, v100, s28
	v_and_b32_e32 v99, 0xffff0000, v99
	v_and_b32_e32 v98, 0xffff0000, v98
	v_or_b32_sdwa v99, v99, v100 dst_sel:DWORD dst_unused:UNUSED_PAD src0_sel:DWORD src1_sel:WORD_1
	v_or_b32_sdwa v98, v98, v101 dst_sel:DWORD dst_unused:UNUSED_PAD src0_sel:DWORD src1_sel:WORD_1
	global_store_dwordx2 v[112:113], v[98:99], off offset:96
	v_mul_f32_e32 v99, 0xbfb8aa3b, v94
	v_exp_f32_e32 v100, v99
	v_mul_f32_e32 v99, 0xbfb8aa3b, v95
	v_mul_f32_e32 v102, 0xbfb8aa3b, v96
	v_exp_f32_e32 v101, v99
	v_exp_f32_e32 v103, v102
	v_mul_f32_e32 v102, 0xbfb8aa3b, v97
	v_exp_f32_e32 v104, v102
	v_add_f32_e32 v101, 1.0, v101
	v_add_f32_e32 v100, 1.0, v100
	v_rcp_f32_e32 v102, v101
	v_add_f32_e32 v101, 1.0, v103
	v_add_f32_e32 v103, 1.0, v104
	v_rcp_f32_e32 v100, v100
	v_rcp_f32_e32 v101, v101
	v_rcp_f32_e32 v103, v103
	v_mov_b32_e32 v104, v94
	v_mov_b32_e32 v105, v96
	v_mov_b32_e32 v96, v95
	v_pk_mul_f32 v[100:101], v[104:105], v[100:101]
	v_mov_b32_e32 v105, v92
	v_pk_mul_f32 v[94:95], v[96:97], v[102:103]
	v_mov_b32_e32 v92, v91
	v_mov_b32_e32 v104, v90
	v_pk_mul_f32 v[90:91], v[92:93], v[94:95]
	v_pk_mul_f32 v[100:101], v[104:105], v[100:101]
	v_and_b32_sdwa v94, v91, v177 dst_sel:DWORD dst_unused:UNUSED_PAD src0_sel:WORD_1 src1_sel:DWORD
	v_and_b32_sdwa v92, v101, v177 dst_sel:DWORD dst_unused:UNUSED_PAD src0_sel:WORD_1 src1_sel:DWORD
	v_and_b32_sdwa v95, v90, v177 dst_sel:DWORD dst_unused:UNUSED_PAD src0_sel:WORD_1 src1_sel:DWORD
	v_add3_u32 v91, v91, v94, s28
	v_and_b32_sdwa v93, v100, v177 dst_sel:DWORD dst_unused:UNUSED_PAD src0_sel:WORD_1 src1_sel:DWORD
	v_add3_u32 v92, v101, v92, s28
	v_add3_u32 v90, v90, v95, s28
	v_and_b32_e32 v91, 0xffff0000, v91
	v_add3_u32 v93, v100, v93, s28
	v_and_b32_e32 v90, 0xffff0000, v90
	v_or_b32_sdwa v91, v91, v92 dst_sel:DWORD dst_unused:UNUSED_PAD src0_sel:DWORD src1_sel:WORD_1
	v_mul_f32_e32 v92, 0xbfb8aa3b, v86
	v_or_b32_sdwa v90, v90, v93 dst_sel:DWORD dst_unused:UNUSED_PAD src0_sel:DWORD src1_sel:WORD_1
	v_exp_f32_e32 v92, v92
	v_mul_f32_e32 v93, 0xbfb8aa3b, v87
	v_or_b32_e32 v98, 16, v110
	v_exp_f32_e32 v93, v93
	v_mad_i64_i32 v[98:99], s[6:7], v98, s52, v[106:107]
	v_lshl_add_u64 v[98:99], v[98:99], 0, v[108:109]
	global_store_dwordx2 v[98:99], v[90:91], off
	v_add_f32_e32 v90, 1.0, v92
	v_mul_f32_e32 v92, 0xbfb8aa3b, v88
	v_add_f32_e32 v91, 1.0, v93
	v_exp_f32_e32 v93, v92
	v_mul_f32_e32 v92, 0xbfb8aa3b, v89
	v_exp_f32_e32 v94, v92
	v_rcp_f32_e32 v92, v91
	v_add_f32_e32 v91, 1.0, v93
	v_rcp_f32_e32 v90, v90
	v_add_f32_e32 v93, 1.0, v94
	v_rcp_f32_e32 v91, v91
	v_rcp_f32_e32 v93, v93
	v_mov_b32_e32 v94, v86
	v_mov_b32_e32 v95, v88
	v_mov_b32_e32 v88, v87
	v_pk_mul_f32 v[90:91], v[94:95], v[90:91]
	v_mov_b32_e32 v95, v84
	v_pk_mul_f32 v[86:87], v[88:89], v[92:93]
	v_mov_b32_e32 v84, v83
	v_mov_b32_e32 v94, v82
	v_pk_mul_f32 v[82:83], v[84:85], v[86:87]
	v_pk_mul_f32 v[90:91], v[94:95], v[90:91]
	v_and_b32_sdwa v86, v83, v177 dst_sel:DWORD dst_unused:UNUSED_PAD src0_sel:WORD_1 src1_sel:DWORD
	v_and_b32_sdwa v84, v91, v177 dst_sel:DWORD dst_unused:UNUSED_PAD src0_sel:WORD_1 src1_sel:DWORD
	v_and_b32_sdwa v87, v82, v177 dst_sel:DWORD dst_unused:UNUSED_PAD src0_sel:WORD_1 src1_sel:DWORD
	v_add3_u32 v83, v83, v86, s28
	v_and_b32_sdwa v85, v90, v177 dst_sel:DWORD dst_unused:UNUSED_PAD src0_sel:WORD_1 src1_sel:DWORD
	v_add3_u32 v84, v91, v84, s28
	v_add3_u32 v82, v82, v87, s28
	v_and_b32_e32 v83, 0xffff0000, v83
	v_add3_u32 v85, v90, v85, s28
	v_and_b32_e32 v82, 0xffff0000, v82
	v_or_b32_sdwa v83, v83, v84 dst_sel:DWORD dst_unused:UNUSED_PAD src0_sel:DWORD src1_sel:WORD_1
	v_mul_f32_e32 v84, 0xbfb8aa3b, v78
	v_or_b32_sdwa v82, v82, v85 dst_sel:DWORD dst_unused:UNUSED_PAD src0_sel:DWORD src1_sel:WORD_1
	v_exp_f32_e32 v84, v84
	v_mul_f32_e32 v85, 0xbfb8aa3b, v79
	v_exp_f32_e32 v85, v85
	global_store_dwordx2 v[98:99], v[82:83], off offset:32
	v_add_f32_e32 v82, 1.0, v84
	v_mul_f32_e32 v84, 0xbfb8aa3b, v80
	v_add_f32_e32 v83, 1.0, v85
	v_exp_f32_e32 v85, v84
	v_mul_f32_e32 v84, 0xbfb8aa3b, v81
	v_exp_f32_e32 v86, v84
	v_rcp_f32_e32 v84, v83
	v_add_f32_e32 v83, 1.0, v85
	v_rcp_f32_e32 v82, v82
	v_add_f32_e32 v85, 1.0, v86
	v_rcp_f32_e32 v83, v83
	v_rcp_f32_e32 v85, v85
	v_mov_b32_e32 v86, v78
	v_mov_b32_e32 v87, v80
	v_mov_b32_e32 v80, v79
	v_pk_mul_f32 v[82:83], v[86:87], v[82:83]
	v_mov_b32_e32 v87, v76
	v_pk_mul_f32 v[78:79], v[80:81], v[84:85]
	v_mov_b32_e32 v76, v75
	v_mov_b32_e32 v86, v74
	v_pk_mul_f32 v[74:75], v[76:77], v[78:79]
	v_pk_mul_f32 v[82:83], v[86:87], v[82:83]
	v_and_b32_sdwa v78, v75, v177 dst_sel:DWORD dst_unused:UNUSED_PAD src0_sel:WORD_1 src1_sel:DWORD
	v_and_b32_sdwa v76, v83, v177 dst_sel:DWORD dst_unused:UNUSED_PAD src0_sel:WORD_1 src1_sel:DWORD
	v_and_b32_sdwa v79, v74, v177 dst_sel:DWORD dst_unused:UNUSED_PAD src0_sel:WORD_1 src1_sel:DWORD
	v_add3_u32 v75, v75, v78, s28
	v_and_b32_sdwa v77, v82, v177 dst_sel:DWORD dst_unused:UNUSED_PAD src0_sel:WORD_1 src1_sel:DWORD
	v_add3_u32 v76, v83, v76, s28
	v_add3_u32 v74, v74, v79, s28
	v_and_b32_e32 v75, 0xffff0000, v75
	v_add3_u32 v77, v82, v77, s28
	v_and_b32_e32 v74, 0xffff0000, v74
	v_or_b32_sdwa v75, v75, v76 dst_sel:DWORD dst_unused:UNUSED_PAD src0_sel:DWORD src1_sel:WORD_1
	v_mul_f32_e32 v76, 0xbfb8aa3b, v70
	v_or_b32_sdwa v74, v74, v77 dst_sel:DWORD dst_unused:UNUSED_PAD src0_sel:DWORD src1_sel:WORD_1
	v_exp_f32_e32 v76, v76
	v_mul_f32_e32 v77, 0xbfb8aa3b, v71
	v_exp_f32_e32 v77, v77
	global_store_dwordx2 v[98:99], v[74:75], off offset:64
	v_add_f32_e32 v74, 1.0, v76
	v_mul_f32_e32 v76, 0xbfb8aa3b, v72
	v_add_f32_e32 v75, 1.0, v77
	v_exp_f32_e32 v77, v76
	v_mul_f32_e32 v76, 0xbfb8aa3b, v73
	v_exp_f32_e32 v78, v76
	v_rcp_f32_e32 v76, v75
	v_add_f32_e32 v75, 1.0, v77
	v_rcp_f32_e32 v74, v74
	v_add_f32_e32 v77, 1.0, v78
	v_rcp_f32_e32 v75, v75
	v_rcp_f32_e32 v77, v77
	v_mov_b32_e32 v78, v70
	v_mov_b32_e32 v79, v72
	v_mov_b32_e32 v72, v71
	v_pk_mul_f32 v[74:75], v[78:79], v[74:75]
	v_mov_b32_e32 v79, v68
	v_pk_mul_f32 v[70:71], v[72:73], v[76:77]
	v_mov_b32_e32 v68, v67
	v_mov_b32_e32 v78, v66
	v_pk_mul_f32 v[66:67], v[68:69], v[70:71]
	v_pk_mul_f32 v[74:75], v[78:79], v[74:75]
	v_and_b32_sdwa v70, v67, v177 dst_sel:DWORD dst_unused:UNUSED_PAD src0_sel:WORD_1 src1_sel:DWORD
	v_and_b32_sdwa v71, v66, v177 dst_sel:DWORD dst_unused:UNUSED_PAD src0_sel:WORD_1 src1_sel:DWORD
	v_and_b32_sdwa v68, v75, v177 dst_sel:DWORD dst_unused:UNUSED_PAD src0_sel:WORD_1 src1_sel:DWORD
	v_and_b32_sdwa v69, v74, v177 dst_sel:DWORD dst_unused:UNUSED_PAD src0_sel:WORD_1 src1_sel:DWORD
	v_add3_u32 v67, v67, v70, s28
	v_add3_u32 v66, v66, v71, s28
	v_add3_u32 v69, v74, v69, s28
	v_add3_u32 v68, v75, v68, s28
	v_and_b32_e32 v67, 0xffff0000, v67
	v_and_b32_e32 v66, 0xffff0000, v66
	v_or_b32_sdwa v67, v67, v68 dst_sel:DWORD dst_unused:UNUSED_PAD src0_sel:DWORD src1_sel:WORD_1
	v_or_b32_sdwa v66, v66, v69 dst_sel:DWORD dst_unused:UNUSED_PAD src0_sel:DWORD src1_sel:WORD_1
	global_store_dwordx2 v[98:99], v[66:67], off offset:96
	v_mul_f32_e32 v67, 0xbfb8aa3b, v62
	v_exp_f32_e32 v68, v67
	v_mul_f32_e32 v67, 0xbfb8aa3b, v63
	v_mul_f32_e32 v70, 0xbfb8aa3b, v64
	v_exp_f32_e32 v69, v67
	v_exp_f32_e32 v71, v70
	v_mul_f32_e32 v70, 0xbfb8aa3b, v65
	v_exp_f32_e32 v72, v70
	v_add_f32_e32 v69, 1.0, v69
	v_add_f32_e32 v68, 1.0, v68
	v_rcp_f32_e32 v70, v69
	v_add_f32_e32 v69, 1.0, v71
	v_add_f32_e32 v71, 1.0, v72
	v_rcp_f32_e32 v68, v68
	v_rcp_f32_e32 v69, v69
	v_rcp_f32_e32 v71, v71
	v_mov_b32_e32 v72, v62
	v_mov_b32_e32 v73, v64
	v_mov_b32_e32 v64, v63
	v_pk_mul_f32 v[68:69], v[72:73], v[68:69]
	v_mov_b32_e32 v73, v60
	v_pk_mul_f32 v[62:63], v[64:65], v[70:71]
	v_mov_b32_e32 v60, v59
	v_mov_b32_e32 v72, v58
	v_pk_mul_f32 v[58:59], v[60:61], v[62:63]
	v_pk_mul_f32 v[68:69], v[72:73], v[68:69]
	v_and_b32_sdwa v62, v59, v177 dst_sel:DWORD dst_unused:UNUSED_PAD src0_sel:WORD_1 src1_sel:DWORD
	v_and_b32_sdwa v60, v69, v177 dst_sel:DWORD dst_unused:UNUSED_PAD src0_sel:WORD_1 src1_sel:DWORD
	v_and_b32_sdwa v63, v58, v177 dst_sel:DWORD dst_unused:UNUSED_PAD src0_sel:WORD_1 src1_sel:DWORD
	v_add3_u32 v59, v59, v62, s28
	v_and_b32_sdwa v61, v68, v177 dst_sel:DWORD dst_unused:UNUSED_PAD src0_sel:WORD_1 src1_sel:DWORD
	v_add3_u32 v60, v69, v60, s28
	v_add3_u32 v58, v58, v63, s28
	v_and_b32_e32 v59, 0xffff0000, v59
	v_add3_u32 v61, v68, v61, s28
	v_and_b32_e32 v58, 0xffff0000, v58
	v_or_b32_sdwa v59, v59, v60 dst_sel:DWORD dst_unused:UNUSED_PAD src0_sel:DWORD src1_sel:WORD_1
	v_mul_f32_e32 v60, 0xbfb8aa3b, v54
	v_or_b32_sdwa v58, v58, v61 dst_sel:DWORD dst_unused:UNUSED_PAD src0_sel:DWORD src1_sel:WORD_1
	v_exp_f32_e32 v60, v60
	v_mul_f32_e32 v61, 0xbfb8aa3b, v55
	v_or_b32_e32 v66, 32, v110
	v_exp_f32_e32 v61, v61
	v_mad_i64_i32 v[66:67], s[6:7], v66, s52, v[106:107]
	v_lshl_add_u64 v[66:67], v[66:67], 0, v[108:109]
	global_store_dwordx2 v[66:67], v[58:59], off
	v_add_f32_e32 v58, 1.0, v60
	v_mul_f32_e32 v60, 0xbfb8aa3b, v56
	v_add_f32_e32 v59, 1.0, v61
	v_exp_f32_e32 v61, v60
	v_mul_f32_e32 v60, 0xbfb8aa3b, v57
	v_exp_f32_e32 v62, v60
	v_rcp_f32_e32 v60, v59
	v_add_f32_e32 v59, 1.0, v61
	v_rcp_f32_e32 v58, v58
	v_add_f32_e32 v61, 1.0, v62
	v_rcp_f32_e32 v59, v59
	v_rcp_f32_e32 v61, v61
	v_mov_b32_e32 v62, v54
	v_mov_b32_e32 v63, v56
	v_mov_b32_e32 v56, v55
	v_pk_mul_f32 v[58:59], v[62:63], v[58:59]
	v_mov_b32_e32 v63, v52
	v_pk_mul_f32 v[54:55], v[56:57], v[60:61]
	v_mov_b32_e32 v52, v51
	v_mov_b32_e32 v62, v50
	v_pk_mul_f32 v[50:51], v[52:53], v[54:55]
	v_pk_mul_f32 v[58:59], v[62:63], v[58:59]
	v_and_b32_sdwa v54, v51, v177 dst_sel:DWORD dst_unused:UNUSED_PAD src0_sel:WORD_1 src1_sel:DWORD
	v_and_b32_sdwa v52, v59, v177 dst_sel:DWORD dst_unused:UNUSED_PAD src0_sel:WORD_1 src1_sel:DWORD
	v_and_b32_sdwa v55, v50, v177 dst_sel:DWORD dst_unused:UNUSED_PAD src0_sel:WORD_1 src1_sel:DWORD
	v_add3_u32 v51, v51, v54, s28
	v_and_b32_sdwa v53, v58, v177 dst_sel:DWORD dst_unused:UNUSED_PAD src0_sel:WORD_1 src1_sel:DWORD
	v_add3_u32 v52, v59, v52, s28
	v_add3_u32 v50, v50, v55, s28
	v_and_b32_e32 v51, 0xffff0000, v51
	v_add3_u32 v53, v58, v53, s28
	v_and_b32_e32 v50, 0xffff0000, v50
	v_or_b32_sdwa v51, v51, v52 dst_sel:DWORD dst_unused:UNUSED_PAD src0_sel:DWORD src1_sel:WORD_1
	v_mul_f32_e32 v52, 0xbfb8aa3b, v46
	v_or_b32_sdwa v50, v50, v53 dst_sel:DWORD dst_unused:UNUSED_PAD src0_sel:DWORD src1_sel:WORD_1
	v_exp_f32_e32 v52, v52
	v_mul_f32_e32 v53, 0xbfb8aa3b, v47
	v_exp_f32_e32 v53, v53
	global_store_dwordx2 v[66:67], v[50:51], off offset:32
	v_add_f32_e32 v50, 1.0, v52
	v_mul_f32_e32 v52, 0xbfb8aa3b, v48
	v_add_f32_e32 v51, 1.0, v53
	v_exp_f32_e32 v53, v52
	v_mul_f32_e32 v52, 0xbfb8aa3b, v49
	v_exp_f32_e32 v54, v52
	v_rcp_f32_e32 v52, v51
	v_add_f32_e32 v51, 1.0, v53
	v_rcp_f32_e32 v50, v50
	v_add_f32_e32 v53, 1.0, v54
	v_rcp_f32_e32 v51, v51
	v_rcp_f32_e32 v53, v53
	v_mov_b32_e32 v54, v46
	v_mov_b32_e32 v55, v48
	v_mov_b32_e32 v48, v47
	v_pk_mul_f32 v[50:51], v[54:55], v[50:51]
	v_mov_b32_e32 v55, v44
	v_pk_mul_f32 v[46:47], v[48:49], v[52:53]
	v_mov_b32_e32 v44, v43
	v_mov_b32_e32 v54, v42
	v_pk_mul_f32 v[42:43], v[44:45], v[46:47]
	v_pk_mul_f32 v[50:51], v[54:55], v[50:51]
	v_and_b32_sdwa v46, v43, v177 dst_sel:DWORD dst_unused:UNUSED_PAD src0_sel:WORD_1 src1_sel:DWORD
	v_and_b32_sdwa v44, v51, v177 dst_sel:DWORD dst_unused:UNUSED_PAD src0_sel:WORD_1 src1_sel:DWORD
	v_and_b32_sdwa v47, v42, v177 dst_sel:DWORD dst_unused:UNUSED_PAD src0_sel:WORD_1 src1_sel:DWORD
	v_add3_u32 v43, v43, v46, s28
	v_and_b32_sdwa v45, v50, v177 dst_sel:DWORD dst_unused:UNUSED_PAD src0_sel:WORD_1 src1_sel:DWORD
	v_add3_u32 v44, v51, v44, s28
	v_add3_u32 v42, v42, v47, s28
	v_and_b32_e32 v43, 0xffff0000, v43
	v_add3_u32 v45, v50, v45, s28
	v_and_b32_e32 v42, 0xffff0000, v42
	v_or_b32_sdwa v43, v43, v44 dst_sel:DWORD dst_unused:UNUSED_PAD src0_sel:DWORD src1_sel:WORD_1
	v_mul_f32_e32 v44, 0xbfb8aa3b, v38
	v_or_b32_sdwa v42, v42, v45 dst_sel:DWORD dst_unused:UNUSED_PAD src0_sel:DWORD src1_sel:WORD_1
	v_exp_f32_e32 v44, v44
	v_mul_f32_e32 v45, 0xbfb8aa3b, v39
	v_exp_f32_e32 v45, v45
	global_store_dwordx2 v[66:67], v[42:43], off offset:64
	v_add_f32_e32 v42, 1.0, v44
	v_mul_f32_e32 v44, 0xbfb8aa3b, v40
	v_add_f32_e32 v43, 1.0, v45
	v_exp_f32_e32 v45, v44
	v_mul_f32_e32 v44, 0xbfb8aa3b, v41
	v_exp_f32_e32 v46, v44
	v_rcp_f32_e32 v44, v43
	v_add_f32_e32 v43, 1.0, v45
	v_rcp_f32_e32 v42, v42
	v_add_f32_e32 v45, 1.0, v46
	v_rcp_f32_e32 v43, v43
	v_rcp_f32_e32 v45, v45
	v_mov_b32_e32 v46, v38
	v_mov_b32_e32 v47, v40
	v_mov_b32_e32 v40, v39
	v_pk_mul_f32 v[42:43], v[46:47], v[42:43]
	v_mov_b32_e32 v47, v36
	v_pk_mul_f32 v[38:39], v[40:41], v[44:45]
	v_mov_b32_e32 v36, v35
	v_mov_b32_e32 v46, v34
	v_pk_mul_f32 v[34:35], v[36:37], v[38:39]
	v_pk_mul_f32 v[42:43], v[46:47], v[42:43]
	v_and_b32_sdwa v38, v35, v177 dst_sel:DWORD dst_unused:UNUSED_PAD src0_sel:WORD_1 src1_sel:DWORD
	v_and_b32_sdwa v39, v34, v177 dst_sel:DWORD dst_unused:UNUSED_PAD src0_sel:WORD_1 src1_sel:DWORD
	v_and_b32_sdwa v36, v43, v177 dst_sel:DWORD dst_unused:UNUSED_PAD src0_sel:WORD_1 src1_sel:DWORD
	v_and_b32_sdwa v37, v42, v177 dst_sel:DWORD dst_unused:UNUSED_PAD src0_sel:WORD_1 src1_sel:DWORD
	v_add3_u32 v35, v35, v38, s28
	v_add3_u32 v34, v34, v39, s28
	v_add3_u32 v37, v42, v37, s28
	v_add3_u32 v36, v43, v36, s28
	v_and_b32_e32 v35, 0xffff0000, v35
	v_and_b32_e32 v34, 0xffff0000, v34
	v_or_b32_sdwa v35, v35, v36 dst_sel:DWORD dst_unused:UNUSED_PAD src0_sel:DWORD src1_sel:WORD_1
	v_or_b32_sdwa v34, v34, v37 dst_sel:DWORD dst_unused:UNUSED_PAD src0_sel:DWORD src1_sel:WORD_1
	global_store_dwordx2 v[66:67], v[34:35], off offset:96
	v_mul_f32_e32 v35, 0xbfb8aa3b, v30
	v_exp_f32_e32 v36, v35
	v_mul_f32_e32 v35, 0xbfb8aa3b, v31
	v_mul_f32_e32 v38, 0xbfb8aa3b, v32
	v_exp_f32_e32 v37, v35
	v_exp_f32_e32 v39, v38
	v_mul_f32_e32 v38, 0xbfb8aa3b, v33
	v_exp_f32_e32 v40, v38
	v_add_f32_e32 v37, 1.0, v37
	v_add_f32_e32 v36, 1.0, v36
	v_rcp_f32_e32 v38, v37
	v_add_f32_e32 v37, 1.0, v39
	v_add_f32_e32 v39, 1.0, v40
	v_rcp_f32_e32 v36, v36
	v_rcp_f32_e32 v37, v37
	v_rcp_f32_e32 v39, v39
	v_mov_b32_e32 v40, v30
	v_mov_b32_e32 v41, v32
	v_mov_b32_e32 v32, v31
	v_pk_mul_f32 v[36:37], v[40:41], v[36:37]
	v_mov_b32_e32 v41, v28
	v_pk_mul_f32 v[30:31], v[32:33], v[38:39]
	v_mov_b32_e32 v28, v27
	v_mov_b32_e32 v40, v26
	v_pk_mul_f32 v[26:27], v[28:29], v[30:31]
	v_pk_mul_f32 v[36:37], v[40:41], v[36:37]
	v_and_b32_sdwa v30, v27, v177 dst_sel:DWORD dst_unused:UNUSED_PAD src0_sel:WORD_1 src1_sel:DWORD
	v_and_b32_sdwa v28, v37, v177 dst_sel:DWORD dst_unused:UNUSED_PAD src0_sel:WORD_1 src1_sel:DWORD
	v_and_b32_sdwa v31, v26, v177 dst_sel:DWORD dst_unused:UNUSED_PAD src0_sel:WORD_1 src1_sel:DWORD
	v_add3_u32 v27, v27, v30, s28
	v_and_b32_sdwa v29, v36, v177 dst_sel:DWORD dst_unused:UNUSED_PAD src0_sel:WORD_1 src1_sel:DWORD
	v_add3_u32 v28, v37, v28, s28
	v_add3_u32 v26, v26, v31, s28
	v_and_b32_e32 v27, 0xffff0000, v27
	v_add3_u32 v29, v36, v29, s28
	v_and_b32_e32 v26, 0xffff0000, v26
	v_or_b32_sdwa v27, v27, v28 dst_sel:DWORD dst_unused:UNUSED_PAD src0_sel:DWORD src1_sel:WORD_1
	v_mul_f32_e32 v28, 0xbfb8aa3b, v22
	v_or_b32_sdwa v26, v26, v29 dst_sel:DWORD dst_unused:UNUSED_PAD src0_sel:DWORD src1_sel:WORD_1
	v_exp_f32_e32 v28, v28
	v_mul_f32_e32 v29, 0xbfb8aa3b, v23
	v_or_b32_e32 v34, 48, v110
	v_exp_f32_e32 v29, v29
	v_mad_i64_i32 v[34:35], s[6:7], v34, s52, v[106:107]
	v_lshl_add_u64 v[34:35], v[34:35], 0, v[108:109]
	global_store_dwordx2 v[34:35], v[26:27], off
	v_add_f32_e32 v26, 1.0, v28
	v_mul_f32_e32 v28, 0xbfb8aa3b, v24
	v_add_f32_e32 v27, 1.0, v29
	v_exp_f32_e32 v29, v28
	v_mul_f32_e32 v28, 0xbfb8aa3b, v25
	v_exp_f32_e32 v30, v28
	v_rcp_f32_e32 v28, v27
	v_add_f32_e32 v27, 1.0, v29
	v_rcp_f32_e32 v26, v26
	v_add_f32_e32 v29, 1.0, v30
	v_rcp_f32_e32 v27, v27
	v_rcp_f32_e32 v29, v29
	v_mov_b32_e32 v30, v22
	v_mov_b32_e32 v31, v24
	v_mov_b32_e32 v24, v23
	v_pk_mul_f32 v[26:27], v[30:31], v[26:27]
	v_mov_b32_e32 v31, v20
	v_pk_mul_f32 v[22:23], v[24:25], v[28:29]
	v_mov_b32_e32 v20, v19
	v_mov_b32_e32 v30, v18
	v_pk_mul_f32 v[18:19], v[20:21], v[22:23]
	v_pk_mul_f32 v[26:27], v[30:31], v[26:27]
	v_and_b32_sdwa v22, v19, v177 dst_sel:DWORD dst_unused:UNUSED_PAD src0_sel:WORD_1 src1_sel:DWORD
	v_and_b32_sdwa v20, v27, v177 dst_sel:DWORD dst_unused:UNUSED_PAD src0_sel:WORD_1 src1_sel:DWORD
	v_and_b32_sdwa v23, v18, v177 dst_sel:DWORD dst_unused:UNUSED_PAD src0_sel:WORD_1 src1_sel:DWORD
	v_add3_u32 v19, v19, v22, s28
	v_and_b32_sdwa v21, v26, v177 dst_sel:DWORD dst_unused:UNUSED_PAD src0_sel:WORD_1 src1_sel:DWORD
	v_add3_u32 v20, v27, v20, s28
	v_add3_u32 v18, v18, v23, s28
	v_and_b32_e32 v19, 0xffff0000, v19
	v_add3_u32 v21, v26, v21, s28
	v_and_b32_e32 v18, 0xffff0000, v18
	v_or_b32_sdwa v19, v19, v20 dst_sel:DWORD dst_unused:UNUSED_PAD src0_sel:DWORD src1_sel:WORD_1
	v_mul_f32_e32 v20, 0xbfb8aa3b, v14
	v_or_b32_sdwa v18, v18, v21 dst_sel:DWORD dst_unused:UNUSED_PAD src0_sel:DWORD src1_sel:WORD_1
	v_exp_f32_e32 v20, v20
	v_mul_f32_e32 v21, 0xbfb8aa3b, v15
	v_exp_f32_e32 v21, v21
	global_store_dwordx2 v[34:35], v[18:19], off offset:32
	v_add_f32_e32 v18, 1.0, v20
	v_mul_f32_e32 v20, 0xbfb8aa3b, v16
	v_add_f32_e32 v19, 1.0, v21
	v_exp_f32_e32 v21, v20
	v_mul_f32_e32 v20, 0xbfb8aa3b, v17
	v_exp_f32_e32 v22, v20
	v_rcp_f32_e32 v20, v19
	v_add_f32_e32 v19, 1.0, v21
	v_rcp_f32_e32 v18, v18
	v_add_f32_e32 v21, 1.0, v22
	v_rcp_f32_e32 v19, v19
	v_rcp_f32_e32 v21, v21
	v_mov_b32_e32 v22, v14
	v_mov_b32_e32 v23, v16
	v_mov_b32_e32 v16, v15
	v_pk_mul_f32 v[18:19], v[22:23], v[18:19]
	v_mov_b32_e32 v23, v12
	v_pk_mul_f32 v[14:15], v[16:17], v[20:21]
	v_mov_b32_e32 v12, v11
	v_mov_b32_e32 v22, v10
	v_pk_mul_f32 v[10:11], v[12:13], v[14:15]
	v_pk_mul_f32 v[18:19], v[22:23], v[18:19]
	v_and_b32_sdwa v14, v11, v177 dst_sel:DWORD dst_unused:UNUSED_PAD src0_sel:WORD_1 src1_sel:DWORD
	v_and_b32_sdwa v12, v19, v177 dst_sel:DWORD dst_unused:UNUSED_PAD src0_sel:WORD_1 src1_sel:DWORD
	v_and_b32_sdwa v15, v10, v177 dst_sel:DWORD dst_unused:UNUSED_PAD src0_sel:WORD_1 src1_sel:DWORD
	v_add3_u32 v11, v11, v14, s28
	v_and_b32_sdwa v13, v18, v177 dst_sel:DWORD dst_unused:UNUSED_PAD src0_sel:WORD_1 src1_sel:DWORD
	v_add3_u32 v12, v19, v12, s28
	v_add3_u32 v10, v10, v15, s28
	v_and_b32_e32 v11, 0xffff0000, v11
	v_add3_u32 v13, v18, v13, s28
	v_and_b32_e32 v10, 0xffff0000, v10
	v_or_b32_sdwa v11, v11, v12 dst_sel:DWORD dst_unused:UNUSED_PAD src0_sel:DWORD src1_sel:WORD_1
	v_mul_f32_e32 v12, 0xbfb8aa3b, v6
	v_or_b32_sdwa v10, v10, v13 dst_sel:DWORD dst_unused:UNUSED_PAD src0_sel:DWORD src1_sel:WORD_1
	v_exp_f32_e32 v12, v12
	v_mul_f32_e32 v13, 0xbfb8aa3b, v7
	v_exp_f32_e32 v13, v13
	global_store_dwordx2 v[34:35], v[10:11], off offset:64
	v_add_f32_e32 v10, 1.0, v12
	v_mul_f32_e32 v12, 0xbfb8aa3b, v8
	v_add_f32_e32 v11, 1.0, v13
	v_exp_f32_e32 v13, v12
	v_mul_f32_e32 v12, 0xbfb8aa3b, v9
	v_exp_f32_e32 v14, v12
	v_rcp_f32_e32 v12, v11
	v_add_f32_e32 v11, 1.0, v13
	v_rcp_f32_e32 v10, v10
	v_add_f32_e32 v13, 1.0, v14
	v_rcp_f32_e32 v11, v11
	v_rcp_f32_e32 v13, v13
	v_mov_b32_e32 v14, v6
	v_mov_b32_e32 v15, v8
	v_mov_b32_e32 v8, v7
	v_pk_mul_f32 v[10:11], v[14:15], v[10:11]
	v_mov_b32_e32 v15, v4
	v_pk_mul_f32 v[6:7], v[8:9], v[12:13]
	v_mov_b32_e32 v4, v3
	v_mov_b32_e32 v14, v2
	v_pk_mul_f32 v[2:3], v[4:5], v[6:7]
	v_pk_mul_f32 v[10:11], v[14:15], v[10:11]
	v_and_b32_sdwa v6, v3, v177 dst_sel:DWORD dst_unused:UNUSED_PAD src0_sel:WORD_1 src1_sel:DWORD
	v_and_b32_sdwa v7, v2, v177 dst_sel:DWORD dst_unused:UNUSED_PAD src0_sel:WORD_1 src1_sel:DWORD
	v_and_b32_sdwa v4, v11, v177 dst_sel:DWORD dst_unused:UNUSED_PAD src0_sel:WORD_1 src1_sel:DWORD
	v_and_b32_sdwa v5, v10, v177 dst_sel:DWORD dst_unused:UNUSED_PAD src0_sel:WORD_1 src1_sel:DWORD
	v_add3_u32 v3, v3, v6, s28
	v_add3_u32 v2, v2, v7, s28
	v_add3_u32 v5, v10, v5, s28
	v_add3_u32 v4, v11, v4, s28
	v_and_b32_e32 v3, 0xffff0000, v3
	v_and_b32_e32 v2, 0xffff0000, v2
	s_add_i32 s14, s14, s11
	v_or_b32_sdwa v3, v3, v4 dst_sel:DWORD dst_unused:UNUSED_PAD src0_sel:DWORD src1_sel:WORD_1
	v_or_b32_sdwa v2, v2, v5 dst_sel:DWORD dst_unused:UNUSED_PAD src0_sel:DWORD src1_sel:WORD_1
	s_cmpk_gt_i32 s14, 0x5ff
	global_store_dwordx2 v[34:35], v[2:3], off offset:96
	s_cbranch_scc0 .LBB0_1461

.LBB0_1527:
	s_ashr_i32 s2, s18, 31
	s_lshr_b32 s2, s2, 26
	s_add_i32 s2, s18, s2
	s_and_b32 s3, s2, 0xffffc0
	s_sub_i32 s3, s18, s3
	s_lshl_b32 s7, s3, 8
	v_add_u32_e32 v2, s7, v204
	v_mad_i64_i32 v[168:169], s[20:21], v2, s52, v[162:163]
	v_add_co_u32_e32 v56, vcc, 0x58000, v168
	s_lshl_b32 s2, s2, 2
	s_nop 0
	v_addc_co_u32_e32 v57, vcc, 0, v169, vcc
	s_waitcnt vmcnt(9)
	v_add_co_u32_e32 v58, vcc, 0xb0000, v168
	s_and_b32 s6, s2, 0xffffff00
	s_nop 0
	v_addc_co_u32_e32 v59, vcc, 0, v169, vcc
	v_add_u32_e32 v2, s6, v204
	v_add_co_u32_e32 v60, vcc, 0x108000, v168
	v_mad_i64_i32 v[170:171], s[20:21], v2, s52, v[164:165]
	s_nop 0
	v_addc_co_u32_e32 v61, vcc, 0, v169, vcc
	s_waitcnt vmcnt(8)
	v_add_co_u32_e32 v62, vcc, s92, v170
	s_mov_b32 s19, 0x108000
	s_nop 0
	v_addc_co_u32_e32 v63, vcc, 0, v171, vcc
	v_add_co_u32_e32 v64, vcc, s53, v170
	global_load_dwordx4 v[24:27], v[56:57], off
	global_load_dwordx4 v[28:31], v[58:59], off
	v_addc_co_u32_e32 v65, vcc, 0, v171, vcc
	v_add_co_u32_e32 v66, vcc, s19, v170
	global_load_dwordx4 v[32:35], v[168:169], off
	global_load_dwordx4 v[36:39], v[170:171], off
	global_load_dwordx4 v[40:43], v[60:61], off
	global_load_dwordx4 v[44:47], v[62:63], off
	v_addc_co_u32_e32 v67, vcc, 0, v171, vcc
	global_load_dwordx4 v[48:51], v[64:65], off
	global_load_dwordx4 v[52:55], v[66:67], off
	s_barrier
	global_load_dwordx4 v[118:121], v[168:169], off offset:128
	global_load_dwordx4 v[110:113], v[56:57], off offset:128
	global_load_dwordx4 v[114:117], v[58:59], off offset:128
	global_load_dwordx4 v[130:133], v[60:61], off offset:128
	global_load_dwordx4 v[126:129], v[170:171], off offset:128
	global_load_dwordx4 v[122:125], v[62:63], off offset:128
	global_load_dwordx4 v[142:145], v[64:65], off offset:128
	global_load_dwordx4 v[138:141], v[66:67], off offset:128
	v_readfirstlane_b32 s100, v172
	s_nop 0
	s_lshr_b32 m0, s100, 8
	v_readfirstlane_b32 vcc_lo, v168
	v_readfirstlane_b32 vcc_hi, v169
	v_readfirstlane_b32 s100, v170
	v_readfirstlane_b32 s101, v171
	s_nop 1
	v_subrev_u32_e32 v168, vcc_lo, v168
	v_subrev_u32_e32 v170, s100, v170
	v_mov_b32_e32 v2, 0
	s_mov_b32 s4, 0
	v_mov_b32_e32 v3, v2
	v_mov_b32_e32 v4, v2
	v_mov_b32_e32 v5, v2
	v_mov_b32_e32 v6, v2
	v_mov_b32_e32 v7, v2
	v_mov_b32_e32 v8, v2
	v_mov_b32_e32 v9, v2
	v_mov_b32_e32 v10, v2
	v_mov_b32_e32 v11, v2
	v_mov_b32_e32 v12, v2
	v_mov_b32_e32 v13, v2
	v_mov_b32_e32 v14, v2
	v_mov_b32_e32 v15, v2
	v_mov_b32_e32 v16, v2
	v_mov_b32_e32 v17, v2
	v_mov_b32_e32 v18, v2
	v_mov_b32_e32 v19, v2
	v_mov_b32_e32 v20, v2
	v_mov_b32_e32 v21, v2
	v_mov_b32_e32 v22, v2
	v_mov_b32_e32 v23, v2
	v_mov_b32_e32 v56, v2
	v_mov_b32_e32 v57, v2
	v_mov_b32_e32 v58, v2
	v_mov_b32_e32 v59, v2
	v_mov_b32_e32 v60, v2
	v_mov_b32_e32 v61, v2
	v_mov_b32_e32 v62, v2
	v_mov_b32_e32 v63, v2
	v_mov_b32_e32 v64, v2
	v_mov_b32_e32 v65, v2
	v_mov_b32_e32 v66, v2
	v_mov_b32_e32 v67, v2
	v_mov_b32_e32 v68, v2
	v_mov_b32_e32 v69, v2
	v_mov_b32_e32 v70, v2
	v_mov_b32_e32 v71, v2
	v_mov_b32_e32 v72, v2
	v_mov_b32_e32 v73, v2
	v_mov_b32_e32 v74, v2
	v_mov_b32_e32 v75, v2
	v_mov_b32_e32 v76, v2
	v_mov_b32_e32 v77, v2
	v_mov_b32_e32 v78, v2
	v_mov_b32_e32 v79, v2
	v_mov_b32_e32 v80, v2
	v_mov_b32_e32 v81, v2
	v_mov_b32_e32 v82, v2
	v_mov_b32_e32 v83, v2
	v_mov_b32_e32 v84, v2
	s_waitcnt vmcnt(13)
	ds_write_b128 v166, v[32:35]
	s_waitcnt vmcnt(12)
	ds_write_b128 v166, v[36:39] offset:32768
	ds_write_b128 v166, v[24:27] offset:8192
	ds_write_b128 v166, v[28:31] offset:16384
	s_waitcnt vmcnt(11)
	ds_write_b128 v166, v[40:43] offset:24576
	s_waitcnt vmcnt(10)
	ds_write_b128 v166, v[44:47] offset:40960
	s_waitcnt vmcnt(9)
	ds_write_b128 v166, v[48:51] offset:49152
	s_waitcnt vmcnt(8)
	ds_write_b128 v166, v[52:55] offset:57344
	v_mov_b32_e32 v24, v2
	v_mov_b32_e32 v25, v2
	v_mov_b32_e32 v26, v2
	v_mov_b32_e32 v27, v2
	v_mov_b32_e32 v28, v2
	v_mov_b32_e32 v29, v2
	v_mov_b32_e32 v30, v2
	v_mov_b32_e32 v31, v2
	v_mov_b32_e32 v32, v2
	v_mov_b32_e32 v33, v2
	v_mov_b32_e32 v34, v2
	v_mov_b32_e32 v35, v2
	v_mov_b32_e32 v36, v2
	v_mov_b32_e32 v37, v2
	v_mov_b32_e32 v38, v2
	v_mov_b32_e32 v39, v2
	v_mov_b32_e32 v40, v2
	v_mov_b32_e32 v41, v2
	v_mov_b32_e32 v42, v2
	v_mov_b32_e32 v43, v2
	v_mov_b32_e32 v44, v2
	v_mov_b32_e32 v45, v2
	v_mov_b32_e32 v46, v2
	v_mov_b32_e32 v47, v2
	v_mov_b32_e32 v48, v2
	v_mov_b32_e32 v49, v2
	v_mov_b32_e32 v50, v2
	v_mov_b32_e32 v51, v2
	v_mov_b32_e32 v52, v2
	v_mov_b32_e32 v53, v2
	v_mov_b32_e32 v54, v2
	v_mov_b32_e32 v55, v2
	v_mov_b32_e32 v85, v2
	v_mov_b32_e32 v86, v2
	v_mov_b32_e32 v87, v2
	v_mov_b32_e32 v88, v2
	v_mov_b32_e32 v89, v2
	v_mov_b32_e32 v90, v2
	v_mov_b32_e32 v91, v2
	v_mov_b32_e32 v92, v2
	v_mov_b32_e32 v93, v2
	v_mov_b32_e32 v94, v2
	v_mov_b32_e32 v95, v2
	v_mov_b32_e32 v96, v2
	v_mov_b32_e32 v97, v2
	v_mov_b32_e32 v98, v2
	v_mov_b32_e32 v99, v2
	v_mov_b32_e32 v100, v2
	v_mov_b32_e32 v101, v2
	v_mov_b32_e32 v102, v2
	v_mov_b32_e32 v103, v2
	v_mov_b32_e32 v104, v2
	v_mov_b32_e32 v105, v2
	v_mov_b32_e32 v106, v2
	v_mov_b32_e32 v107, v2
	v_mov_b32_e32 v108, v2
	v_mov_b32_e32 v109, v2
	v_mov_b32_e32 v134, v2
	v_mov_b32_e32 v135, v2
	v_mov_b32_e32 v136, v2
	v_mov_b32_e32 v137, v2
	v_mov_b32_e32 v146, v2
	v_mov_b32_e32 v147, v2
	v_mov_b32_e32 v148, v2
	v_mov_b32_e32 v149, v2
	v_mov_b32_e32 v150, v2
	v_mov_b32_e32 v151, v2
	v_mov_b32_e32 v152, v2
	v_mov_b32_e32 v153, v2
	v_mov_b32_e32 v154, v2
	v_mov_b32_e32 v155, v2
	v_mov_b32_e32 v156, v2
	v_mov_b32_e32 v157, v2
	v_mov_b32_e32 v158, v2
	v_mov_b32_e32 v159, v2
	v_mov_b32_e32 v160, v2
	v_mov_b32_e32 v161, v2
	s_waitcnt lgkmcnt(0)
	s_barrier
	s_cmp_lg_u32 m0, 0
	s_cbranch_scc1 .Lg1_1528
.LBB0_1528:
	s_bitcmp1_b32 s4, 0
	s_cselect_b32 s2, 0x12000, 0
	v_or_b32_e32 v218, s2, v207
	v_add_u32_e32 v214, v218, v0
	v_add_u32_e32 v246, v218, v167
	ds_read_b128 v[184:187], v214
	ds_read_b128 v[218:221], v246 offset:32768
	ds_read_b128 v[198:201], v214 offset:2048
	ds_read_b128 v[210:213], v214 offset:4096
	ds_read_b128 v[214:217], v214 offset:6144
	ds_read_b128 v[222:225], v246 offset:34816
	ds_read_b128 v[226:229], v246 offset:36864
	ds_read_b128 v[230:233], v246 offset:38912
	ds_read_b128 v[234:237], v246 offset:40960
	ds_read_b128 v[238:241], v246 offset:43008
	ds_read_b128 v[242:245], v246 offset:45056
	ds_read_b128 v[246:249], v246 offset:47104
	s_add_i32 s10, s4, 1
	s_bitcmp1_b32 s10, 0
	s_cselect_b32 s3, 0x12000, 0
	v_add_u32_e32 v171, s3, v166
	v_xor_b32_e32 v169, 64, v207
	v_add3_u32 v169, s2, v167, v169
	s_waitcnt lgkmcnt(10)
	v_mfma_f32_16x16x32_bf16 v[158:161], v[218:221], v[184:187], v[158:161]
	s_waitcnt lgkmcnt(9)
	v_mfma_f32_16x16x32_bf16 v[94:97], v[218:221], v[198:201], v[94:97]
	s_waitcnt lgkmcnt(8)
	v_mfma_f32_16x16x32_bf16 v[62:65], v[218:221], v[210:213], v[62:65]
	s_waitcnt lgkmcnt(7)
	v_mfma_f32_16x16x32_bf16 v[30:33], v[218:221], v[214:217], v[30:33]
	ds_read_b128 v[218:221], v169 offset:32768
	s_waitcnt lgkmcnt(7)
	v_mfma_f32_16x16x32_bf16 v[154:157], v[222:225], v[184:187], v[154:157]
	v_mfma_f32_16x16x32_bf16 v[90:93], v[222:225], v[198:201], v[90:93]
	v_mfma_f32_16x16x32_bf16 v[58:61], v[222:225], v[210:213], v[58:61]
	v_mfma_f32_16x16x32_bf16 v[26:29], v[222:225], v[214:217], v[26:29]
	ds_read_b128 v[222:225], v169 offset:34816
	s_waitcnt lgkmcnt(7)
	v_mfma_f32_16x16x32_bf16 v[150:153], v[226:229], v[184:187], v[150:153]
	v_mfma_f32_16x16x32_bf16 v[86:89], v[226:229], v[198:201], v[86:89]
	v_mfma_f32_16x16x32_bf16 v[54:57], v[226:229], v[210:213], v[54:57]
	v_mfma_f32_16x16x32_bf16 v[22:25], v[226:229], v[214:217], v[22:25]
	ds_read_b128 v[226:229], v169 offset:36864
	s_waitcnt lgkmcnt(7)
	v_mfma_f32_16x16x32_bf16 v[146:149], v[230:233], v[184:187], v[146:149]
	v_mfma_f32_16x16x32_bf16 v[82:85], v[230:233], v[198:201], v[82:85]
	v_mfma_f32_16x16x32_bf16 v[50:53], v[230:233], v[210:213], v[50:53]
	v_mfma_f32_16x16x32_bf16 v[18:21], v[230:233], v[214:217], v[18:21]
	ds_read_b128 v[230:233], v169 offset:38912
	s_waitcnt lgkmcnt(7)
	v_mfma_f32_16x16x32_bf16 v[134:137], v[234:237], v[184:187], v[134:137]
	v_mfma_f32_16x16x32_bf16 v[78:81], v[234:237], v[198:201], v[78:81]
	v_mfma_f32_16x16x32_bf16 v[46:49], v[234:237], v[210:213], v[46:49]
	v_mfma_f32_16x16x32_bf16 v[14:17], v[234:237], v[214:217], v[14:17]
	ds_read_b128 v[234:237], v169 offset:40960
	s_waitcnt lgkmcnt(7)
	v_mfma_f32_16x16x32_bf16 v[106:109], v[238:241], v[184:187], v[106:109]
	v_mfma_f32_16x16x32_bf16 v[74:77], v[238:241], v[198:201], v[74:77]
	v_mfma_f32_16x16x32_bf16 v[42:45], v[238:241], v[210:213], v[42:45]
	v_mfma_f32_16x16x32_bf16 v[10:13], v[238:241], v[214:217], v[10:13]
	ds_read_b128 v[238:241], v169 offset:43008
	s_waitcnt lgkmcnt(7)
	v_mfma_f32_16x16x32_bf16 v[102:105], v[242:245], v[184:187], v[102:105]
	v_mfma_f32_16x16x32_bf16 v[70:73], v[242:245], v[198:201], v[70:73]
	v_mfma_f32_16x16x32_bf16 v[38:41], v[242:245], v[210:213], v[38:41]
	v_mfma_f32_16x16x32_bf16 v[6:9], v[242:245], v[214:217], v[6:9]
	ds_read_b128 v[242:245], v169 offset:45056
	s_waitcnt lgkmcnt(7)
	v_mfma_f32_16x16x32_bf16 v[98:101], v[246:249], v[184:187], v[98:101]
	v_mfma_f32_16x16x32_bf16 v[66:69], v[246:249], v[198:201], v[66:69]
	v_xor_b32_e32 v169, 64, v207
	v_add3_u32 v169, s2, v0, v169
	ds_read_b128 v[184:187], v169
	ds_read_b128 v[198:201], v169 offset:2048
	v_mfma_f32_16x16x32_bf16 v[34:37], v[246:249], v[210:213], v[34:37]
	ds_read_b128 v[210:213], v169 offset:4096
	v_mfma_f32_16x16x32_bf16 v[2:5], v[246:249], v[214:217], v[2:5]
	ds_read_b128 v[214:217], v169 offset:6144
	v_xor_b32_e32 v169, 64, v207
	v_add3_u32 v169, s2, v167, v169
	ds_read_b128 v[246:249], v169 offset:47104
	s_waitcnt lgkmcnt(4)
	v_mfma_f32_16x16x32_bf16 v[158:161], v[218:221], v[184:187], v[158:161]
	s_waitcnt lgkmcnt(3)
	v_mfma_f32_16x16x32_bf16 v[94:97], v[218:221], v[198:201], v[94:97]
	s_waitcnt lgkmcnt(2)
	v_mfma_f32_16x16x32_bf16 v[62:65], v[218:221], v[210:213], v[62:65]
	s_waitcnt lgkmcnt(1)
	v_mfma_f32_16x16x32_bf16 v[30:33], v[218:221], v[214:217], v[30:33]
	s_waitcnt vmcnt(7)
	ds_write_b128 v171, v[118:121]
	v_mfma_f32_16x16x32_bf16 v[154:157], v[222:225], v[184:187], v[154:157]
	v_mfma_f32_16x16x32_bf16 v[90:93], v[222:225], v[198:201], v[90:93]
	global_load_dwordx4 v[118:121], v168, vcc offset:256
	v_mfma_f32_16x16x32_bf16 v[58:61], v[222:225], v[210:213], v[58:61]
	v_mfma_f32_16x16x32_bf16 v[26:29], v[222:225], v[214:217], v[26:29]
	s_waitcnt vmcnt(7)
	ds_write_b128 v171, v[110:113] offset:8192
	v_mfma_f32_16x16x32_bf16 v[150:153], v[226:229], v[184:187], v[150:153]
	v_mfma_f32_16x16x32_bf16 v[86:89], v[226:229], v[198:201], v[86:89]
	v_add_u32_e32 v110, 0x58000, v168
	global_load_dwordx4 v[110:113], v110, vcc offset:256
	v_mfma_f32_16x16x32_bf16 v[54:57], v[226:229], v[210:213], v[54:57]
	v_mfma_f32_16x16x32_bf16 v[22:25], v[226:229], v[214:217], v[22:25]
	s_waitcnt vmcnt(7)
	ds_write_b128 v171, v[114:117] offset:16384
	v_mfma_f32_16x16x32_bf16 v[146:149], v[230:233], v[184:187], v[146:149]
	v_mfma_f32_16x16x32_bf16 v[82:85], v[230:233], v[198:201], v[82:85]
	v_add_u32_e32 v114, 0xb0000, v168
	global_load_dwordx4 v[114:117], v114, vcc offset:256
	v_mfma_f32_16x16x32_bf16 v[50:53], v[230:233], v[210:213], v[50:53]
	v_mfma_f32_16x16x32_bf16 v[18:21], v[230:233], v[214:217], v[18:21]
	s_waitcnt vmcnt(7)
	ds_write_b128 v171, v[130:133] offset:24576
	v_mfma_f32_16x16x32_bf16 v[134:137], v[234:237], v[184:187], v[134:137]
	v_mfma_f32_16x16x32_bf16 v[78:81], v[234:237], v[198:201], v[78:81]
	v_add_u32_e32 v130, 0x108000, v168
	global_load_dwordx4 v[130:133], v130, vcc offset:256
	v_mfma_f32_16x16x32_bf16 v[46:49], v[234:237], v[210:213], v[46:49]
	v_mfma_f32_16x16x32_bf16 v[14:17], v[234:237], v[214:217], v[14:17]
	s_waitcnt vmcnt(7)
	ds_write_b128 v171, v[126:129] offset:32768
	v_mfma_f32_16x16x32_bf16 v[106:109], v[238:241], v[184:187], v[106:109]
	v_mfma_f32_16x16x32_bf16 v[74:77], v[238:241], v[198:201], v[74:77]
	global_load_dwordx4 v[126:129], v170, s[100:101] offset:256
	v_mfma_f32_16x16x32_bf16 v[42:45], v[238:241], v[210:213], v[42:45]
	v_mfma_f32_16x16x32_bf16 v[10:13], v[238:241], v[214:217], v[10:13]
	s_waitcnt vmcnt(7)
	ds_write_b128 v171, v[122:125] offset:40960
	v_mfma_f32_16x16x32_bf16 v[102:105], v[242:245], v[184:187], v[102:105]
	v_mfma_f32_16x16x32_bf16 v[70:73], v[242:245], v[198:201], v[70:73]
	v_add_u32_e32 v122, 0x58000, v170
	global_load_dwordx4 v[122:125], v122, s[100:101] offset:256
	v_mfma_f32_16x16x32_bf16 v[38:41], v[242:245], v[210:213], v[38:41]
	v_mfma_f32_16x16x32_bf16 v[6:9], v[242:245], v[214:217], v[6:9]
	s_waitcnt vmcnt(7)
	ds_write_b128 v171, v[142:145] offset:49152
	s_waitcnt lgkmcnt(7)
	v_mfma_f32_16x16x32_bf16 v[98:101], v[246:249], v[184:187], v[98:101]
	v_mfma_f32_16x16x32_bf16 v[66:69], v[246:249], v[198:201], v[66:69]
	v_add_u32_e32 v142, 0xb0000, v170
	global_load_dwordx4 v[142:145], v142, s[100:101] offset:256
	v_mfma_f32_16x16x32_bf16 v[34:37], v[246:249], v[210:213], v[34:37]
	v_mfma_f32_16x16x32_bf16 v[2:5], v[246:249], v[214:217], v[2:5]
	s_waitcnt vmcnt(7)
	ds_write_b128 v171, v[138:141] offset:57344
	v_add_u32_e32 v138, 0x108000, v170
	global_load_dwordx4 v[138:141], v138, s[100:101] offset:256
	v_add_u32_e32 v168, 0x80, v168
	v_add_u32_e32 v170, 0x80, v170
	s_waitcnt lgkmcnt(0)
	s_barrier
	s_cmp_eq_u32 s10, 44
	s_mov_b32 s4, s10
	s_cbranch_scc0 .LBB0_1528
	s_branch .Lkdone_1528
.Lg1_1528:
	v_add_u32_e32 v171, 0x12000, v166
	s_waitcnt vmcnt(7)
	ds_write_b128 v171, v[118:121]
	global_load_dwordx4 v[118:121], v168, vcc offset:256
	s_waitcnt vmcnt(7)
	ds_write_b128 v171, v[110:113] offset:8192
	v_add_u32_e32 v110, 0x58000, v168
	global_load_dwordx4 v[110:113], v110, vcc offset:256
	s_waitcnt vmcnt(7)
	ds_write_b128 v171, v[114:117] offset:16384
	v_add_u32_e32 v114, 0xb0000, v168
	global_load_dwordx4 v[114:117], v114, vcc offset:256
	s_waitcnt vmcnt(7)
	ds_write_b128 v171, v[130:133] offset:24576
	v_add_u32_e32 v130, 0x108000, v168
	global_load_dwordx4 v[130:133], v130, vcc offset:256
	s_waitcnt vmcnt(7)
	ds_write_b128 v171, v[126:129] offset:32768
	global_load_dwordx4 v[126:129], v170, s[100:101] offset:256
	s_waitcnt vmcnt(7)
	ds_write_b128 v171, v[122:125] offset:40960
	v_add_u32_e32 v122, 0x58000, v170
	global_load_dwordx4 v[122:125], v122, s[100:101] offset:256
	s_waitcnt vmcnt(7)
	ds_write_b128 v171, v[142:145] offset:49152
	v_add_u32_e32 v142, 0xb0000, v170
	global_load_dwordx4 v[142:145], v142, s[100:101] offset:256
	s_waitcnt vmcnt(7)
	ds_write_b128 v171, v[138:141] offset:57344
	v_add_u32_e32 v138, 0x108000, v170
	global_load_dwordx4 v[138:141], v138, s[100:101] offset:256
	v_add_u32_e32 v168, 0x80, v168
	v_add_u32_e32 v170, 0x80, v170
.Lg1loop_1528:
	s_bitcmp1_b32 s4, 0
	s_cselect_b32 s2, 0x12000, 0
	v_or_b32_e32 v218, s2, v207
	v_add_u32_e32 v214, v218, v0
	v_add_u32_e32 v246, v218, v167
	ds_read_b128 v[184:187], v214
	ds_read_b128 v[218:221], v246 offset:32768
	ds_read_b128 v[198:201], v214 offset:2048
	ds_read_b128 v[210:213], v214 offset:4096
	ds_read_b128 v[214:217], v214 offset:6144
	ds_read_b128 v[222:225], v246 offset:34816
	ds_read_b128 v[226:229], v246 offset:36864
	ds_read_b128 v[230:233], v246 offset:38912
	ds_read_b128 v[234:237], v246 offset:40960
	ds_read_b128 v[238:241], v246 offset:43008
	ds_read_b128 v[242:245], v246 offset:45056
	ds_read_b128 v[246:249], v246 offset:47104
	s_add_i32 s10, s4, 1
	s_bitcmp1_b32 s10, 0
	s_cselect_b32 s3, 0x12000, 0
	v_add_u32_e32 v171, s2, v166
	v_xor_b32_e32 v169, 64, v207
	v_add3_u32 v169, s2, v167, v169
	s_waitcnt lgkmcnt(10)
	v_mfma_f32_16x16x32_bf16 v[158:161], v[218:221], v[184:187], v[158:161]
	s_waitcnt lgkmcnt(9)
	v_mfma_f32_16x16x32_bf16 v[94:97], v[218:221], v[198:201], v[94:97]
	s_waitcnt lgkmcnt(8)
	v_mfma_f32_16x16x32_bf16 v[62:65], v[218:221], v[210:213], v[62:65]
	s_waitcnt lgkmcnt(7)
	v_mfma_f32_16x16x32_bf16 v[30:33], v[218:221], v[214:217], v[30:33]
	ds_read_b128 v[218:221], v169 offset:32768
	s_waitcnt lgkmcnt(7)
	v_mfma_f32_16x16x32_bf16 v[154:157], v[222:225], v[184:187], v[154:157]
	v_mfma_f32_16x16x32_bf16 v[90:93], v[222:225], v[198:201], v[90:93]
	v_mfma_f32_16x16x32_bf16 v[58:61], v[222:225], v[210:213], v[58:61]
	v_mfma_f32_16x16x32_bf16 v[26:29], v[222:225], v[214:217], v[26:29]
	ds_read_b128 v[222:225], v169 offset:34816
	s_waitcnt lgkmcnt(7)
	v_mfma_f32_16x16x32_bf16 v[150:153], v[226:229], v[184:187], v[150:153]
	v_mfma_f32_16x16x32_bf16 v[86:89], v[226:229], v[198:201], v[86:89]
	v_mfma_f32_16x16x32_bf16 v[54:57], v[226:229], v[210:213], v[54:57]
	v_mfma_f32_16x16x32_bf16 v[22:25], v[226:229], v[214:217], v[22:25]
	ds_read_b128 v[226:229], v169 offset:36864
	s_waitcnt lgkmcnt(7)
	v_mfma_f32_16x16x32_bf16 v[146:149], v[230:233], v[184:187], v[146:149]
	v_mfma_f32_16x16x32_bf16 v[82:85], v[230:233], v[198:201], v[82:85]
	v_mfma_f32_16x16x32_bf16 v[50:53], v[230:233], v[210:213], v[50:53]
	v_mfma_f32_16x16x32_bf16 v[18:21], v[230:233], v[214:217], v[18:21]
	ds_read_b128 v[230:233], v169 offset:38912
	s_waitcnt lgkmcnt(7)
	v_mfma_f32_16x16x32_bf16 v[134:137], v[234:237], v[184:187], v[134:137]
	v_mfma_f32_16x16x32_bf16 v[78:81], v[234:237], v[198:201], v[78:81]
	v_mfma_f32_16x16x32_bf16 v[46:49], v[234:237], v[210:213], v[46:49]
	v_mfma_f32_16x16x32_bf16 v[14:17], v[234:237], v[214:217], v[14:17]
	ds_read_b128 v[234:237], v169 offset:40960
	s_waitcnt lgkmcnt(7)
	v_mfma_f32_16x16x32_bf16 v[106:109], v[238:241], v[184:187], v[106:109]
	v_mfma_f32_16x16x32_bf16 v[74:77], v[238:241], v[198:201], v[74:77]
	v_mfma_f32_16x16x32_bf16 v[42:45], v[238:241], v[210:213], v[42:45]
	v_mfma_f32_16x16x32_bf16 v[10:13], v[238:241], v[214:217], v[10:13]
	ds_read_b128 v[238:241], v169 offset:43008
	s_waitcnt lgkmcnt(7)
	v_mfma_f32_16x16x32_bf16 v[102:105], v[242:245], v[184:187], v[102:105]
	v_mfma_f32_16x16x32_bf16 v[70:73], v[242:245], v[198:201], v[70:73]
	v_mfma_f32_16x16x32_bf16 v[38:41], v[242:245], v[210:213], v[38:41]
	v_mfma_f32_16x16x32_bf16 v[6:9], v[242:245], v[214:217], v[6:9]
	ds_read_b128 v[242:245], v169 offset:45056
	s_waitcnt lgkmcnt(7)
	v_mfma_f32_16x16x32_bf16 v[98:101], v[246:249], v[184:187], v[98:101]
	v_mfma_f32_16x16x32_bf16 v[66:69], v[246:249], v[198:201], v[66:69]
	v_xor_b32_e32 v169, 64, v207
	v_add3_u32 v169, s2, v0, v169
	ds_read_b128 v[184:187], v169
	ds_read_b128 v[198:201], v169 offset:2048
	v_mfma_f32_16x16x32_bf16 v[34:37], v[246:249], v[210:213], v[34:37]
	ds_read_b128 v[210:213], v169 offset:4096
	v_mfma_f32_16x16x32_bf16 v[2:5], v[246:249], v[214:217], v[2:5]
	ds_read_b128 v[214:217], v169 offset:6144
	v_xor_b32_e32 v169, 64, v207
	v_add3_u32 v169, s2, v167, v169
	ds_read_b128 v[246:249], v169 offset:47104
	s_waitcnt lgkmcnt(0)
	s_barrier
	s_waitcnt lgkmcnt(4)
	v_mfma_f32_16x16x32_bf16 v[158:161], v[218:221], v[184:187], v[158:161]
	s_waitcnt lgkmcnt(3)
	v_mfma_f32_16x16x32_bf16 v[94:97], v[218:221], v[198:201], v[94:97]
	s_waitcnt lgkmcnt(2)
	v_mfma_f32_16x16x32_bf16 v[62:65], v[218:221], v[210:213], v[62:65]
	s_waitcnt lgkmcnt(1)
	v_mfma_f32_16x16x32_bf16 v[30:33], v[218:221], v[214:217], v[30:33]
	s_waitcnt vmcnt(7)
	ds_write_b128 v171, v[118:121]
	v_mfma_f32_16x16x32_bf16 v[154:157], v[222:225], v[184:187], v[154:157]
	v_mfma_f32_16x16x32_bf16 v[90:93], v[222:225], v[198:201], v[90:93]
	global_load_dwordx4 v[118:121], v168, vcc offset:256
	v_mfma_f32_16x16x32_bf16 v[58:61], v[222:225], v[210:213], v[58:61]
	v_mfma_f32_16x16x32_bf16 v[26:29], v[222:225], v[214:217], v[26:29]
	s_waitcnt vmcnt(7)
	ds_write_b128 v171, v[110:113] offset:8192
	v_mfma_f32_16x16x32_bf16 v[150:153], v[226:229], v[184:187], v[150:153]
	v_mfma_f32_16x16x32_bf16 v[86:89], v[226:229], v[198:201], v[86:89]
	v_add_u32_e32 v110, 0x58000, v168
	global_load_dwordx4 v[110:113], v110, vcc offset:256
	v_mfma_f32_16x16x32_bf16 v[54:57], v[226:229], v[210:213], v[54:57]
	v_mfma_f32_16x16x32_bf16 v[22:25], v[226:229], v[214:217], v[22:25]
	s_waitcnt vmcnt(7)
	ds_write_b128 v171, v[114:117] offset:16384
	v_mfma_f32_16x16x32_bf16 v[146:149], v[230:233], v[184:187], v[146:149]
	v_mfma_f32_16x16x32_bf16 v[82:85], v[230:233], v[198:201], v[82:85]
	v_add_u32_e32 v114, 0xb0000, v168
	global_load_dwordx4 v[114:117], v114, vcc offset:256
	v_mfma_f32_16x16x32_bf16 v[50:53], v[230:233], v[210:213], v[50:53]
	v_mfma_f32_16x16x32_bf16 v[18:21], v[230:233], v[214:217], v[18:21]
	s_waitcnt vmcnt(7)
	ds_write_b128 v171, v[130:133] offset:24576
	v_mfma_f32_16x16x32_bf16 v[134:137], v[234:237], v[184:187], v[134:137]
	v_mfma_f32_16x16x32_bf16 v[78:81], v[234:237], v[198:201], v[78:81]
	v_add_u32_e32 v130, 0x108000, v168
	global_load_dwordx4 v[130:133], v130, vcc offset:256
	v_mfma_f32_16x16x32_bf16 v[46:49], v[234:237], v[210:213], v[46:49]
	v_mfma_f32_16x16x32_bf16 v[14:17], v[234:237], v[214:217], v[14:17]
	s_waitcnt vmcnt(7)
	ds_write_b128 v171, v[126:129] offset:32768
	v_mfma_f32_16x16x32_bf16 v[106:109], v[238:241], v[184:187], v[106:109]
	v_mfma_f32_16x16x32_bf16 v[74:77], v[238:241], v[198:201], v[74:77]
	global_load_dwordx4 v[126:129], v170, s[100:101] offset:256
	v_mfma_f32_16x16x32_bf16 v[42:45], v[238:241], v[210:213], v[42:45]
	v_mfma_f32_16x16x32_bf16 v[10:13], v[238:241], v[214:217], v[10:13]
	s_waitcnt vmcnt(7)
	ds_write_b128 v171, v[122:125] offset:40960
	v_mfma_f32_16x16x32_bf16 v[102:105], v[242:245], v[184:187], v[102:105]
	v_mfma_f32_16x16x32_bf16 v[70:73], v[242:245], v[198:201], v[70:73]
	v_add_u32_e32 v122, 0x58000, v170
	global_load_dwordx4 v[122:125], v122, s[100:101] offset:256
	v_mfma_f32_16x16x32_bf16 v[38:41], v[242:245], v[210:213], v[38:41]
	v_mfma_f32_16x16x32_bf16 v[6:9], v[242:245], v[214:217], v[6:9]
	s_waitcnt vmcnt(7)
	ds_write_b128 v171, v[142:145] offset:49152
	s_waitcnt lgkmcnt(7)
	v_mfma_f32_16x16x32_bf16 v[98:101], v[246:249], v[184:187], v[98:101]
	v_mfma_f32_16x16x32_bf16 v[66:69], v[246:249], v[198:201], v[66:69]
	v_add_u32_e32 v142, 0xb0000, v170
	global_load_dwordx4 v[142:145], v142, s[100:101] offset:256
	v_mfma_f32_16x16x32_bf16 v[34:37], v[246:249], v[210:213], v[34:37]
	v_mfma_f32_16x16x32_bf16 v[2:5], v[246:249], v[214:217], v[2:5]
	s_waitcnt vmcnt(7)
	ds_write_b128 v171, v[138:141] offset:57344
	v_add_u32_e32 v138, 0x108000, v170
	global_load_dwordx4 v[138:141], v138, s[100:101] offset:256
	v_add_u32_e32 v168, 0x80, v168
	v_add_u32_e32 v170, 0x80, v170
	s_cmp_eq_u32 s10, 44
	s_mov_b32 s4, s10
	s_cbranch_scc0 .Lg1loop_1528
	s_waitcnt lgkmcnt(0)
.Lkdone_1528:
	s_waitcnt vmcnt(4)
	v_add_u32_e32 v110, s7, v206
	s_waitcnt vmcnt(3)
	v_or_b32_e32 v114, v110, v205
	v_cmp_lt_i32_e32 vcc, s97, v114
	v_ashrrev_i32_e32 v112, 31, v114
	v_add_u32_e32 v116, 0xffffc000, v114
	v_ashrrev_i32_e32 v115, 11, v110
	v_cndmask_b32_e64 v113, v112, 0, vcc
	v_cndmask_b32_e32 v112, v114, v116, vcc
	v_mov_b32_e32 v116, s45
	v_mov_b32_e32 v117, s13
	v_mov_b32_e32 v118, s44
	v_mov_b32_e32 v119, s12
	v_or_b32_e32 v110, s6, v208
	s_waitcnt vmcnt(2)
	v_cndmask_b32_e64 v122, v115, 8, vcc
	v_cndmask_b32_e32 v121, v116, v117, vcc
	v_cndmask_b32_e32 v120, v118, v119, vcc
	v_lshlrev_b64 v[112:113], 12, v[112:113]
	v_ashrrev_i32_e32 v111, 31, v110
	v_lshl_add_u64 v[112:113], v[120:121], 0, v[112:113]
	v_mul_hi_i32_i24_e32 v121, 0x9000, v122
	v_mul_i32_i24_e32 v120, 0x9000, v122
	v_lshl_add_u64 v[120:121], s[14:15], 0, v[120:121]
	v_lshlrev_b64 v[110:111], 2, v[110:111]
	s_waitcnt vmcnt(0)
	v_lshl_add_u64 v[128:129], v[120:121], 0, v[110:111]
	global_load_dwordx4 v[120:123], v[128:129], off
	v_lshl_add_u64 v[112:113], v[112:113], 0, v[110:111]
	global_load_dwordx4 v[124:127], v[112:113], off
	s_waitcnt vmcnt(1)
	v_pk_mul_f32 v[120:121], v[120:121], 0.5 op_sel_hi:[1,0]
	v_pk_mul_f32 v[122:123], v[122:123], 0.5 op_sel_hi:[1,0]
	s_waitcnt vmcnt(0)
	v_pk_fma_f32 v[120:121], v[158:159], v[120:121], v[124:125]
	v_pk_fma_f32 v[122:123], v[160:161], v[122:123], v[126:127]
	global_store_dwordx4 v[112:113], v[120:123], off
	global_load_dwordx4 v[120:123], v[128:129], off offset:64
	s_nop 0
	global_load_dwordx4 v[124:127], v[112:113], off offset:64
	s_waitcnt vmcnt(1)
	v_pk_mul_f32 v[120:121], v[120:121], 0.5 op_sel_hi:[1,0]
	v_pk_mul_f32 v[122:123], v[122:123], 0.5 op_sel_hi:[1,0]
	s_waitcnt vmcnt(0)
	v_pk_fma_f32 v[120:121], v[154:155], v[120:121], v[124:125]
	v_pk_fma_f32 v[122:123], v[156:157], v[122:123], v[126:127]
	global_store_dwordx4 v[112:113], v[120:123], off offset:64
	global_load_dwordx4 v[120:123], v[128:129], off offset:128
	s_nop 0
	global_load_dwordx4 v[124:127], v[112:113], off offset:128
	s_waitcnt vmcnt(1)
	v_pk_mul_f32 v[120:121], v[120:121], 0.5 op_sel_hi:[1,0]
	v_pk_mul_f32 v[122:123], v[122:123], 0.5 op_sel_hi:[1,0]
	s_waitcnt vmcnt(0)
	v_pk_fma_f32 v[120:121], v[150:151], v[120:121], v[124:125]
	v_pk_fma_f32 v[122:123], v[152:153], v[122:123], v[126:127]
	global_store_dwordx4 v[112:113], v[120:123], off offset:128
	global_load_dwordx4 v[120:123], v[128:129], off offset:192
	s_nop 0
	global_load_dwordx4 v[124:127], v[112:113], off offset:192
	s_waitcnt vmcnt(1)
	v_pk_mul_f32 v[120:121], v[120:121], 0.5 op_sel_hi:[1,0]
	v_pk_mul_f32 v[122:123], v[122:123], 0.5 op_sel_hi:[1,0]
	s_waitcnt vmcnt(0)
	v_pk_fma_f32 v[120:121], v[146:147], v[120:121], v[124:125]
	v_pk_fma_f32 v[122:123], v[148:149], v[122:123], v[126:127]
	global_store_dwordx4 v[112:113], v[120:123], off offset:192
	global_load_dwordx4 v[120:123], v[128:129], off offset:256
	s_nop 0
	global_load_dwordx4 v[124:127], v[112:113], off offset:256
	s_waitcnt vmcnt(1)
	v_pk_mul_f32 v[120:121], v[120:121], 0.5 op_sel_hi:[1,0]
	v_pk_mul_f32 v[122:123], v[122:123], 0.5 op_sel_hi:[1,0]
	s_waitcnt vmcnt(0)
	v_pk_fma_f32 v[120:121], v[134:135], v[120:121], v[124:125]
	v_pk_fma_f32 v[122:123], v[136:137], v[122:123], v[126:127]
	global_store_dwordx4 v[112:113], v[120:123], off offset:256
	global_load_dwordx4 v[120:123], v[128:129], off offset:320
	s_nop 0
	global_load_dwordx4 v[124:127], v[112:113], off offset:320
	s_waitcnt vmcnt(1)
	v_pk_mul_f32 v[120:121], v[120:121], 0.5 op_sel_hi:[1,0]
	v_pk_mul_f32 v[122:123], v[122:123], 0.5 op_sel_hi:[1,0]
	s_waitcnt vmcnt(0)
	v_pk_fma_f32 v[106:107], v[106:107], v[120:121], v[124:125]
	v_pk_fma_f32 v[108:109], v[108:109], v[122:123], v[126:127]
	global_store_dwordx4 v[112:113], v[106:109], off offset:320
	global_load_dwordx4 v[106:109], v[128:129], off offset:384
	s_nop 0
	global_load_dwordx4 v[120:123], v[112:113], off offset:384
	s_waitcnt vmcnt(1)
	v_pk_mul_f32 v[106:107], v[106:107], 0.5 op_sel_hi:[1,0]
	v_pk_mul_f32 v[108:109], v[108:109], 0.5 op_sel_hi:[1,0]
	s_waitcnt vmcnt(0)
	v_pk_fma_f32 v[102:103], v[102:103], v[106:107], v[120:121]
	v_pk_fma_f32 v[104:105], v[104:105], v[108:109], v[122:123]
	global_store_dwordx4 v[112:113], v[102:105], off offset:384
	global_load_dwordx4 v[102:105], v[128:129], off offset:448
	s_nop 0
	global_load_dwordx4 v[106:109], v[112:113], off offset:448
	s_waitcnt vmcnt(1)
	v_pk_mul_f32 v[102:103], v[102:103], 0.5 op_sel_hi:[1,0]
	v_pk_mul_f32 v[104:105], v[104:105], 0.5 op_sel_hi:[1,0]
	s_waitcnt vmcnt(0)
	v_pk_fma_f32 v[98:99], v[98:99], v[102:103], v[106:107]
	v_pk_fma_f32 v[100:101], v[100:101], v[104:105], v[108:109]
	global_store_dwordx4 v[112:113], v[98:101], off offset:448
	s_nop 1
	v_or_b32_e32 v98, 16, v114
	v_cmp_lt_i32_e32 vcc, s97, v98
	v_add_u32_e32 v100, 0xffffc010, v114
	v_ashrrev_i32_e32 v99, 31, v98
	v_cndmask_b32_e64 v99, v99, 0, vcc
	v_cndmask_b32_e32 v98, v98, v100, vcc
	v_cndmask_b32_e64 v102, v115, 8, vcc
	v_cndmask_b32_e32 v101, v116, v117, vcc
	v_cndmask_b32_e32 v100, v118, v119, vcc
	v_lshlrev_b64 v[98:99], 12, v[98:99]
	v_lshl_add_u64 v[98:99], v[100:101], 0, v[98:99]
	v_mul_hi_i32_i24_e32 v101, 0x9000, v102
	v_mul_i32_i24_e32 v100, 0x9000, v102
	v_lshl_add_u64 v[100:101], s[14:15], 0, v[100:101]
	v_lshl_add_u64 v[108:109], v[100:101], 0, v[110:111]
	global_load_dwordx4 v[100:103], v[108:109], off
	v_lshl_add_u64 v[98:99], v[98:99], 0, v[110:111]
	global_load_dwordx4 v[104:107], v[98:99], off
	s_waitcnt vmcnt(1)
	v_pk_mul_f32 v[100:101], v[100:101], 0.5 op_sel_hi:[1,0]
	v_pk_mul_f32 v[102:103], v[102:103], 0.5 op_sel_hi:[1,0]
	s_waitcnt vmcnt(0)
	v_pk_fma_f32 v[94:95], v[94:95], v[100:101], v[104:105]
	v_pk_fma_f32 v[96:97], v[96:97], v[102:103], v[106:107]
	global_store_dwordx4 v[98:99], v[94:97], off
	global_load_dwordx4 v[94:97], v[108:109], off offset:64
	s_nop 0
	global_load_dwordx4 v[100:103], v[98:99], off offset:64
	s_waitcnt vmcnt(1)
	v_pk_mul_f32 v[94:95], v[94:95], 0.5 op_sel_hi:[1,0]
	v_pk_mul_f32 v[96:97], v[96:97], 0.5 op_sel_hi:[1,0]
	s_waitcnt vmcnt(0)
	v_pk_fma_f32 v[90:91], v[90:91], v[94:95], v[100:101]
	v_pk_fma_f32 v[92:93], v[92:93], v[96:97], v[102:103]
	global_store_dwordx4 v[98:99], v[90:93], off offset:64
	global_load_dwordx4 v[90:93], v[108:109], off offset:128
	s_nop 0
	global_load_dwordx4 v[94:97], v[98:99], off offset:128
	s_waitcnt vmcnt(1)
	v_pk_mul_f32 v[90:91], v[90:91], 0.5 op_sel_hi:[1,0]
	v_pk_mul_f32 v[92:93], v[92:93], 0.5 op_sel_hi:[1,0]
	s_waitcnt vmcnt(0)
	v_pk_fma_f32 v[86:87], v[86:87], v[90:91], v[94:95]
	v_pk_fma_f32 v[88:89], v[88:89], v[92:93], v[96:97]
	global_store_dwordx4 v[98:99], v[86:89], off offset:128
	global_load_dwordx4 v[86:89], v[108:109], off offset:192
	s_nop 0
	global_load_dwordx4 v[90:93], v[98:99], off offset:192
	s_waitcnt vmcnt(1)
	v_pk_mul_f32 v[86:87], v[86:87], 0.5 op_sel_hi:[1,0]
	v_pk_mul_f32 v[88:89], v[88:89], 0.5 op_sel_hi:[1,0]
	s_waitcnt vmcnt(0)
	v_pk_fma_f32 v[82:83], v[82:83], v[86:87], v[90:91]
	v_pk_fma_f32 v[84:85], v[84:85], v[88:89], v[92:93]
	global_store_dwordx4 v[98:99], v[82:85], off offset:192
	global_load_dwordx4 v[82:85], v[108:109], off offset:256
	s_nop 0
	global_load_dwordx4 v[86:89], v[98:99], off offset:256
	s_waitcnt vmcnt(1)
	v_pk_mul_f32 v[82:83], v[82:83], 0.5 op_sel_hi:[1,0]
	v_pk_mul_f32 v[84:85], v[84:85], 0.5 op_sel_hi:[1,0]
	s_waitcnt vmcnt(0)
	v_pk_fma_f32 v[78:79], v[78:79], v[82:83], v[86:87]
	v_pk_fma_f32 v[80:81], v[80:81], v[84:85], v[88:89]
	global_store_dwordx4 v[98:99], v[78:81], off offset:256
	global_load_dwordx4 v[78:81], v[108:109], off offset:320
	s_nop 0
	global_load_dwordx4 v[82:85], v[98:99], off offset:320
	s_waitcnt vmcnt(1)
	v_pk_mul_f32 v[78:79], v[78:79], 0.5 op_sel_hi:[1,0]
	v_pk_mul_f32 v[80:81], v[80:81], 0.5 op_sel_hi:[1,0]
	s_waitcnt vmcnt(0)
	v_pk_fma_f32 v[74:75], v[74:75], v[78:79], v[82:83]
	v_pk_fma_f32 v[76:77], v[76:77], v[80:81], v[84:85]
	global_store_dwordx4 v[98:99], v[74:77], off offset:320
	global_load_dwordx4 v[74:77], v[108:109], off offset:384
	s_nop 0
	global_load_dwordx4 v[78:81], v[98:99], off offset:384
	s_waitcnt vmcnt(1)
	v_pk_mul_f32 v[74:75], v[74:75], 0.5 op_sel_hi:[1,0]
	v_pk_mul_f32 v[76:77], v[76:77], 0.5 op_sel_hi:[1,0]
	s_waitcnt vmcnt(0)
	v_pk_fma_f32 v[70:71], v[70:71], v[74:75], v[78:79]
	v_pk_fma_f32 v[72:73], v[72:73], v[76:77], v[80:81]
	global_store_dwordx4 v[98:99], v[70:73], off offset:384
	global_load_dwordx4 v[70:73], v[108:109], off offset:448
	s_nop 0
	global_load_dwordx4 v[74:77], v[98:99], off offset:448
	s_waitcnt vmcnt(1)
	v_pk_mul_f32 v[70:71], v[70:71], 0.5 op_sel_hi:[1,0]
	v_pk_mul_f32 v[72:73], v[72:73], 0.5 op_sel_hi:[1,0]
	s_waitcnt vmcnt(0)
	v_pk_fma_f32 v[66:67], v[66:67], v[70:71], v[74:75]
	v_pk_fma_f32 v[68:69], v[68:69], v[72:73], v[76:77]
	global_store_dwordx4 v[98:99], v[66:69], off offset:448
	s_nop 1
	v_or_b32_e32 v66, 32, v114
	v_cmp_lt_i32_e32 vcc, s97, v66
	v_add_u32_e32 v68, 0xffffc020, v114
	v_ashrrev_i32_e32 v67, 31, v66
	v_cndmask_b32_e64 v67, v67, 0, vcc
	v_cndmask_b32_e32 v66, v66, v68, vcc
	v_cndmask_b32_e64 v70, v115, 8, vcc
	v_cndmask_b32_e32 v69, v116, v117, vcc
	v_cndmask_b32_e32 v68, v118, v119, vcc
	v_lshlrev_b64 v[66:67], 12, v[66:67]
	v_lshl_add_u64 v[66:67], v[68:69], 0, v[66:67]
	v_mul_hi_i32_i24_e32 v69, 0x9000, v70
	v_mul_i32_i24_e32 v68, 0x9000, v70
	v_lshl_add_u64 v[68:69], s[14:15], 0, v[68:69]
	v_lshl_add_u64 v[76:77], v[68:69], 0, v[110:111]
	global_load_dwordx4 v[68:71], v[76:77], off
	v_lshl_add_u64 v[66:67], v[66:67], 0, v[110:111]
	global_load_dwordx4 v[72:75], v[66:67], off
	s_waitcnt vmcnt(1)
	v_pk_mul_f32 v[68:69], v[68:69], 0.5 op_sel_hi:[1,0]
	v_pk_mul_f32 v[70:71], v[70:71], 0.5 op_sel_hi:[1,0]
	s_waitcnt vmcnt(0)
	v_pk_fma_f32 v[62:63], v[62:63], v[68:69], v[72:73]
	v_pk_fma_f32 v[64:65], v[64:65], v[70:71], v[74:75]
	global_store_dwordx4 v[66:67], v[62:65], off
	global_load_dwordx4 v[62:65], v[76:77], off offset:64
	s_nop 0
	global_load_dwordx4 v[68:71], v[66:67], off offset:64
	s_waitcnt vmcnt(1)
	v_pk_mul_f32 v[62:63], v[62:63], 0.5 op_sel_hi:[1,0]
	v_pk_mul_f32 v[64:65], v[64:65], 0.5 op_sel_hi:[1,0]
	s_waitcnt vmcnt(0)
	v_pk_fma_f32 v[58:59], v[58:59], v[62:63], v[68:69]
	v_pk_fma_f32 v[60:61], v[60:61], v[64:65], v[70:71]
	global_store_dwordx4 v[66:67], v[58:61], off offset:64
	global_load_dwordx4 v[58:61], v[76:77], off offset:128
	s_nop 0
	global_load_dwordx4 v[62:65], v[66:67], off offset:128
	s_waitcnt vmcnt(1)
	v_pk_mul_f32 v[58:59], v[58:59], 0.5 op_sel_hi:[1,0]
	v_pk_mul_f32 v[60:61], v[60:61], 0.5 op_sel_hi:[1,0]
	s_waitcnt vmcnt(0)
	v_pk_fma_f32 v[54:55], v[54:55], v[58:59], v[62:63]
	v_pk_fma_f32 v[56:57], v[56:57], v[60:61], v[64:65]
	global_store_dwordx4 v[66:67], v[54:57], off offset:128
	global_load_dwordx4 v[54:57], v[76:77], off offset:192
	s_nop 0
	global_load_dwordx4 v[58:61], v[66:67], off offset:192
	s_waitcnt vmcnt(1)
	v_pk_mul_f32 v[54:55], v[54:55], 0.5 op_sel_hi:[1,0]
	v_pk_mul_f32 v[56:57], v[56:57], 0.5 op_sel_hi:[1,0]
	s_waitcnt vmcnt(0)
	v_pk_fma_f32 v[50:51], v[50:51], v[54:55], v[58:59]
	v_pk_fma_f32 v[52:53], v[52:53], v[56:57], v[60:61]
	global_store_dwordx4 v[66:67], v[50:53], off offset:192
	global_load_dwordx4 v[50:53], v[76:77], off offset:256
	s_nop 0
	global_load_dwordx4 v[54:57], v[66:67], off offset:256
	s_waitcnt vmcnt(1)
	v_pk_mul_f32 v[50:51], v[50:51], 0.5 op_sel_hi:[1,0]
	v_pk_mul_f32 v[52:53], v[52:53], 0.5 op_sel_hi:[1,0]
	s_waitcnt vmcnt(0)
	v_pk_fma_f32 v[46:47], v[46:47], v[50:51], v[54:55]
	v_pk_fma_f32 v[48:49], v[48:49], v[52:53], v[56:57]
	global_store_dwordx4 v[66:67], v[46:49], off offset:256
	global_load_dwordx4 v[46:49], v[76:77], off offset:320
	s_nop 0
	global_load_dwordx4 v[50:53], v[66:67], off offset:320
	s_waitcnt vmcnt(1)
	v_pk_mul_f32 v[46:47], v[46:47], 0.5 op_sel_hi:[1,0]
	v_pk_mul_f32 v[48:49], v[48:49], 0.5 op_sel_hi:[1,0]
	s_waitcnt vmcnt(0)
	v_pk_fma_f32 v[42:43], v[42:43], v[46:47], v[50:51]
	v_pk_fma_f32 v[44:45], v[44:45], v[48:49], v[52:53]
	global_store_dwordx4 v[66:67], v[42:45], off offset:320
	global_load_dwordx4 v[42:45], v[76:77], off offset:384
	s_nop 0
	global_load_dwordx4 v[46:49], v[66:67], off offset:384
	s_waitcnt vmcnt(1)
	v_pk_mul_f32 v[42:43], v[42:43], 0.5 op_sel_hi:[1,0]
	v_pk_mul_f32 v[44:45], v[44:45], 0.5 op_sel_hi:[1,0]
	s_waitcnt vmcnt(0)
	v_pk_fma_f32 v[38:39], v[38:39], v[42:43], v[46:47]
	v_pk_fma_f32 v[40:41], v[40:41], v[44:45], v[48:49]
	global_store_dwordx4 v[66:67], v[38:41], off offset:384
	global_load_dwordx4 v[38:41], v[76:77], off offset:448
	s_nop 0
	global_load_dwordx4 v[42:45], v[66:67], off offset:448
	s_waitcnt vmcnt(1)
	v_pk_mul_f32 v[38:39], v[38:39], 0.5 op_sel_hi:[1,0]
	v_pk_mul_f32 v[40:41], v[40:41], 0.5 op_sel_hi:[1,0]
	s_waitcnt vmcnt(0)
	v_pk_fma_f32 v[34:35], v[34:35], v[38:39], v[42:43]
	v_pk_fma_f32 v[36:37], v[36:37], v[40:41], v[44:45]
	global_store_dwordx4 v[66:67], v[34:37], off offset:448
	s_nop 1
	v_or_b32_e32 v34, 48, v114
	v_cmp_lt_i32_e32 vcc, s97, v34
	v_add_u32_e32 v36, 0xffffc030, v114
	v_ashrrev_i32_e32 v35, 31, v34
	v_cndmask_b32_e64 v35, v35, 0, vcc
	v_cndmask_b32_e32 v34, v34, v36, vcc
	v_cndmask_b32_e64 v38, v115, 8, vcc
	v_cndmask_b32_e32 v37, v116, v117, vcc
	v_cndmask_b32_e32 v36, v118, v119, vcc
	v_lshlrev_b64 v[34:35], 12, v[34:35]
	v_lshl_add_u64 v[34:35], v[36:37], 0, v[34:35]
	v_mul_hi_i32_i24_e32 v37, 0x9000, v38
	v_mul_i32_i24_e32 v36, 0x9000, v38
	v_lshl_add_u64 v[36:37], s[14:15], 0, v[36:37]
	v_lshl_add_u64 v[44:45], v[36:37], 0, v[110:111]
	global_load_dwordx4 v[36:39], v[44:45], off
	v_lshl_add_u64 v[34:35], v[34:35], 0, v[110:111]
	global_load_dwordx4 v[40:43], v[34:35], off
	s_waitcnt vmcnt(1)
	v_pk_mul_f32 v[36:37], v[36:37], 0.5 op_sel_hi:[1,0]
	v_pk_mul_f32 v[38:39], v[38:39], 0.5 op_sel_hi:[1,0]
	s_waitcnt vmcnt(0)
	v_pk_fma_f32 v[30:31], v[30:31], v[36:37], v[40:41]
	v_pk_fma_f32 v[32:33], v[32:33], v[38:39], v[42:43]
	global_store_dwordx4 v[34:35], v[30:33], off
	global_load_dwordx4 v[30:33], v[44:45], off offset:64
	s_nop 0
	global_load_dwordx4 v[36:39], v[34:35], off offset:64
	s_waitcnt vmcnt(1)
	v_pk_mul_f32 v[30:31], v[30:31], 0.5 op_sel_hi:[1,0]
	v_pk_mul_f32 v[32:33], v[32:33], 0.5 op_sel_hi:[1,0]
	s_waitcnt vmcnt(0)
	v_pk_fma_f32 v[26:27], v[26:27], v[30:31], v[36:37]
	v_pk_fma_f32 v[28:29], v[28:29], v[32:33], v[38:39]
	global_store_dwordx4 v[34:35], v[26:29], off offset:64
	global_load_dwordx4 v[26:29], v[44:45], off offset:128
	s_nop 0
	global_load_dwordx4 v[30:33], v[34:35], off offset:128
	s_waitcnt vmcnt(1)
	v_pk_mul_f32 v[26:27], v[26:27], 0.5 op_sel_hi:[1,0]
	v_pk_mul_f32 v[28:29], v[28:29], 0.5 op_sel_hi:[1,0]
	s_waitcnt vmcnt(0)
	v_pk_fma_f32 v[22:23], v[22:23], v[26:27], v[30:31]
	v_pk_fma_f32 v[24:25], v[24:25], v[28:29], v[32:33]
	global_store_dwordx4 v[34:35], v[22:25], off offset:128
	global_load_dwordx4 v[22:25], v[44:45], off offset:192
	s_nop 0
	global_load_dwordx4 v[26:29], v[34:35], off offset:192
	s_waitcnt vmcnt(1)
	v_pk_mul_f32 v[22:23], v[22:23], 0.5 op_sel_hi:[1,0]
	v_pk_mul_f32 v[24:25], v[24:25], 0.5 op_sel_hi:[1,0]
	s_waitcnt vmcnt(0)
	v_pk_fma_f32 v[18:19], v[18:19], v[22:23], v[26:27]
	v_pk_fma_f32 v[20:21], v[20:21], v[24:25], v[28:29]
	global_store_dwordx4 v[34:35], v[18:21], off offset:192
	global_load_dwordx4 v[18:21], v[44:45], off offset:256
	s_nop 0
	global_load_dwordx4 v[22:25], v[34:35], off offset:256
	s_waitcnt vmcnt(1)
	v_pk_mul_f32 v[18:19], v[18:19], 0.5 op_sel_hi:[1,0]
	v_pk_mul_f32 v[20:21], v[20:21], 0.5 op_sel_hi:[1,0]
	s_waitcnt vmcnt(0)
	v_pk_fma_f32 v[14:15], v[14:15], v[18:19], v[22:23]
	v_pk_fma_f32 v[16:17], v[16:17], v[20:21], v[24:25]
	global_store_dwordx4 v[34:35], v[14:17], off offset:256
	global_load_dwordx4 v[14:17], v[44:45], off offset:320
	s_nop 0
	global_load_dwordx4 v[18:21], v[34:35], off offset:320
	s_waitcnt vmcnt(1)
	v_pk_mul_f32 v[14:15], v[14:15], 0.5 op_sel_hi:[1,0]
	v_pk_mul_f32 v[16:17], v[16:17], 0.5 op_sel_hi:[1,0]
	s_waitcnt vmcnt(0)
	v_pk_fma_f32 v[10:11], v[10:11], v[14:15], v[18:19]
	v_pk_fma_f32 v[12:13], v[12:13], v[16:17], v[20:21]
	global_store_dwordx4 v[34:35], v[10:13], off offset:320
	global_load_dwordx4 v[10:13], v[44:45], off offset:384
	s_nop 0
	global_load_dwordx4 v[14:17], v[34:35], off offset:384
	s_waitcnt vmcnt(1)
	v_pk_mul_f32 v[10:11], v[10:11], 0.5 op_sel_hi:[1,0]
	v_pk_mul_f32 v[12:13], v[12:13], 0.5 op_sel_hi:[1,0]
	s_waitcnt vmcnt(0)
	v_pk_fma_f32 v[6:7], v[6:7], v[10:11], v[14:15]
	v_pk_fma_f32 v[8:9], v[8:9], v[12:13], v[16:17]
	global_store_dwordx4 v[34:35], v[6:9], off offset:384
	global_load_dwordx4 v[6:9], v[44:45], off offset:448
	s_nop 0
	global_load_dwordx4 v[10:13], v[34:35], off offset:448
	s_waitcnt vmcnt(1)
	v_pk_mul_f32 v[6:7], v[6:7], 0.5 op_sel_hi:[1,0]
	v_pk_mul_f32 v[8:9], v[8:9], 0.5 op_sel_hi:[1,0]
	s_waitcnt vmcnt(0)
	v_pk_fma_f32 v[2:3], v[2:3], v[6:7], v[10:11]
	v_pk_fma_f32 v[4:5], v[4:5], v[8:9], v[12:13]
	global_store_dwordx4 v[34:35], v[2:5], off offset:448
	s_add_i32 s18, s18, s11
	s_cmpk_gt_i32 s18, 0xff
	s_cbranch_scc0 .LBB0_1527
